# branch A: counted wait corrected to the 12 prefetch loads actually issued (6 groups x K,V); otherwise identical to the previous version
# baseline (speedup 1.0000x reference)
; __device__ __forceinline__ void attn_a_unit(LAS unsigned char* lds, const bf16* Z, bf16* Y, const float* sink, int unit) {
;     const int tid = threadIdx.x, lane = tid & 63, wid = tid >> 6, lq = lane & 15, g = lane >> 4;
;     const int ib = unit & 63, kvh = (unit >> 6) & 1, b = unit >> 7;
;     const size_t tok0 = (size_t)b * SEQ; const int kstart = (ib - 1) * 128;
;     LAS unsigned char* Kl = lds + A_KOFF; LAS unsigned char* Vl = lds + A_VOFF;
;     const int hq = kvh * 4 + (wid >> 1);
;     const float slope2 = __builtin_amdgcn_exp2f(-(float)(hq + 1)) * LOG2E, sink2 = sink[hq] * LOG2E, c1 = 0.125f * LOG2E;
;     const bool edge = (ib == 0) || (ib == 63);
;     for (int bp = 0; bp < 2; ++bp) {
;         const int qoffA = (wid & 1) * 64 + bp * 32, qoffB = qoffA + 16;
;         const size_t qtokA = tok0 + ib * 128 + qoffA + lq, qtokB = qtokA + 16;
;         const unsigned char* qpA = (const unsigned char*)Z + tmo((int)qtokA, Z_QA / 64 + hq, ZLD / 64) + 16 * g; const unsigned char* qpB = qpA + 16 * 128;
;         const bf16x8 qA0 = *(const bf16x8*)qpA, qA1 = *(const bf16x8*)(qpA + 64), qB0 = *(const bf16x8*)qpB, qB1 = *(const bf16x8*)(qpB + 64);
;         float mA = sink2, lA = (g == 0) ? 1.0f : 0.0f, mB = sink2, lB = lA;
;         f32x4 OA[4], OB[4];
; #pragma unroll
;         for (int d = 0; d < 4; ++d) { OA[d] = (f32x4){0.f, 0.f, 0.f, 0.f}; OB[d] = (f32x4){0.f, 0.f, 0.f, 0.f}; }
;         if (edge) {
;         for (int st = 0; st < 9; ++st) {
;             const int rbA = qoffA + 32 * st, rbB = rbA + 16;
;             f32x4 SA0, SA1, SB0, SB1;
;             qk_step(Kl, rbA, rbA + 16, lq, g, qA0, qA1, SA0, SA1);
;             qk_step(Kl, rbB, rbB + 16, lq, g, qB0, qB1, SB0, SB1);
;             const float basef = (float)(128 + lq - 32 * st - 4 * g);
;             a_scores<true>(SA0, SA1, basef, c1, slope2, rbA + 4 * g, kstart); a_scores<true>(SB0, SB1, basef, c1, slope2, rbB + 4 * g, kstart);
;             softmax_step(SA0, SA1, mA, lA, OA);
;             softmax_step(SB0, SB1, mB, lB, OB);
;             pv_step(Vl, rbA, rbA + 16, lane, g, SA0, SA1, OA);
;             pv_step(Vl, rbB, rbB + 16, lane, g, SB0, SB1, OB);
;         }
;         } else {
;         const LAS unsigned char* kp0 = Kl + swz(qoffA + lq, g); const LAS unsigned char* kp1 = Kl + swz(qoffA + lq, 4 + g);
;         const LAS unsigned char* vp[4];
.LBB0_257:
	s_waitcnt vmcnt(12)
	v_and_b32_e32 v219, 15, v218
	v_bfe_u32 v244, v218, 4, 2
	v_add_u32_e32 v245, s85, v219
	v_lshlrev_b32_e32 v245, 7, v245
	v_bitop3_b32 v120, v219, v244, 7 bitop3:0x6c
	v_lshl_add_u32 v122, v120, 4, v245
	v_xor_b32_e32 v120, 4, v120
	v_lshl_add_u32 v123, v120, 4, v245
	v_lshlrev_b32_e32 v245, 2, v244
	v_sub_u32_e32 v120, v219, v245
	v_cmp_ge_i32_e64 s[16:17], 0, v120
	v_cmp_le_i32_e64 s[28:29], 0, v120
	v_cmp_ge_i32_e64 s[18:19], 1, v120
	v_cmp_le_i32_e64 s[52:53], 1, v120
	v_cmp_ge_i32_e64 s[22:23], 2, v120
	v_cmp_le_i32_e64 s[54:55], 2, v120
	v_cmp_ge_i32_e64 s[24:25], 3, v120
	v_cmp_le_i32_e64 s[88:89], 3, v120
	v_cmp_eq_u32_e64 s[74:75], 0, v244
	v_cvt_f32_i32_e32 v129, v120
	v_lshrrev_b32_e32 v120, 2, v219
	v_add_u32_e32 v245, v245, v120
	v_bfe_u32 v120, v219, 1, 1
	v_and_b32_e32 v219, 1, v219
	v_lshlrev_b32_e32 v219, 3, v219
	v_add_u32_e32 v244, s85, v245
	v_lshl_add_u32 v219, v244, 7, v219
	v_add_u32_e32 v219, 0xc800, v219
	v_or_b32_e32 v245, 0, v120
	v_bitop3_b32 v245, v244, v245, 7 bitop3:0x6c
	v_lshl_add_u32 v124, v245, 4, v219
	v_or_b32_e32 v245, 2, v120
	v_bitop3_b32 v245, v244, v245, 7 bitop3:0x6c
	v_lshl_add_u32 v125, v245, 4, v219
	v_or_b32_e32 v245, 4, v120
	v_bitop3_b32 v245, v244, v245, 7 bitop3:0x6c
	v_lshl_add_u32 v126, v245, 4, v219
	v_or_b32_e32 v245, 6, v120
	v_bitop3_b32 v245, v244, v245, 7 bitop3:0x6c
	v_lshl_add_u32 v127, v245, 4, v219
	v_mov_b32_e32 v131, s84
	v_xor_b32_e32 v130, 0x80000000, v131
	v_mov_b32_e32 v219, s76
	v_mul_f32_e32 v145, 0x3fb8aa3b, v219
	v_mul_f32_e32 v132, v130, v129
	v_mul_f32_e32 v133, v131, v129
	s_cmp_eq_u32 s77, 0
	s_cbranch_scc1 .La_edge_lo
	s_cmp_eq_u32 s77, 63
	s_cbranch_scc1 .La_edge_hi
	v_fmamk_f32 v50, v130, 0x43000000, v132
	v_fmamk_f32 v51, v130, 0x42fe0000, v132
	v_fmamk_f32 v52, v130, 0x42fc0000, v132
	v_fmamk_f32 v53, v130, 0x42fa0000, v132
	v_mov_b32_e32 v245, 0xff800000
	v_cndmask_b32_e64 v50, v245, v50, s[16:17]
	v_cndmask_b32_e64 v51, v245, v51, s[18:19]
	v_cndmask_b32_e64 v52, v245, v52, s[22:23]
	v_cndmask_b32_e64 v53, v245, v53, s[24:25]
	v_fmamk_f32 v54, v130, 0x42e00000, v132
	v_fmamk_f32 v55, v130, 0x42de0000, v132
	v_fmamk_f32 v56, v130, 0x42dc0000, v132
	v_fmamk_f32 v57, v130, 0x42da0000, v132
	v_fmamk_f32 v58, v130, 0x42c00000, v132
	v_fmamk_f32 v59, v130, 0x42be0000, v132
	v_fmamk_f32 v60, v130, 0x42bc0000, v132
	v_fmamk_f32 v61, v130, 0x42ba0000, v132
	v_fmamk_f32 v62, v130, 0x42a00000, v132
	v_fmamk_f32 v63, v130, 0x429e0000, v132
	v_fmamk_f32 v64, v130, 0x429c0000, v132
	v_fmamk_f32 v65, v130, 0x429a0000, v132
	v_fmamk_f32 v66, v130, 0x42800000, v132
	v_fmamk_f32 v67, v130, 0x427c0000, v132
	v_fmamk_f32 v68, v130, 0x42780000, v132
	v_fmamk_f32 v69, v130, 0x42740000, v132
	v_fmamk_f32 v70, v130, 0x42400000, v132
	v_fmamk_f32 v71, v130, 0x423c0000, v132
	v_fmamk_f32 v72, v130, 0x42380000, v132
	v_fmamk_f32 v73, v130, 0x42340000, v132
	v_fmamk_f32 v74, v130, 0x42000000, v132
	v_fmamk_f32 v75, v130, 0x41f80000, v132
	v_fmamk_f32 v76, v130, 0x41f00000, v132
	v_fmamk_f32 v77, v130, 0x41e80000, v132
	v_fmamk_f32 v78, v130, 0x41800000, v132
	v_fmamk_f32 v79, v130, 0x41700000, v132
	v_fmamk_f32 v80, v130, 0x41600000, v132
	v_fmamk_f32 v81, v130, 0x41500000, v132
	v_add_f32_e32 v219, 0, v129
	v_mul_f32_e64 v82, v130, |v219|
	v_add_f32_e32 v245, 0xbf800000, v129
	v_mul_f32_e64 v83, v130, |v245|
	v_add_f32_e32 v219, 0xc0000000, v129
	v_mul_f32_e64 v84, v130, |v219|
	v_add_f32_e32 v245, 0xc0400000, v129
	v_mul_f32_e64 v85, v130, |v245|
	v_fmamk_f32 v86, v131, 0xc1800000, v133
	v_fmamk_f32 v87, v131, 0xc1880000, v133
	v_fmamk_f32 v88, v131, 0xc1900000, v133
	v_fmamk_f32 v89, v131, 0xc1980000, v133
	v_fmamk_f32 v90, v131, 0xc2000000, v133
	v_fmamk_f32 v91, v131, 0xc2040000, v133
	v_fmamk_f32 v92, v131, 0xc2080000, v133
	v_fmamk_f32 v93, v131, 0xc20c0000, v133
	v_fmamk_f32 v94, v131, 0xc2400000, v133
	v_fmamk_f32 v95, v131, 0xc2440000, v133
	v_fmamk_f32 v96, v131, 0xc2480000, v133
	v_fmamk_f32 v97, v131, 0xc24c0000, v133
	v_fmamk_f32 v98, v131, 0xc2800000, v133
	v_fmamk_f32 v99, v131, 0xc2820000, v133
	v_fmamk_f32 v100, v131, 0xc2840000, v133
	v_fmamk_f32 v101, v131, 0xc2860000, v133
	v_fmamk_f32 v102, v131, 0xc2a00000, v133
	v_fmamk_f32 v103, v131, 0xc2a20000, v133
	v_fmamk_f32 v104, v131, 0xc2a40000, v133
	v_fmamk_f32 v105, v131, 0xc2a60000, v133
	v_fmamk_f32 v106, v131, 0xc2c00000, v133
	v_fmamk_f32 v107, v131, 0xc2c20000, v133
	v_fmamk_f32 v108, v131, 0xc2c40000, v133
	v_fmamk_f32 v109, v131, 0xc2c60000, v133
	v_fmamk_f32 v110, v131, 0xc2e00000, v133
	v_fmamk_f32 v111, v131, 0xc2e20000, v133
	v_fmamk_f32 v112, v131, 0xc2e40000, v133
	v_fmamk_f32 v113, v131, 0xc2e60000, v133
	v_fmamk_f32 v114, v131, 0xc3000000, v133
	v_fmamk_f32 v115, v131, 0xc3010000, v133
	v_fmamk_f32 v116, v131, 0xc3020000, v133
	v_fmamk_f32 v117, v131, 0xc3030000, v133
	v_mov_b32_e32 v245, 0xff800000
	v_cndmask_b32_e64 v114, v245, v114, s[28:29]
	v_cndmask_b32_e64 v115, v245, v115, s[52:53]
	v_cndmask_b32_e64 v116, v245, v116, s[54:55]
	v_cndmask_b32_e64 v117, v245, v117, s[88:89]
	ds_read_b128 v[186:189], v122 offset:0
	ds_read_b128 v[190:193], v123 offset:0
	ds_read_b128 v[194:197], v122 offset:2048
	ds_read_b128 v[198:201], v123 offset:2048
	ds_read_b128 v[202:205], v122 offset:4096
	ds_read_b128 v[206:209], v123 offset:4096
	ds_read_b128 v[210:213], v122 offset:6144
	ds_read_b128 v[214:217], v123 offset:6144
	ds_read_b128 v[220:223], v122 offset:8192
	ds_read_b128 v[224:227], v123 offset:8192
	ds_read_b128 v[228:231], v122 offset:10240
	ds_read_b128 v[232:235], v123 offset:10240
	ds_read_b128 v[236:239], v122 offset:12288
	ds_read_b128 v[240:243], v123 offset:12288
	s_waitcnt lgkmcnt(13)
; #define LAS __attribute__((address_space(3)))
; #define MFMA16(a, b, c) __builtin_amdgcn_mfma_f32_16x16x32_bf16((a), (b), (c), 0, 0, 0)
; __device__ __forceinline__ void qk_at(const LAS unsigned char* kp0, const LAS unsigned char* kp1, int off, bf16x8 qf0, bf16x8 qf1, f32x4& S0, f32x4& S1) {
;     const bf16x8 k00 = *(const LAS bf16x8*)(kp0 + off), k01 = *(const LAS bf16x8*)(kp1 + off);
;     const bf16x8 k10 = *(const LAS bf16x8*)(kp0 + off + 2048), k11 = *(const LAS bf16x8*)(kp1 + off + 2048);
;     const f32x4 z = {0.f, 0.f, 0.f, 0.f};
;     S0 = MFMA16(k00, qf0, z); S0 = MFMA16(k01, qf1, S0);
;     S1 = MFMA16(k10, qf0, z); S1 = MFMA16(k11, qf1, S1);
; }
; __device__ __forceinline__ float xrow16_max(float x) {
;     auto s = __builtin_amdgcn_permlane16_swap(__float_as_uint(x), __float_as_uint(x), false, false);
;     x = fmaxf(__uint_as_float(s[0]), __uint_as_float(s[1]));
;     auto t = __builtin_amdgcn_permlane32_swap(__float_as_uint(x), __float_as_uint(x), false, false);
;     return fmaxf(__uint_as_float(t[0]), __uint_as_float(t[1]));
; }
; __device__ __forceinline__ void softmax_step(f32x4& s0, f32x4& s1, float& m, float& l, f32x4 (&O)[4]) {
;     float t = fmaxf(fmaxf(fmaxf(s0[0], s0[1]), fmaxf(s0[2], s0[3])), fmaxf(fmaxf(s1[0], s1[1]), fmaxf(s1[2], s1[3])));
;     t = xrow16_max(t);
;     const float mn = fmaxf(m, t), alpha = __builtin_amdgcn_exp2f(m - mn);
;     m = mn;
	v_mfma_f32_16x16x32_bf16 v[50:53], v[186:189], v[146:149], v[50:53]
	s_waitcnt lgkmcnt(12)
	v_mfma_f32_16x16x32_bf16 v[50:53], v[190:193], v[150:153], v[50:53]
	ds_read_b128 v[186:189], v122 offset:14336
	ds_read_b128 v[190:193], v123 offset:14336
	s_waitcnt lgkmcnt(13)
	v_mfma_f32_16x16x32_bf16 v[54:57], v[194:197], v[146:149], v[54:57]
	s_waitcnt lgkmcnt(12)
	v_mfma_f32_16x16x32_bf16 v[54:57], v[198:201], v[150:153], v[54:57]
	ds_read_b128 v[194:197], v122 offset:16384
	ds_read_b128 v[198:201], v123 offset:16384
	s_waitcnt lgkmcnt(13)
	v_mfma_f32_16x16x32_bf16 v[58:61], v[202:205], v[146:149], v[58:61]
	s_waitcnt lgkmcnt(12)
	v_mfma_f32_16x16x32_bf16 v[58:61], v[206:209], v[150:153], v[58:61]
	ds_read_b128 v[202:205], v122 offset:18432
	ds_read_b128 v[206:209], v123 offset:18432
	s_waitcnt lgkmcnt(13)
	v_mfma_f32_16x16x32_bf16 v[62:65], v[210:213], v[146:149], v[62:65]
	s_waitcnt lgkmcnt(12)
	v_mfma_f32_16x16x32_bf16 v[62:65], v[214:217], v[150:153], v[62:65]
	ds_read_b128 v[210:213], v122 offset:20480
	ds_read_b128 v[214:217], v123 offset:20480
	s_waitcnt lgkmcnt(13)
	v_mfma_f32_16x16x32_bf16 v[66:69], v[220:223], v[146:149], v[66:69]
	s_waitcnt lgkmcnt(12)
	v_mfma_f32_16x16x32_bf16 v[66:69], v[224:227], v[150:153], v[66:69]
	ds_read_b128 v[220:223], v122 offset:22528
	ds_read_b128 v[224:227], v123 offset:22528
	s_waitcnt lgkmcnt(13)
	v_mfma_f32_16x16x32_bf16 v[70:73], v[228:231], v[146:149], v[70:73]
	s_waitcnt lgkmcnt(12)
	v_mfma_f32_16x16x32_bf16 v[70:73], v[232:235], v[150:153], v[70:73]
	ds_read_b128 v[228:231], v122 offset:24576
	ds_read_b128 v[232:235], v123 offset:24576
	s_waitcnt lgkmcnt(13)
	v_mfma_f32_16x16x32_bf16 v[74:77], v[236:239], v[146:149], v[74:77]
	s_waitcnt lgkmcnt(12)
	v_mfma_f32_16x16x32_bf16 v[74:77], v[240:243], v[150:153], v[74:77]
	ds_read_b128 v[236:239], v122 offset:26624
	ds_read_b128 v[240:243], v123 offset:26624
	s_waitcnt lgkmcnt(13)
	v_mfma_f32_16x16x32_bf16 v[78:81], v[186:189], v[146:149], v[78:81]
	s_waitcnt lgkmcnt(12)
	v_mfma_f32_16x16x32_bf16 v[78:81], v[190:193], v[150:153], v[78:81]
	ds_read_b128 v[186:189], v122 offset:28672
	ds_read_b128 v[190:193], v123 offset:28672
	s_waitcnt lgkmcnt(13)
	v_mfma_f32_16x16x32_bf16 v[82:85], v[194:197], v[146:149], v[82:85]
	s_waitcnt lgkmcnt(12)
	v_mfma_f32_16x16x32_bf16 v[82:85], v[198:201], v[150:153], v[82:85]
	ds_read_b128 v[194:197], v122 offset:30720
	ds_read_b128 v[198:201], v123 offset:30720
	s_waitcnt lgkmcnt(13)
	v_mfma_f32_16x16x32_bf16 v[86:89], v[202:205], v[146:149], v[86:89]
	s_waitcnt lgkmcnt(12)
	v_mfma_f32_16x16x32_bf16 v[86:89], v[206:209], v[150:153], v[86:89]
	ds_read_b128 v[202:205], v122 offset:32768
	ds_read_b128 v[206:209], v123 offset:32768
	s_waitcnt lgkmcnt(13)
	v_mfma_f32_16x16x32_bf16 v[90:93], v[210:213], v[146:149], v[90:93]
	s_waitcnt lgkmcnt(12)
	v_mfma_f32_16x16x32_bf16 v[90:93], v[214:217], v[150:153], v[90:93]
	s_waitcnt lgkmcnt(11)
	v_mfma_f32_16x16x32_bf16 v[94:97], v[220:223], v[146:149], v[94:97]
	s_waitcnt lgkmcnt(10)
	v_mfma_f32_16x16x32_bf16 v[94:97], v[224:227], v[150:153], v[94:97]
	s_waitcnt lgkmcnt(9)
	v_mfma_f32_16x16x32_bf16 v[98:101], v[228:231], v[146:149], v[98:101]
	s_waitcnt lgkmcnt(8)
	v_mfma_f32_16x16x32_bf16 v[98:101], v[232:235], v[150:153], v[98:101]
	s_waitcnt lgkmcnt(7)
	v_mfma_f32_16x16x32_bf16 v[102:105], v[236:239], v[146:149], v[102:105]
	s_waitcnt lgkmcnt(6)
	v_mfma_f32_16x16x32_bf16 v[102:105], v[240:243], v[150:153], v[102:105]
	s_waitcnt lgkmcnt(5)
	v_mfma_f32_16x16x32_bf16 v[106:109], v[186:189], v[146:149], v[106:109]
	s_waitcnt lgkmcnt(4)
	v_mfma_f32_16x16x32_bf16 v[106:109], v[190:193], v[150:153], v[106:109]
	s_waitcnt lgkmcnt(3)
	v_mfma_f32_16x16x32_bf16 v[110:113], v[194:197], v[146:149], v[110:113]
	s_waitcnt lgkmcnt(2)
	v_mfma_f32_16x16x32_bf16 v[110:113], v[198:201], v[150:153], v[110:113]
	s_waitcnt lgkmcnt(1)
	v_mfma_f32_16x16x32_bf16 v[114:117], v[202:205], v[146:149], v[114:117]
	s_waitcnt lgkmcnt(0)
	v_mfma_f32_16x16x32_bf16 v[114:117], v[206:209], v[150:153], v[114:117]
	v_max3_f32 v219, v50, v51, v52
	v_max3_f32 v244, v54, v55, v56
	v_max3_f32 v245, v58, v59, v60
	v_max3_f32 v120, v62, v63, v64
	v_max3_f32 v219, v219, v53, v66
	v_max3_f32 v244, v244, v57, v70
	v_max3_f32 v245, v245, v61, v74
	v_max3_f32 v120, v120, v65, v78
	v_max3_f32 v219, v219, v67, v68
	v_max3_f32 v244, v244, v71, v72
	v_max3_f32 v245, v245, v75, v76
	v_max3_f32 v120, v120, v79, v80
	ds_read_b64_tr_b16 v[186:187], v124 offset:0
	ds_read_b64_tr_b16 v[188:189], v124 offset:2048
	ds_read_b64_tr_b16 v[190:191], v125 offset:0
	ds_read_b64_tr_b16 v[192:193], v125 offset:2048
	ds_read_b64_tr_b16 v[194:195], v126 offset:0
	ds_read_b64_tr_b16 v[196:197], v126 offset:2048
	ds_read_b64_tr_b16 v[198:199], v127 offset:0
	ds_read_b64_tr_b16 v[200:201], v127 offset:2048
	v_max3_f32 v219, v219, v69, v82
	v_max3_f32 v244, v244, v73, v86
	v_max3_f32 v245, v245, v77, v90
	v_max3_f32 v120, v120, v81, v94
	v_max3_f32 v219, v219, v83, v84
	v_max3_f32 v244, v244, v87, v88
	v_max3_f32 v245, v245, v91, v92
	v_max3_f32 v120, v120, v95, v96
	v_max3_f32 v219, v219, v85, v98
	v_max3_f32 v244, v244, v89, v102
	v_max3_f32 v245, v245, v93, v106
	v_max3_f32 v120, v120, v97, v110
	v_max3_f32 v219, v219, v99, v100
	v_max3_f32 v244, v244, v103, v104
	v_max3_f32 v245, v245, v107, v108
	v_max3_f32 v120, v120, v111, v112
	v_max3_f32 v219, v219, v101, v114
	v_max3_f32 v219, v219, v115, v116
	v_max_f32_e32 v219, v219, v117
	v_max_f32_e32 v244, v244, v105
	v_max_f32_e32 v245, v245, v109
	v_max_f32_e32 v120, v120, v113
	v_max3_f32 v178, v219, v244, v245
	v_max_f32_e32 v178, v178, v120
	v_mov_b32_e32 v219, v178
	s_nop 1
	v_permlane16_swap_b32_e32 v178, v219
	v_max_f32_e32 v178, v178, v219
	v_mov_b32_e32 v219, v178
	s_nop 1
	v_permlane32_swap_b32_e32 v178, v219
	v_max3_f32 v178, v178, v219, v145
	s_waitcnt lgkmcnt(7)
; __device__ __forceinline__ unsigned pk2(float lo, float hi) { return pg8::cvt_pk_bf16(lo, hi); }
; __device__ __forceinline__ void pv_at(const LAS unsigned char* const (&vp)[4], int off, const f32x4& P0, const f32x4& P1, f32x4 (&O)[4]) {
;     v4u pw; pw.x = pk2(P0[0], P0[1]); pw.y = pk2(P0[2], P0[3]); pw.z = pk2(P1[0], P1[1]); pw.w = pk2(P1[2], P1[3]);
;     const bf16x8 pb = __builtin_bit_cast(bf16x8, pw);
; __device__ __forceinline__ void softmax_step(f32x4& s0, f32x4& s1, float& m, float& l, f32x4 (&O)[4]) {
;     float t = fmaxf(fmaxf(fmaxf(s0[0], s0[1]), fmaxf(s0[2], s0[3])), fmaxf(fmaxf(s1[0], s1[1]), fmaxf(s1[2], s1[3])));
;     t = xrow16_max(t);
;     const float mn = fmaxf(m, t), alpha = __builtin_amdgcn_exp2f(m - mn);
;     m = mn;
; #pragma unroll
;     for (int k = 0; k < 4; ++k) { s0[k] = __builtin_amdgcn_exp2f(s0[k] - mn); s1[k] = __builtin_amdgcn_exp2f(s1[k] - mn); }
;     l = l * alpha + ((s0[0] + s0[1]) + (s0[2] + s0[3])) + ((s1[0] + s1[1]) + (s1[2] + s1[3]));
; #pragma unroll
;     for (int db = 0; db < 4; ++db) O[db] *= alpha;
; }
	ds_read_b64_tr_b16 v[202:203], v124 offset:4096
	ds_read_b64_tr_b16 v[204:205], v124 offset:6144
	ds_read_b64_tr_b16 v[206:207], v125 offset:4096
	ds_read_b64_tr_b16 v[208:209], v125 offset:6144
	ds_read_b64_tr_b16 v[228:229], v126 offset:4096
	ds_read_b64_tr_b16 v[230:231], v126 offset:6144
	ds_read_b64_tr_b16 v[232:233], v127 offset:4096
	ds_read_b64_tr_b16 v[234:235], v127 offset:6144
	v_mov_b32_e32 v244, v178
	v_pk_add_f32 v[50:51], v[50:51], v[244:245] op_sel_hi:[1,0] neg_lo:[0,1] neg_hi:[0,1]
	v_pk_add_f32 v[52:53], v[52:53], v[244:245] op_sel_hi:[1,0] neg_lo:[0,1] neg_hi:[0,1]
	v_pk_add_f32 v[54:55], v[54:55], v[244:245] op_sel_hi:[1,0] neg_lo:[0,1] neg_hi:[0,1]
	v_pk_add_f32 v[56:57], v[56:57], v[244:245] op_sel_hi:[1,0] neg_lo:[0,1] neg_hi:[0,1]
	v_pk_add_f32 v[58:59], v[58:59], v[244:245] op_sel_hi:[1,0] neg_lo:[0,1] neg_hi:[0,1]
	v_pk_add_f32 v[60:61], v[60:61], v[244:245] op_sel_hi:[1,0] neg_lo:[0,1] neg_hi:[0,1]
	v_pk_add_f32 v[62:63], v[62:63], v[244:245] op_sel_hi:[1,0] neg_lo:[0,1] neg_hi:[0,1]
	v_pk_add_f32 v[64:65], v[64:65], v[244:245] op_sel_hi:[1,0] neg_lo:[0,1] neg_hi:[0,1]
	v_pk_add_f32 v[66:67], v[66:67], v[244:245] op_sel_hi:[1,0] neg_lo:[0,1] neg_hi:[0,1]
	v_pk_add_f32 v[68:69], v[68:69], v[244:245] op_sel_hi:[1,0] neg_lo:[0,1] neg_hi:[0,1]
	v_pk_add_f32 v[70:71], v[70:71], v[244:245] op_sel_hi:[1,0] neg_lo:[0,1] neg_hi:[0,1]
	v_pk_add_f32 v[72:73], v[72:73], v[244:245] op_sel_hi:[1,0] neg_lo:[0,1] neg_hi:[0,1]
	v_pk_add_f32 v[74:75], v[74:75], v[244:245] op_sel_hi:[1,0] neg_lo:[0,1] neg_hi:[0,1]
	v_pk_add_f32 v[76:77], v[76:77], v[244:245] op_sel_hi:[1,0] neg_lo:[0,1] neg_hi:[0,1]
	v_pk_add_f32 v[78:79], v[78:79], v[244:245] op_sel_hi:[1,0] neg_lo:[0,1] neg_hi:[0,1]
	v_pk_add_f32 v[80:81], v[80:81], v[244:245] op_sel_hi:[1,0] neg_lo:[0,1] neg_hi:[0,1]
	v_pk_add_f32 v[82:83], v[82:83], v[244:245] op_sel_hi:[1,0] neg_lo:[0,1] neg_hi:[0,1]
	v_pk_add_f32 v[84:85], v[84:85], v[244:245] op_sel_hi:[1,0] neg_lo:[0,1] neg_hi:[0,1]
	v_pk_add_f32 v[86:87], v[86:87], v[244:245] op_sel_hi:[1,0] neg_lo:[0,1] neg_hi:[0,1]
	v_pk_add_f32 v[88:89], v[88:89], v[244:245] op_sel_hi:[1,0] neg_lo:[0,1] neg_hi:[0,1]
	v_pk_add_f32 v[90:91], v[90:91], v[244:245] op_sel_hi:[1,0] neg_lo:[0,1] neg_hi:[0,1]
	v_pk_add_f32 v[92:93], v[92:93], v[244:245] op_sel_hi:[1,0] neg_lo:[0,1] neg_hi:[0,1]
	v_pk_add_f32 v[94:95], v[94:95], v[244:245] op_sel_hi:[1,0] neg_lo:[0,1] neg_hi:[0,1]
	v_pk_add_f32 v[96:97], v[96:97], v[244:245] op_sel_hi:[1,0] neg_lo:[0,1] neg_hi:[0,1]
	v_pk_add_f32 v[98:99], v[98:99], v[244:245] op_sel_hi:[1,0] neg_lo:[0,1] neg_hi:[0,1]
	v_pk_add_f32 v[100:101], v[100:101], v[244:245] op_sel_hi:[1,0] neg_lo:[0,1] neg_hi:[0,1]
	v_pk_add_f32 v[102:103], v[102:103], v[244:245] op_sel_hi:[1,0] neg_lo:[0,1] neg_hi:[0,1]
	v_pk_add_f32 v[104:105], v[104:105], v[244:245] op_sel_hi:[1,0] neg_lo:[0,1] neg_hi:[0,1]
	v_pk_add_f32 v[106:107], v[106:107], v[244:245] op_sel_hi:[1,0] neg_lo:[0,1] neg_hi:[0,1]
	v_pk_add_f32 v[108:109], v[108:109], v[244:245] op_sel_hi:[1,0] neg_lo:[0,1] neg_hi:[0,1]
	v_pk_add_f32 v[110:111], v[110:111], v[244:245] op_sel_hi:[1,0] neg_lo:[0,1] neg_hi:[0,1]
	v_pk_add_f32 v[112:113], v[112:113], v[244:245] op_sel_hi:[1,0] neg_lo:[0,1] neg_hi:[0,1]
	v_pk_add_f32 v[114:115], v[114:115], v[244:245] op_sel_hi:[1,0] neg_lo:[0,1] neg_hi:[0,1]
	v_pk_add_f32 v[116:117], v[116:117], v[244:245] op_sel_hi:[1,0] neg_lo:[0,1] neg_hi:[0,1]
	v_sub_f32_e32 v219, v145, v178
	v_exp_f32_e32 v50, v50
	v_exp_f32_e32 v51, v51
	v_exp_f32_e32 v52, v52
	v_exp_f32_e32 v53, v53
	v_exp_f32_e32 v54, v54
	v_exp_f32_e32 v55, v55
	v_exp_f32_e32 v56, v56
	v_exp_f32_e32 v57, v57
	v_exp_f32_e32 v58, v58
	v_exp_f32_e32 v59, v59
	v_exp_f32_e32 v60, v60
	v_exp_f32_e32 v61, v61
	v_exp_f32_e32 v62, v62
	v_exp_f32_e32 v63, v63
	v_exp_f32_e32 v64, v64
	v_exp_f32_e32 v65, v65
	v_exp_f32_e32 v66, v66
	v_exp_f32_e32 v67, v67
	v_exp_f32_e32 v68, v68
	v_exp_f32_e32 v69, v69
	v_exp_f32_e32 v70, v70
	v_exp_f32_e32 v71, v71
	v_exp_f32_e32 v72, v72
	v_exp_f32_e32 v73, v73
	v_exp_f32_e32 v74, v74
	v_exp_f32_e32 v75, v75
	v_exp_f32_e32 v76, v76
	v_exp_f32_e32 v77, v77
	v_exp_f32_e32 v78, v78
	v_exp_f32_e32 v79, v79
	v_exp_f32_e32 v80, v80
	v_exp_f32_e32 v81, v81
	v_exp_f32_e32 v82, v82
	v_exp_f32_e32 v83, v83
	v_exp_f32_e32 v84, v84
	v_exp_f32_e32 v85, v85
	v_exp_f32_e32 v86, v86
	v_exp_f32_e32 v87, v87
	v_exp_f32_e32 v88, v88
	v_exp_f32_e32 v89, v89
	v_exp_f32_e32 v90, v90
	v_exp_f32_e32 v91, v91
	v_exp_f32_e32 v92, v92
	v_exp_f32_e32 v93, v93
	v_exp_f32_e32 v94, v94
	v_exp_f32_e32 v95, v95
	v_exp_f32_e32 v96, v96
	v_exp_f32_e32 v97, v97
	v_exp_f32_e32 v98, v98
	v_exp_f32_e32 v99, v99
	v_exp_f32_e32 v100, v100
	v_exp_f32_e32 v101, v101
	v_exp_f32_e32 v102, v102
	v_exp_f32_e32 v103, v103
	v_exp_f32_e32 v104, v104
	v_exp_f32_e32 v105, v105
	v_exp_f32_e32 v106, v106
	v_exp_f32_e32 v107, v107
	v_exp_f32_e32 v108, v108
	v_exp_f32_e32 v109, v109
	v_exp_f32_e32 v110, v110
	v_exp_f32_e32 v111, v111
	v_exp_f32_e32 v112, v112
	v_exp_f32_e32 v113, v113
	v_exp_f32_e32 v114, v114
	v_exp_f32_e32 v115, v115
	v_exp_f32_e32 v116, v116
	v_exp_f32_e32 v117, v117
	v_exp_f32_e32 v219, v219
	v_pk_add_f32 v[236:237], v[50:51], v[52:53]
	v_pk_add_f32 v[238:239], v[54:55], v[56:57]
	v_pk_add_f32 v[240:241], v[58:59], v[60:61]
	v_pk_add_f32 v[242:243], v[62:63], v[64:65]
	v_pk_add_f32 v[236:237], v[236:237], v[66:67]
	v_pk_add_f32 v[238:239], v[238:239], v[70:71]
	v_pk_add_f32 v[240:241], v[240:241], v[74:75]
	v_pk_add_f32 v[242:243], v[242:243], v[78:79]
	v_pk_add_f32 v[236:237], v[236:237], v[68:69]
	v_pk_add_f32 v[238:239], v[238:239], v[72:73]
	v_pk_add_f32 v[240:241], v[240:241], v[76:77]
	v_pk_add_f32 v[242:243], v[242:243], v[80:81]
	v_pk_add_f32 v[236:237], v[236:237], v[82:83]
	v_pk_add_f32 v[238:239], v[238:239], v[86:87]
	v_pk_add_f32 v[240:241], v[240:241], v[90:91]
	v_pk_add_f32 v[242:243], v[242:243], v[94:95]
	v_pk_add_f32 v[236:237], v[236:237], v[84:85]
	v_pk_add_f32 v[238:239], v[238:239], v[88:89]
	v_pk_add_f32 v[240:241], v[240:241], v[92:93]
	v_pk_add_f32 v[242:243], v[242:243], v[96:97]
	v_pk_add_f32 v[236:237], v[236:237], v[98:99]
	v_pk_add_f32 v[238:239], v[238:239], v[102:103]
	v_pk_add_f32 v[240:241], v[240:241], v[106:107]
	v_pk_add_f32 v[242:243], v[242:243], v[110:111]
	v_pk_add_f32 v[236:237], v[236:237], v[100:101]
	v_pk_add_f32 v[238:239], v[238:239], v[104:105]
	v_pk_add_f32 v[240:241], v[240:241], v[108:109]
	v_pk_add_f32 v[242:243], v[242:243], v[112:113]
	v_pk_add_f32 v[236:237], v[236:237], v[114:115]
	v_pk_add_f32 v[236:237], v[236:237], v[116:117]
	v_pk_add_f32 v[236:237], v[236:237], v[238:239]
	v_pk_add_f32 v[240:241], v[240:241], v[242:243]
	v_cndmask_b32_e64 v219, 0, v219, s[74:75]
	v_pk_add_f32 v[236:237], v[236:237], v[240:241]
	v_add_f32_e32 v185, v236, v237
	v_add_f32_e32 v185, v185, v219
	v_cvt_pk_bf16_f32 v236, v50, v51
	v_cvt_pk_bf16_f32 v237, v52, v53
	v_cvt_pk_bf16_f32 v238, v54, v55
	v_cvt_pk_bf16_f32 v239, v56, v57
	s_nop 1
	s_waitcnt lgkmcnt(14)
; #define LAS __attribute__((address_space(3)))
; __device__ __forceinline__ unsigned pk2(float lo, float hi) { return pg8::cvt_pk_bf16(lo, hi); }
; __device__ __forceinline__ s16x4 vtr(const LAS unsigned char* p) { return __builtin_bit_cast(s16x4, __builtin_amdgcn_ds_read_tr16_b64_v4i16((LAS s16x4*)p)); }
; #define MFMA16(a, b, c) __builtin_amdgcn_mfma_f32_16x16x32_bf16((a), (b), (c), 0, 0, 0)
; __device__ __forceinline__ void pv_at(const LAS unsigned char* const (&vp)[4], int off, const f32x4& P0, const f32x4& P1, f32x4 (&O)[4]) {
;     v4u pw; pw.x = pk2(P0[0], P0[1]); pw.y = pk2(P0[2], P0[3]); pw.z = pk2(P1[0], P1[1]); pw.w = pk2(P1[2], P1[3]);
;     const bf16x8 pb = __builtin_bit_cast(bf16x8, pw);
; #pragma unroll
;     for (int db = 0; db < 4; ++db) {
;         const s16x4 lo = vtr(vp[db] + off), hi = vtr(vp[db] + off + 2048);
;         const bf16x8 vt = (bf16x8){lo[0], lo[1], lo[2], lo[3], hi[0], hi[1], hi[2], hi[3]};
;         O[db] = MFMA16(vt, pb, O[db]);
;     }
; }
; template <bool MASK> __device__ __forceinline__ void a_scores(f32x4& S0, f32x4& S1, float basef, float c1, float slope2, int krow0, int kstart) {
; #pragma unroll
;     for (int r = 0; r < 4; ++r) {
;         const float d0 = fabsf(basef - (float)r), d1 = fabsf(basef - (float)(16 + r));
;         const float v0 = S0[r] - slope2 * d0, v1 = S1[r] - slope2 * d1;
;         if (MASK) { const int p0 = kstart + krow0 + r, p1 = p0 + 16;
;             S0[r] = (d0 <= 128.f && p0 >= 0 && p0 < SEQ) ? v0 : -INFINITY; S1[r] = (d1 <= 128.f && p1 >= 0 && p1 < SEQ) ? v1 : -INFINITY; }
;         else { S0[r] = v0; S1[r] = v1; }
;     }
; }
	v_mfma_f32_16x16x32_bf16 v[210:213], v[186:189], v[236:239], 0
	s_waitcnt lgkmcnt(12)
	v_mfma_f32_16x16x32_bf16 v[214:217], v[190:193], v[236:239], 0
	s_waitcnt lgkmcnt(10)
	v_mfma_f32_16x16x32_bf16 v[220:223], v[194:197], v[236:239], 0
	s_waitcnt lgkmcnt(8)
	v_mfma_f32_16x16x32_bf16 v[224:227], v[198:201], v[236:239], 0
	v_cvt_pk_bf16_f32 v240, v58, v59
	v_cvt_pk_bf16_f32 v241, v60, v61
	v_cvt_pk_bf16_f32 v242, v62, v63
	v_cvt_pk_bf16_f32 v243, v64, v65
	s_waitcnt lgkmcnt(7)
	ds_read_b64_tr_b16 v[186:187], v124 offset:8192
	ds_read_b64_tr_b16 v[188:189], v124 offset:10240
	ds_read_b64_tr_b16 v[190:191], v125 offset:8192
	ds_read_b64_tr_b16 v[192:193], v125 offset:10240
	ds_read_b64_tr_b16 v[194:195], v126 offset:8192
	ds_read_b64_tr_b16 v[196:197], v126 offset:10240
	ds_read_b64_tr_b16 v[198:199], v127 offset:8192
	ds_read_b64_tr_b16 v[200:201], v127 offset:10240
	v_fmamk_f32 v50, v130, 0x43000000, v132
	v_fmamk_f32 v51, v130, 0x42fe0000, v132
	v_fmamk_f32 v52, v130, 0x42fc0000, v132
	v_fmamk_f32 v53, v130, 0x42fa0000, v132
	v_mov_b32_e32 v245, 0xff800000
	v_cndmask_b32_e64 v50, v245, v50, s[16:17]
	v_cndmask_b32_e64 v51, v245, v51, s[18:19]
	v_cndmask_b32_e64 v52, v245, v52, s[22:23]
	v_cndmask_b32_e64 v53, v245, v53, s[24:25]
	v_fmamk_f32 v54, v130, 0x42e00000, v132
	v_fmamk_f32 v55, v130, 0x42de0000, v132
	v_fmamk_f32 v56, v130, 0x42dc0000, v132
	v_fmamk_f32 v57, v130, 0x42da0000, v132
	s_waitcnt lgkmcnt(14)
	v_mfma_f32_16x16x32_bf16 v[210:213], v[202:205], v[240:243], v[210:213]
	s_waitcnt lgkmcnt(12)
	v_mfma_f32_16x16x32_bf16 v[214:217], v[206:209], v[240:243], v[214:217]
	s_waitcnt lgkmcnt(10)
	v_mfma_f32_16x16x32_bf16 v[220:223], v[228:231], v[240:243], v[220:223]
	s_waitcnt lgkmcnt(8)
	v_mfma_f32_16x16x32_bf16 v[224:227], v[232:235], v[240:243], v[224:227]
	v_cvt_pk_bf16_f32 v236, v66, v67
	v_cvt_pk_bf16_f32 v237, v68, v69
	v_cvt_pk_bf16_f32 v238, v70, v71
	v_cvt_pk_bf16_f32 v239, v72, v73
	s_waitcnt lgkmcnt(7)
	ds_read_b64_tr_b16 v[202:203], v124 offset:12288
	ds_read_b64_tr_b16 v[204:205], v124 offset:14336
	ds_read_b64_tr_b16 v[206:207], v125 offset:12288
	ds_read_b64_tr_b16 v[208:209], v125 offset:14336
	ds_read_b64_tr_b16 v[228:229], v126 offset:12288
	ds_read_b64_tr_b16 v[230:231], v126 offset:14336
	ds_read_b64_tr_b16 v[232:233], v127 offset:12288
	ds_read_b64_tr_b16 v[234:235], v127 offset:14336
	v_fmamk_f32 v58, v130, 0x42c00000, v132
	v_fmamk_f32 v59, v130, 0x42be0000, v132
	v_fmamk_f32 v60, v130, 0x42bc0000, v132
	v_fmamk_f32 v61, v130, 0x42ba0000, v132
	v_fmamk_f32 v62, v130, 0x42a00000, v132
	v_fmamk_f32 v63, v130, 0x429e0000, v132
	v_fmamk_f32 v64, v130, 0x429c0000, v132
	v_fmamk_f32 v65, v130, 0x429a0000, v132
	s_waitcnt lgkmcnt(14)
	v_mfma_f32_16x16x32_bf16 v[210:213], v[186:189], v[236:239], v[210:213]
	s_waitcnt lgkmcnt(12)
	v_mfma_f32_16x16x32_bf16 v[214:217], v[190:193], v[236:239], v[214:217]
	s_waitcnt lgkmcnt(10)
	v_mfma_f32_16x16x32_bf16 v[220:223], v[194:197], v[236:239], v[220:223]
	s_waitcnt lgkmcnt(8)
	v_mfma_f32_16x16x32_bf16 v[224:227], v[198:201], v[236:239], v[224:227]
	v_cvt_pk_bf16_f32 v240, v74, v75
	v_cvt_pk_bf16_f32 v241, v76, v77
	v_cvt_pk_bf16_f32 v242, v78, v79
	v_cvt_pk_bf16_f32 v243, v80, v81
	s_waitcnt lgkmcnt(7)
	ds_read_b64_tr_b16 v[186:187], v124 offset:16384
	ds_read_b64_tr_b16 v[188:189], v124 offset:18432
	ds_read_b64_tr_b16 v[190:191], v125 offset:16384
	ds_read_b64_tr_b16 v[192:193], v125 offset:18432
	ds_read_b64_tr_b16 v[194:195], v126 offset:16384
	ds_read_b64_tr_b16 v[196:197], v126 offset:18432
	ds_read_b64_tr_b16 v[198:199], v127 offset:16384
	ds_read_b64_tr_b16 v[200:201], v127 offset:18432
	v_fmamk_f32 v66, v130, 0x42800000, v132
	v_fmamk_f32 v67, v130, 0x427c0000, v132
	v_fmamk_f32 v68, v130, 0x42780000, v132
	v_fmamk_f32 v69, v130, 0x42740000, v132
	v_fmamk_f32 v70, v130, 0x42400000, v132
	v_fmamk_f32 v71, v130, 0x423c0000, v132
	v_fmamk_f32 v72, v130, 0x42380000, v132
	v_fmamk_f32 v73, v130, 0x42340000, v132
	s_waitcnt lgkmcnt(14)
	v_mfma_f32_16x16x32_bf16 v[210:213], v[202:205], v[240:243], v[210:213]
	s_waitcnt lgkmcnt(12)
	v_mfma_f32_16x16x32_bf16 v[214:217], v[206:209], v[240:243], v[214:217]
	s_waitcnt lgkmcnt(10)
	v_mfma_f32_16x16x32_bf16 v[220:223], v[228:231], v[240:243], v[220:223]
	s_waitcnt lgkmcnt(8)
	v_mfma_f32_16x16x32_bf16 v[224:227], v[232:235], v[240:243], v[224:227]
	v_cvt_pk_bf16_f32 v236, v82, v83
	v_cvt_pk_bf16_f32 v237, v84, v85
	v_cvt_pk_bf16_f32 v238, v86, v87
	v_cvt_pk_bf16_f32 v239, v88, v89
	s_waitcnt lgkmcnt(7)
	ds_read_b64_tr_b16 v[202:203], v124 offset:20480
	ds_read_b64_tr_b16 v[204:205], v124 offset:22528
	ds_read_b64_tr_b16 v[206:207], v125 offset:20480
	ds_read_b64_tr_b16 v[208:209], v125 offset:22528
	ds_read_b64_tr_b16 v[228:229], v126 offset:20480
	ds_read_b64_tr_b16 v[230:231], v126 offset:22528
	ds_read_b64_tr_b16 v[232:233], v127 offset:20480
	ds_read_b64_tr_b16 v[234:235], v127 offset:22528
	v_fmamk_f32 v74, v130, 0x42000000, v132
	v_fmamk_f32 v75, v130, 0x41f80000, v132
	v_fmamk_f32 v76, v130, 0x41f00000, v132
	v_fmamk_f32 v77, v130, 0x41e80000, v132
	v_fmamk_f32 v78, v130, 0x41800000, v132
	v_fmamk_f32 v79, v130, 0x41700000, v132
	v_fmamk_f32 v80, v130, 0x41600000, v132
	v_fmamk_f32 v81, v130, 0x41500000, v132
	s_waitcnt lgkmcnt(14)
	v_mfma_f32_16x16x32_bf16 v[210:213], v[186:189], v[236:239], v[210:213]
	s_waitcnt lgkmcnt(12)
	v_mfma_f32_16x16x32_bf16 v[214:217], v[190:193], v[236:239], v[214:217]
	s_waitcnt lgkmcnt(10)
	v_mfma_f32_16x16x32_bf16 v[220:223], v[194:197], v[236:239], v[220:223]
	s_waitcnt lgkmcnt(8)
; #define LAS __attribute__((address_space(3)))
; __device__ __forceinline__ unsigned pk2(float lo, float hi) { return pg8::cvt_pk_bf16(lo, hi); }
; __device__ __forceinline__ s16x4 vtr(const LAS unsigned char* p) { return __builtin_bit_cast(s16x4, __builtin_amdgcn_ds_read_tr16_b64_v4i16((LAS s16x4*)p)); }
; #define MFMA16(a, b, c) __builtin_amdgcn_mfma_f32_16x16x32_bf16((a), (b), (c), 0, 0, 0)
; __device__ __forceinline__ void pv_at(const LAS unsigned char* const (&vp)[4], int off, const f32x4& P0, const f32x4& P1, f32x4 (&O)[4]) {
;     v4u pw; pw.x = pk2(P0[0], P0[1]); pw.y = pk2(P0[2], P0[3]); pw.z = pk2(P1[0], P1[1]); pw.w = pk2(P1[2], P1[3]);
;     const bf16x8 pb = __builtin_bit_cast(bf16x8, pw);
; #pragma unroll
;     for (int db = 0; db < 4; ++db) {
;         const s16x4 lo = vtr(vp[db] + off), hi = vtr(vp[db] + off + 2048);
;         const bf16x8 vt = (bf16x8){lo[0], lo[1], lo[2], lo[3], hi[0], hi[1], hi[2], hi[3]};
;         O[db] = MFMA16(vt, pb, O[db]);
;     }
; }
; template <bool MASK> __device__ __forceinline__ void a_scores(f32x4& S0, f32x4& S1, float basef, float c1, float slope2, int krow0, int kstart) {
; #pragma unroll
;     for (int r = 0; r < 4; ++r) {
;         const float d0 = fabsf(basef - (float)r), d1 = fabsf(basef - (float)(16 + r));
;         const float v0 = S0[r] - slope2 * d0, v1 = S1[r] - slope2 * d1;
;         if (MASK) { const int p0 = kstart + krow0 + r, p1 = p0 + 16;
;             S0[r] = (d0 <= 128.f && p0 >= 0 && p0 < SEQ) ? v0 : -INFINITY; S1[r] = (d1 <= 128.f && p1 >= 0 && p1 < SEQ) ? v1 : -INFINITY; }
;         else { S0[r] = v0; S1[r] = v1; }
;     }
; }
	v_mfma_f32_16x16x32_bf16 v[224:227], v[198:201], v[236:239], v[224:227]
	v_cvt_pk_bf16_f32 v240, v90, v91
	v_cvt_pk_bf16_f32 v241, v92, v93
	v_cvt_pk_bf16_f32 v242, v94, v95
	v_cvt_pk_bf16_f32 v243, v96, v97
	s_waitcnt lgkmcnt(7)
	ds_read_b64_tr_b16 v[186:187], v124 offset:24576
	ds_read_b64_tr_b16 v[188:189], v124 offset:26624
	ds_read_b64_tr_b16 v[190:191], v125 offset:24576
	ds_read_b64_tr_b16 v[192:193], v125 offset:26624
	ds_read_b64_tr_b16 v[194:195], v126 offset:24576
	ds_read_b64_tr_b16 v[196:197], v126 offset:26624
	ds_read_b64_tr_b16 v[198:199], v127 offset:24576
	ds_read_b64_tr_b16 v[200:201], v127 offset:26624
	v_add_f32_e32 v219, 0, v129
	v_mul_f32_e64 v82, v130, |v219|
	v_add_f32_e32 v245, 0xbf800000, v129
	v_mul_f32_e64 v83, v130, |v245|
	v_add_f32_e32 v219, 0xc0000000, v129
	v_mul_f32_e64 v84, v130, |v219|
	v_add_f32_e32 v245, 0xc0400000, v129
	v_mul_f32_e64 v85, v130, |v245|
	v_fmamk_f32 v86, v131, 0xc1800000, v133
	v_fmamk_f32 v87, v131, 0xc1880000, v133
	v_fmamk_f32 v88, v131, 0xc1900000, v133
	v_fmamk_f32 v89, v131, 0xc1980000, v133
	s_waitcnt lgkmcnt(14)
	v_mfma_f32_16x16x32_bf16 v[210:213], v[202:205], v[240:243], v[210:213]
	s_waitcnt lgkmcnt(12)
	v_mfma_f32_16x16x32_bf16 v[214:217], v[206:209], v[240:243], v[214:217]
	s_waitcnt lgkmcnt(10)
	v_mfma_f32_16x16x32_bf16 v[220:223], v[228:231], v[240:243], v[220:223]
	s_waitcnt lgkmcnt(8)
	v_mfma_f32_16x16x32_bf16 v[224:227], v[232:235], v[240:243], v[224:227]
	v_cvt_pk_bf16_f32 v236, v98, v99
	v_cvt_pk_bf16_f32 v237, v100, v101
	v_cvt_pk_bf16_f32 v238, v102, v103
	v_cvt_pk_bf16_f32 v239, v104, v105
	s_waitcnt lgkmcnt(7)
	ds_read_b64_tr_b16 v[202:203], v124 offset:28672
	ds_read_b64_tr_b16 v[204:205], v124 offset:30720
	ds_read_b64_tr_b16 v[206:207], v125 offset:28672
	ds_read_b64_tr_b16 v[208:209], v125 offset:30720
	ds_read_b64_tr_b16 v[228:229], v126 offset:28672
	ds_read_b64_tr_b16 v[230:231], v126 offset:30720
	ds_read_b64_tr_b16 v[232:233], v127 offset:28672
	ds_read_b64_tr_b16 v[234:235], v127 offset:30720
	v_fmamk_f32 v90, v131, 0xc2000000, v133
	v_fmamk_f32 v91, v131, 0xc2040000, v133
	v_fmamk_f32 v92, v131, 0xc2080000, v133
	v_fmamk_f32 v93, v131, 0xc20c0000, v133
	v_fmamk_f32 v94, v131, 0xc2400000, v133
	v_fmamk_f32 v95, v131, 0xc2440000, v133
	v_fmamk_f32 v96, v131, 0xc2480000, v133
	v_fmamk_f32 v97, v131, 0xc24c0000, v133
	s_waitcnt lgkmcnt(14)
	v_mfma_f32_16x16x32_bf16 v[210:213], v[186:189], v[236:239], v[210:213]
	s_waitcnt lgkmcnt(12)
	v_mfma_f32_16x16x32_bf16 v[214:217], v[190:193], v[236:239], v[214:217]
	s_waitcnt lgkmcnt(10)
	v_mfma_f32_16x16x32_bf16 v[220:223], v[194:197], v[236:239], v[220:223]
	s_waitcnt lgkmcnt(8)
	v_mfma_f32_16x16x32_bf16 v[224:227], v[198:201], v[236:239], v[224:227]
	v_cvt_pk_bf16_f32 v240, v106, v107
	v_cvt_pk_bf16_f32 v241, v108, v109
	v_cvt_pk_bf16_f32 v242, v110, v111
	v_cvt_pk_bf16_f32 v243, v112, v113
	s_waitcnt lgkmcnt(7)
	ds_read_b64_tr_b16 v[186:187], v124 offset:32768
	ds_read_b64_tr_b16 v[188:189], v124 offset:34816
	ds_read_b64_tr_b16 v[190:191], v125 offset:32768
	ds_read_b64_tr_b16 v[192:193], v125 offset:34816
	ds_read_b64_tr_b16 v[194:195], v126 offset:32768
	ds_read_b64_tr_b16 v[196:197], v126 offset:34816
	ds_read_b64_tr_b16 v[198:199], v127 offset:32768
	ds_read_b64_tr_b16 v[200:201], v127 offset:34816
	v_fmamk_f32 v98, v131, 0xc2800000, v133
	v_fmamk_f32 v99, v131, 0xc2820000, v133
	v_fmamk_f32 v100, v131, 0xc2840000, v133
	v_fmamk_f32 v101, v131, 0xc2860000, v133
	v_fmamk_f32 v102, v131, 0xc2a00000, v133
	v_fmamk_f32 v103, v131, 0xc2a20000, v133
	v_fmamk_f32 v104, v131, 0xc2a40000, v133
	v_fmamk_f32 v105, v131, 0xc2a60000, v133
	s_waitcnt lgkmcnt(14)
	v_mfma_f32_16x16x32_bf16 v[210:213], v[202:205], v[240:243], v[210:213]
	s_waitcnt lgkmcnt(12)
	v_mfma_f32_16x16x32_bf16 v[214:217], v[206:209], v[240:243], v[214:217]
	s_waitcnt lgkmcnt(10)
	v_mfma_f32_16x16x32_bf16 v[220:223], v[228:231], v[240:243], v[220:223]
	s_waitcnt lgkmcnt(8)
	v_mfma_f32_16x16x32_bf16 v[224:227], v[232:235], v[240:243], v[224:227]
	v_cvt_pk_bf16_f32 v236, v114, v115
	v_cvt_pk_bf16_f32 v237, v116, v117
	v_mov_b32_e32 v238, 0
	v_mov_b32_e32 v239, 0
	s_nop 1
	v_fmamk_f32 v106, v131, 0xc2c00000, v133
	v_fmamk_f32 v107, v131, 0xc2c20000, v133
	v_fmamk_f32 v108, v131, 0xc2c40000, v133
	v_fmamk_f32 v109, v131, 0xc2c60000, v133
	v_fmamk_f32 v110, v131, 0xc2e00000, v133
	v_fmamk_f32 v111, v131, 0xc2e20000, v133
	v_fmamk_f32 v112, v131, 0xc2e40000, v133
	v_fmamk_f32 v113, v131, 0xc2e60000, v133
	s_waitcnt lgkmcnt(6)
	v_mfma_f32_16x16x32_bf16 v[210:213], v[186:189], v[236:239], v[210:213]
	s_waitcnt lgkmcnt(4)
	v_mfma_f32_16x16x32_bf16 v[214:217], v[190:193], v[236:239], v[214:217]
	s_waitcnt lgkmcnt(2)
	v_mfma_f32_16x16x32_bf16 v[220:223], v[194:197], v[236:239], v[220:223]
	s_waitcnt lgkmcnt(0)
; #define LAS __attribute__((address_space(3)))
; __device__ __forceinline__ unsigned pk2(float lo, float hi) { return pg8::cvt_pk_bf16(lo, hi); }
; #define MFMA16(a, b, c) __builtin_amdgcn_mfma_f32_16x16x32_bf16((a), (b), (c), 0, 0, 0)
; __device__ __forceinline__ void qk_at(const LAS unsigned char* kp0, const LAS unsigned char* kp1, int off, bf16x8 qf0, bf16x8 qf1, f32x4& S0, f32x4& S1) {
;     const bf16x8 k00 = *(const LAS bf16x8*)(kp0 + off), k01 = *(const LAS bf16x8*)(kp1 + off);
;     const bf16x8 k10 = *(const LAS bf16x8*)(kp0 + off + 2048), k11 = *(const LAS bf16x8*)(kp1 + off + 2048);
;     const f32x4 z = {0.f, 0.f, 0.f, 0.f};
;     S0 = MFMA16(k00, qf0, z); S0 = MFMA16(k01, qf1, S0);
;     S1 = MFMA16(k10, qf0, z); S1 = MFMA16(k11, qf1, S1);
; }
; __device__ __forceinline__ void store_o(bf16* yrow, int g, float l, const f32x4 (&O)[4]) {
;     const float inv = 1.0f / xrow16_sum(l);
;     unsigned wx[4], wy[4];
; #pragma unroll
;     for (int db = 0; db < 4; ++db) { wx[db] = pk2(O[db][0] * inv, O[db][1] * inv); wy[db] = pk2(O[db][2] * inv, O[db][3] * inv); }
; #pragma unroll
;     for (int p = 0; p < 2; ++p) {
;         auto rx = __builtin_amdgcn_permlane16_swap(wx[2 * p], wx[2 * p + 1], false, false); wx[2 * p] = rx[0]; wx[2 * p + 1] = rx[1];
;         auto ry = __builtin_amdgcn_permlane16_swap(wy[2 * p], wy[2 * p + 1], false, false); wy[2 * p] = ry[0]; wy[2 * p + 1] = ry[1]; }
; #pragma unroll
;     for (int p = 0; p < 2; ++p) {
;         auto rx = __builtin_amdgcn_permlane32_swap(wx[p], wx[p + 2], false, false); wx[p] = rx[0]; wx[p + 2] = rx[1];
;         auto ry = __builtin_amdgcn_permlane32_swap(wy[p], wy[p + 2], false, false); wy[p] = ry[0]; wy[p + 2] = ry[1]; }
;     v4u lo = {wx[0], wy[0], wx[1], wy[1]}, hi = {wx[2], wy[2], wx[3], wy[3]};
;     *(v4u*)(yrow + 16 * g) = lo; *(v4u*)(yrow + 16 * g + 8) = hi;
	v_mfma_f32_16x16x32_bf16 v[224:227], v[198:201], v[236:239], v[224:227]
	v_fmamk_f32 v114, v131, 0xc3000000, v133
	v_fmamk_f32 v115, v131, 0xc3010000, v133
	v_fmamk_f32 v116, v131, 0xc3020000, v133
	v_fmamk_f32 v117, v131, 0xc3030000, v133
	v_mov_b32_e32 v245, 0xff800000
	v_cndmask_b32_e64 v114, v245, v114, s[28:29]
	v_cndmask_b32_e64 v115, v245, v115, s[52:53]
	v_cndmask_b32_e64 v116, v245, v116, s[54:55]
	v_cndmask_b32_e64 v117, v245, v117, s[88:89]
	v_mov_b32_e32 v219, v185
	s_nop 1
	v_permlane16_swap_b32_e32 v185, v219
	v_add_f32_e32 v185, v185, v219
	v_mov_b32_e32 v219, v185
	s_nop 1
	v_permlane32_swap_b32_e32 v185, v219
	v_add_f32_e32 v185, v185, v219
	v_div_scale_f32 v236, s[78:79], v185, v185, 1.0
	v_div_scale_f32 v237, vcc, 1.0, v185, 1.0
	v_rcp_f32_e32 v238, v236
	s_nop 0
	v_fma_f32 v239, -v236, v238, 1.0
	v_fmac_f32_e32 v238, v239, v238
	v_mul_f32_e32 v240, v237, v238
	v_fma_f32 v241, -v236, v240, v237
	v_fmac_f32_e32 v240, v241, v238
	v_fma_f32 v237, -v236, v240, v237
	v_div_fmas_f32 v237, v237, v238, v240
	v_div_fixup_f32 v244, v237, v185, 1.0
	v_mul_f32_e32 v240, v210, v244
	v_mul_f32_e32 v241, v211, v244
	v_mul_f32_e32 v242, v212, v244
	v_mul_f32_e32 v243, v213, v244
	v_cvt_pk_bf16_f32 v186, v240, v241
	v_cvt_pk_bf16_f32 v187, v242, v243
	v_mul_f32_e32 v240, v214, v244
	v_mul_f32_e32 v241, v215, v244
	v_mul_f32_e32 v242, v216, v244
	v_mul_f32_e32 v243, v217, v244
	v_cvt_pk_bf16_f32 v188, v240, v241
	v_cvt_pk_bf16_f32 v189, v242, v243
	v_mul_f32_e32 v240, v220, v244
	v_mul_f32_e32 v241, v221, v244
	v_mul_f32_e32 v242, v222, v244
	v_mul_f32_e32 v243, v223, v244
	v_cvt_pk_bf16_f32 v190, v240, v241
	v_cvt_pk_bf16_f32 v191, v242, v243
	v_mul_f32_e32 v240, v224, v244
	v_mul_f32_e32 v241, v225, v244
	v_mul_f32_e32 v242, v226, v244
	v_mul_f32_e32 v243, v227, v244
	v_cvt_pk_bf16_f32 v192, v240, v241
	v_cvt_pk_bf16_f32 v193, v242, v243
	s_nop 1
	v_permlane16_swap_b32_e32 v186, v188
	v_permlane16_swap_b32_e32 v187, v189
	v_permlane16_swap_b32_e32 v190, v192
	v_permlane16_swap_b32_e32 v191, v193
	s_nop 0
	v_permlane32_swap_b32_e32 v186, v190
	v_permlane32_swap_b32_e32 v187, v191
	v_permlane32_swap_b32_e32 v188, v192
	v_permlane32_swap_b32_e32 v189, v193
	global_store_dwordx4 v128, v[186:189], s[82:83] offset:0
	global_store_dwordx4 v128, v[190:193], s[82:83] offset:16
	s_nop 1
	ds_read_b128 v[186:189], v122 offset:2048
	ds_read_b128 v[190:193], v123 offset:2048
	ds_read_b128 v[194:197], v122 offset:4096
	ds_read_b128 v[198:201], v123 offset:4096
	ds_read_b128 v[202:205], v122 offset:6144
	ds_read_b128 v[206:209], v123 offset:6144
	ds_read_b128 v[210:213], v122 offset:8192
	ds_read_b128 v[214:217], v123 offset:8192
	ds_read_b128 v[220:223], v122 offset:10240
	ds_read_b128 v[224:227], v123 offset:10240
	ds_read_b128 v[228:231], v122 offset:12288
	ds_read_b128 v[232:235], v123 offset:12288
	ds_read_b128 v[236:239], v122 offset:14336
	ds_read_b128 v[240:243], v123 offset:14336
	s_waitcnt lgkmcnt(13)
	v_mfma_f32_16x16x32_bf16 v[50:53], v[186:189], v[154:157], v[50:53]
	s_waitcnt lgkmcnt(12)
	v_mfma_f32_16x16x32_bf16 v[50:53], v[190:193], v[158:161], v[50:53]
	ds_read_b128 v[186:189], v122 offset:16384
	ds_read_b128 v[190:193], v123 offset:16384
	s_waitcnt lgkmcnt(13)
	v_mfma_f32_16x16x32_bf16 v[54:57], v[194:197], v[154:157], v[54:57]
	s_waitcnt lgkmcnt(12)
	v_mfma_f32_16x16x32_bf16 v[54:57], v[198:201], v[158:161], v[54:57]
	ds_read_b128 v[194:197], v122 offset:18432
	ds_read_b128 v[198:201], v123 offset:18432
	s_waitcnt lgkmcnt(13)
	v_mfma_f32_16x16x32_bf16 v[58:61], v[202:205], v[154:157], v[58:61]
	s_waitcnt lgkmcnt(12)
	v_mfma_f32_16x16x32_bf16 v[58:61], v[206:209], v[158:161], v[58:61]
	ds_read_b128 v[202:205], v122 offset:20480
	ds_read_b128 v[206:209], v123 offset:20480
	s_waitcnt lgkmcnt(13)
	v_mfma_f32_16x16x32_bf16 v[62:65], v[210:213], v[154:157], v[62:65]
	s_waitcnt lgkmcnt(12)
	v_mfma_f32_16x16x32_bf16 v[62:65], v[214:217], v[158:161], v[62:65]
	ds_read_b128 v[210:213], v122 offset:22528
	ds_read_b128 v[214:217], v123 offset:22528
	s_waitcnt lgkmcnt(13)
	v_mfma_f32_16x16x32_bf16 v[66:69], v[220:223], v[154:157], v[66:69]
	s_waitcnt lgkmcnt(12)
	v_mfma_f32_16x16x32_bf16 v[66:69], v[224:227], v[158:161], v[66:69]
	ds_read_b128 v[220:223], v122 offset:24576
	ds_read_b128 v[224:227], v123 offset:24576
	s_waitcnt lgkmcnt(13)
	v_mfma_f32_16x16x32_bf16 v[70:73], v[228:231], v[154:157], v[70:73]
	s_waitcnt lgkmcnt(12)
	v_mfma_f32_16x16x32_bf16 v[70:73], v[232:235], v[158:161], v[70:73]
	ds_read_b128 v[228:231], v122 offset:26624
	ds_read_b128 v[232:235], v123 offset:26624
	s_waitcnt lgkmcnt(13)
	v_mfma_f32_16x16x32_bf16 v[74:77], v[236:239], v[154:157], v[74:77]
	s_waitcnt lgkmcnt(12)
	v_mfma_f32_16x16x32_bf16 v[74:77], v[240:243], v[158:161], v[74:77]
	ds_read_b128 v[236:239], v122 offset:28672
	ds_read_b128 v[240:243], v123 offset:28672
	s_waitcnt lgkmcnt(13)
	v_mfma_f32_16x16x32_bf16 v[78:81], v[186:189], v[154:157], v[78:81]
	s_waitcnt lgkmcnt(12)
	v_mfma_f32_16x16x32_bf16 v[78:81], v[190:193], v[158:161], v[78:81]
	ds_read_b128 v[186:189], v122 offset:30720
	ds_read_b128 v[190:193], v123 offset:30720
	s_waitcnt lgkmcnt(13)
	v_mfma_f32_16x16x32_bf16 v[82:85], v[194:197], v[154:157], v[82:85]
	s_waitcnt lgkmcnt(12)
	v_mfma_f32_16x16x32_bf16 v[82:85], v[198:201], v[158:161], v[82:85]
	ds_read_b128 v[194:197], v122 offset:32768
	ds_read_b128 v[198:201], v123 offset:32768
	s_waitcnt lgkmcnt(13)
	v_mfma_f32_16x16x32_bf16 v[86:89], v[202:205], v[154:157], v[86:89]
	s_waitcnt lgkmcnt(12)
	v_mfma_f32_16x16x32_bf16 v[86:89], v[206:209], v[158:161], v[86:89]
	ds_read_b128 v[202:205], v122 offset:34816
	ds_read_b128 v[206:209], v123 offset:34816
	s_waitcnt lgkmcnt(13)
; #define LAS __attribute__((address_space(3)))
; #define MFMA16(a, b, c) __builtin_amdgcn_mfma_f32_16x16x32_bf16((a), (b), (c), 0, 0, 0)
; __device__ __forceinline__ void qk_at(const LAS unsigned char* kp0, const LAS unsigned char* kp1, int off, bf16x8 qf0, bf16x8 qf1, f32x4& S0, f32x4& S1) {
;     const bf16x8 k00 = *(const LAS bf16x8*)(kp0 + off), k01 = *(const LAS bf16x8*)(kp1 + off);
;     const bf16x8 k10 = *(const LAS bf16x8*)(kp0 + off + 2048), k11 = *(const LAS bf16x8*)(kp1 + off + 2048);
;     const f32x4 z = {0.f, 0.f, 0.f, 0.f};
;     S0 = MFMA16(k00, qf0, z); S0 = MFMA16(k01, qf1, S0);
;     S1 = MFMA16(k10, qf0, z); S1 = MFMA16(k11, qf1, S1);
; }
; __device__ __forceinline__ void softmax_step(f32x4& s0, f32x4& s1, float& m, float& l, f32x4 (&O)[4]) {
;     float t = fmaxf(fmaxf(fmaxf(s0[0], s0[1]), fmaxf(s0[2], s0[3])), fmaxf(fmaxf(s1[0], s1[1]), fmaxf(s1[2], s1[3])));
;     t = xrow16_max(t);
;     const float mn = fmaxf(m, t), alpha = __builtin_amdgcn_exp2f(m - mn);
;     m = mn;
	v_mfma_f32_16x16x32_bf16 v[90:93], v[210:213], v[154:157], v[90:93]
	s_waitcnt lgkmcnt(12)
	v_mfma_f32_16x16x32_bf16 v[90:93], v[214:217], v[158:161], v[90:93]
	s_waitcnt lgkmcnt(11)
	v_mfma_f32_16x16x32_bf16 v[94:97], v[220:223], v[154:157], v[94:97]
	s_waitcnt lgkmcnt(10)
	v_mfma_f32_16x16x32_bf16 v[94:97], v[224:227], v[158:161], v[94:97]
	s_waitcnt lgkmcnt(9)
	v_mfma_f32_16x16x32_bf16 v[98:101], v[228:231], v[154:157], v[98:101]
	s_waitcnt lgkmcnt(8)
	v_mfma_f32_16x16x32_bf16 v[98:101], v[232:235], v[158:161], v[98:101]
	s_waitcnt lgkmcnt(7)
	v_mfma_f32_16x16x32_bf16 v[102:105], v[236:239], v[154:157], v[102:105]
	s_waitcnt lgkmcnt(6)
	v_mfma_f32_16x16x32_bf16 v[102:105], v[240:243], v[158:161], v[102:105]
	s_waitcnt lgkmcnt(5)
	v_mfma_f32_16x16x32_bf16 v[106:109], v[186:189], v[154:157], v[106:109]
	s_waitcnt lgkmcnt(4)
	v_mfma_f32_16x16x32_bf16 v[106:109], v[190:193], v[158:161], v[106:109]
	s_waitcnt lgkmcnt(3)
	v_mfma_f32_16x16x32_bf16 v[110:113], v[194:197], v[154:157], v[110:113]
	s_waitcnt lgkmcnt(2)
	v_mfma_f32_16x16x32_bf16 v[110:113], v[198:201], v[158:161], v[110:113]
	s_waitcnt lgkmcnt(1)
	v_mfma_f32_16x16x32_bf16 v[114:117], v[202:205], v[154:157], v[114:117]
	s_waitcnt lgkmcnt(0)
	v_mfma_f32_16x16x32_bf16 v[114:117], v[206:209], v[158:161], v[114:117]
	v_max3_f32 v219, v50, v51, v52
	v_max3_f32 v244, v54, v55, v56
	v_max3_f32 v245, v58, v59, v60
	v_max3_f32 v120, v62, v63, v64
	v_max3_f32 v219, v219, v53, v66
	v_max3_f32 v244, v244, v57, v70
	v_max3_f32 v245, v245, v61, v74
	v_max3_f32 v120, v120, v65, v78
	v_max3_f32 v219, v219, v67, v68
	v_max3_f32 v244, v244, v71, v72
	v_max3_f32 v245, v245, v75, v76
	v_max3_f32 v120, v120, v79, v80
	ds_read_b64_tr_b16 v[186:187], v124 offset:2048
	ds_read_b64_tr_b16 v[188:189], v124 offset:4096
	ds_read_b64_tr_b16 v[190:191], v125 offset:2048
	ds_read_b64_tr_b16 v[192:193], v125 offset:4096
	ds_read_b64_tr_b16 v[194:195], v126 offset:2048
	ds_read_b64_tr_b16 v[196:197], v126 offset:4096
	ds_read_b64_tr_b16 v[198:199], v127 offset:2048
	ds_read_b64_tr_b16 v[200:201], v127 offset:4096
	v_max3_f32 v219, v219, v69, v82
	v_max3_f32 v244, v244, v73, v86
	v_max3_f32 v245, v245, v77, v90
	v_max3_f32 v120, v120, v81, v94
	v_max3_f32 v219, v219, v83, v84
	v_max3_f32 v244, v244, v87, v88
	v_max3_f32 v245, v245, v91, v92
	v_max3_f32 v120, v120, v95, v96
	v_max3_f32 v219, v219, v85, v98
	v_max3_f32 v244, v244, v89, v102
	v_max3_f32 v245, v245, v93, v106
	v_max3_f32 v120, v120, v97, v110
	v_max3_f32 v219, v219, v99, v100
	v_max3_f32 v244, v244, v103, v104
	v_max3_f32 v245, v245, v107, v108
	v_max3_f32 v120, v120, v111, v112
	v_max3_f32 v219, v219, v101, v114
	v_max3_f32 v219, v219, v115, v116
	v_max_f32_e32 v219, v219, v117
	v_max_f32_e32 v244, v244, v105
	v_max_f32_e32 v245, v245, v109
	v_max_f32_e32 v120, v120, v113
	v_max3_f32 v178, v219, v244, v245
	v_max_f32_e32 v178, v178, v120
	v_mov_b32_e32 v219, v178
	s_nop 1
	v_permlane16_swap_b32_e32 v178, v219
	v_max_f32_e32 v178, v178, v219
	v_mov_b32_e32 v219, v178
	s_nop 1
	v_permlane32_swap_b32_e32 v178, v219
	v_max3_f32 v178, v178, v219, v145
	s_waitcnt lgkmcnt(7)
	ds_read_b64_tr_b16 v[202:203], v124 offset:6144
	ds_read_b64_tr_b16 v[204:205], v124 offset:8192
	ds_read_b64_tr_b16 v[206:207], v125 offset:6144
	ds_read_b64_tr_b16 v[208:209], v125 offset:8192
	ds_read_b64_tr_b16 v[228:229], v126 offset:6144
	ds_read_b64_tr_b16 v[230:231], v126 offset:8192
	ds_read_b64_tr_b16 v[232:233], v127 offset:6144
	ds_read_b64_tr_b16 v[234:235], v127 offset:8192
	v_mov_b32_e32 v244, v178
	v_pk_add_f32 v[50:51], v[50:51], v[244:245] op_sel_hi:[1,0] neg_lo:[0,1] neg_hi:[0,1]
	v_pk_add_f32 v[52:53], v[52:53], v[244:245] op_sel_hi:[1,0] neg_lo:[0,1] neg_hi:[0,1]
	v_pk_add_f32 v[54:55], v[54:55], v[244:245] op_sel_hi:[1,0] neg_lo:[0,1] neg_hi:[0,1]
	v_pk_add_f32 v[56:57], v[56:57], v[244:245] op_sel_hi:[1,0] neg_lo:[0,1] neg_hi:[0,1]
	v_pk_add_f32 v[58:59], v[58:59], v[244:245] op_sel_hi:[1,0] neg_lo:[0,1] neg_hi:[0,1]
	v_pk_add_f32 v[60:61], v[60:61], v[244:245] op_sel_hi:[1,0] neg_lo:[0,1] neg_hi:[0,1]
	v_pk_add_f32 v[62:63], v[62:63], v[244:245] op_sel_hi:[1,0] neg_lo:[0,1] neg_hi:[0,1]
	v_pk_add_f32 v[64:65], v[64:65], v[244:245] op_sel_hi:[1,0] neg_lo:[0,1] neg_hi:[0,1]
	v_pk_add_f32 v[66:67], v[66:67], v[244:245] op_sel_hi:[1,0] neg_lo:[0,1] neg_hi:[0,1]
	v_pk_add_f32 v[68:69], v[68:69], v[244:245] op_sel_hi:[1,0] neg_lo:[0,1] neg_hi:[0,1]
	v_pk_add_f32 v[70:71], v[70:71], v[244:245] op_sel_hi:[1,0] neg_lo:[0,1] neg_hi:[0,1]
	v_pk_add_f32 v[72:73], v[72:73], v[244:245] op_sel_hi:[1,0] neg_lo:[0,1] neg_hi:[0,1]
	v_pk_add_f32 v[74:75], v[74:75], v[244:245] op_sel_hi:[1,0] neg_lo:[0,1] neg_hi:[0,1]
	v_pk_add_f32 v[76:77], v[76:77], v[244:245] op_sel_hi:[1,0] neg_lo:[0,1] neg_hi:[0,1]
	v_pk_add_f32 v[78:79], v[78:79], v[244:245] op_sel_hi:[1,0] neg_lo:[0,1] neg_hi:[0,1]
	v_pk_add_f32 v[80:81], v[80:81], v[244:245] op_sel_hi:[1,0] neg_lo:[0,1] neg_hi:[0,1]
	v_pk_add_f32 v[82:83], v[82:83], v[244:245] op_sel_hi:[1,0] neg_lo:[0,1] neg_hi:[0,1]
	v_pk_add_f32 v[84:85], v[84:85], v[244:245] op_sel_hi:[1,0] neg_lo:[0,1] neg_hi:[0,1]
	v_pk_add_f32 v[86:87], v[86:87], v[244:245] op_sel_hi:[1,0] neg_lo:[0,1] neg_hi:[0,1]
	v_pk_add_f32 v[88:89], v[88:89], v[244:245] op_sel_hi:[1,0] neg_lo:[0,1] neg_hi:[0,1]
	v_pk_add_f32 v[90:91], v[90:91], v[244:245] op_sel_hi:[1,0] neg_lo:[0,1] neg_hi:[0,1]
	v_pk_add_f32 v[92:93], v[92:93], v[244:245] op_sel_hi:[1,0] neg_lo:[0,1] neg_hi:[0,1]
	v_pk_add_f32 v[94:95], v[94:95], v[244:245] op_sel_hi:[1,0] neg_lo:[0,1] neg_hi:[0,1]
	v_pk_add_f32 v[96:97], v[96:97], v[244:245] op_sel_hi:[1,0] neg_lo:[0,1] neg_hi:[0,1]
; __device__ __forceinline__ void softmax_step(f32x4& s0, f32x4& s1, float& m, float& l, f32x4 (&O)[4]) {
;     float t = fmaxf(fmaxf(fmaxf(s0[0], s0[1]), fmaxf(s0[2], s0[3])), fmaxf(fmaxf(s1[0], s1[1]), fmaxf(s1[2], s1[3])));
;     t = xrow16_max(t);
;     const float mn = fmaxf(m, t), alpha = __builtin_amdgcn_exp2f(m - mn);
;     m = mn;
; #pragma unroll
;     for (int k = 0; k < 4; ++k) { s0[k] = __builtin_amdgcn_exp2f(s0[k] - mn); s1[k] = __builtin_amdgcn_exp2f(s1[k] - mn); }
;     l = l * alpha + ((s0[0] + s0[1]) + (s0[2] + s0[3])) + ((s1[0] + s1[1]) + (s1[2] + s1[3]));
; #pragma unroll
;     for (int db = 0; db < 4; ++db) O[db] *= alpha;
; }
; template <bool MASK> __device__ __forceinline__ void a_scores(f32x4& S0, f32x4& S1, float basef, float c1, float slope2, int krow0, int kstart) {
; #pragma unroll
;     for (int r = 0; r < 4; ++r) {
;         const float d0 = fabsf(basef - (float)r), d1 = fabsf(basef - (float)(16 + r));
;         const float v0 = S0[r] - slope2 * d0, v1 = S1[r] - slope2 * d1;
;         if (MASK) { const int p0 = kstart + krow0 + r, p1 = p0 + 16;
;             S0[r] = (d0 <= 128.f && p0 >= 0 && p0 < SEQ) ? v0 : -INFINITY; S1[r] = (d1 <= 128.f && p1 >= 0 && p1 < SEQ) ? v1 : -INFINITY; }
;         else { S0[r] = v0; S1[r] = v1; }
;     }
; }
	v_pk_add_f32 v[98:99], v[98:99], v[244:245] op_sel_hi:[1,0] neg_lo:[0,1] neg_hi:[0,1]
	v_pk_add_f32 v[100:101], v[100:101], v[244:245] op_sel_hi:[1,0] neg_lo:[0,1] neg_hi:[0,1]
	v_pk_add_f32 v[102:103], v[102:103], v[244:245] op_sel_hi:[1,0] neg_lo:[0,1] neg_hi:[0,1]
	v_pk_add_f32 v[104:105], v[104:105], v[244:245] op_sel_hi:[1,0] neg_lo:[0,1] neg_hi:[0,1]
	v_pk_add_f32 v[106:107], v[106:107], v[244:245] op_sel_hi:[1,0] neg_lo:[0,1] neg_hi:[0,1]
	v_pk_add_f32 v[108:109], v[108:109], v[244:245] op_sel_hi:[1,0] neg_lo:[0,1] neg_hi:[0,1]
	v_pk_add_f32 v[110:111], v[110:111], v[244:245] op_sel_hi:[1,0] neg_lo:[0,1] neg_hi:[0,1]
	v_pk_add_f32 v[112:113], v[112:113], v[244:245] op_sel_hi:[1,0] neg_lo:[0,1] neg_hi:[0,1]
	v_pk_add_f32 v[114:115], v[114:115], v[244:245] op_sel_hi:[1,0] neg_lo:[0,1] neg_hi:[0,1]
	v_pk_add_f32 v[116:117], v[116:117], v[244:245] op_sel_hi:[1,0] neg_lo:[0,1] neg_hi:[0,1]
	v_sub_f32_e32 v219, v145, v178
	v_exp_f32_e32 v50, v50
	v_exp_f32_e32 v51, v51
	v_exp_f32_e32 v52, v52
	v_exp_f32_e32 v53, v53
	v_exp_f32_e32 v54, v54
	v_exp_f32_e32 v55, v55
	v_exp_f32_e32 v56, v56
	v_exp_f32_e32 v57, v57
	v_exp_f32_e32 v58, v58
	v_exp_f32_e32 v59, v59
	v_exp_f32_e32 v60, v60
	v_exp_f32_e32 v61, v61
	v_exp_f32_e32 v62, v62
	v_exp_f32_e32 v63, v63
	v_exp_f32_e32 v64, v64
	v_exp_f32_e32 v65, v65
	v_exp_f32_e32 v66, v66
	v_exp_f32_e32 v67, v67
	v_exp_f32_e32 v68, v68
	v_exp_f32_e32 v69, v69
	v_exp_f32_e32 v70, v70
	v_exp_f32_e32 v71, v71
	v_exp_f32_e32 v72, v72
	v_exp_f32_e32 v73, v73
	v_exp_f32_e32 v74, v74
	v_exp_f32_e32 v75, v75
	v_exp_f32_e32 v76, v76
	v_exp_f32_e32 v77, v77
	v_exp_f32_e32 v78, v78
	v_exp_f32_e32 v79, v79
	v_exp_f32_e32 v80, v80
	v_exp_f32_e32 v81, v81
	v_exp_f32_e32 v82, v82
	v_exp_f32_e32 v83, v83
	v_exp_f32_e32 v84, v84
	v_exp_f32_e32 v85, v85
	v_exp_f32_e32 v86, v86
	v_exp_f32_e32 v87, v87
	v_exp_f32_e32 v88, v88
	v_exp_f32_e32 v89, v89
	v_exp_f32_e32 v90, v90
	v_exp_f32_e32 v91, v91
	v_exp_f32_e32 v92, v92
	v_exp_f32_e32 v93, v93
	v_exp_f32_e32 v94, v94
	v_exp_f32_e32 v95, v95
	v_exp_f32_e32 v96, v96
	v_exp_f32_e32 v97, v97
	v_exp_f32_e32 v98, v98
	v_exp_f32_e32 v99, v99
	v_exp_f32_e32 v100, v100
	v_exp_f32_e32 v101, v101
	v_exp_f32_e32 v102, v102
	v_exp_f32_e32 v103, v103
	v_exp_f32_e32 v104, v104
	v_exp_f32_e32 v105, v105
	v_exp_f32_e32 v106, v106
	v_exp_f32_e32 v107, v107
	v_exp_f32_e32 v108, v108
	v_exp_f32_e32 v109, v109
	v_exp_f32_e32 v110, v110
	v_exp_f32_e32 v111, v111
	v_exp_f32_e32 v112, v112
	v_exp_f32_e32 v113, v113
	v_exp_f32_e32 v114, v114
	v_exp_f32_e32 v115, v115
	v_exp_f32_e32 v116, v116
	v_exp_f32_e32 v117, v117
	v_exp_f32_e32 v219, v219
	v_pk_add_f32 v[236:237], v[50:51], v[52:53]
	v_pk_add_f32 v[238:239], v[54:55], v[56:57]
	v_pk_add_f32 v[240:241], v[58:59], v[60:61]
	v_pk_add_f32 v[242:243], v[62:63], v[64:65]
	v_pk_add_f32 v[236:237], v[236:237], v[66:67]
	v_pk_add_f32 v[238:239], v[238:239], v[70:71]
	v_pk_add_f32 v[240:241], v[240:241], v[74:75]
	v_pk_add_f32 v[242:243], v[242:243], v[78:79]
	v_pk_add_f32 v[236:237], v[236:237], v[68:69]
	v_pk_add_f32 v[238:239], v[238:239], v[72:73]
	v_pk_add_f32 v[240:241], v[240:241], v[76:77]
	v_pk_add_f32 v[242:243], v[242:243], v[80:81]
	v_pk_add_f32 v[236:237], v[236:237], v[82:83]
	v_pk_add_f32 v[238:239], v[238:239], v[86:87]
	v_pk_add_f32 v[240:241], v[240:241], v[90:91]
	v_pk_add_f32 v[242:243], v[242:243], v[94:95]
	v_pk_add_f32 v[236:237], v[236:237], v[84:85]
	v_pk_add_f32 v[238:239], v[238:239], v[88:89]
	v_pk_add_f32 v[240:241], v[240:241], v[92:93]
	v_pk_add_f32 v[242:243], v[242:243], v[96:97]
	v_pk_add_f32 v[236:237], v[236:237], v[98:99]
	v_pk_add_f32 v[238:239], v[238:239], v[102:103]
	v_pk_add_f32 v[240:241], v[240:241], v[106:107]
	v_pk_add_f32 v[242:243], v[242:243], v[110:111]
	v_pk_add_f32 v[236:237], v[236:237], v[100:101]
	v_pk_add_f32 v[238:239], v[238:239], v[104:105]
	v_pk_add_f32 v[240:241], v[240:241], v[108:109]
	v_pk_add_f32 v[242:243], v[242:243], v[112:113]
	v_pk_add_f32 v[236:237], v[236:237], v[114:115]
	v_pk_add_f32 v[236:237], v[236:237], v[116:117]
	v_pk_add_f32 v[236:237], v[236:237], v[238:239]
	v_pk_add_f32 v[240:241], v[240:241], v[242:243]
	v_cndmask_b32_e64 v219, 0, v219, s[74:75]
	v_pk_add_f32 v[236:237], v[236:237], v[240:241]
	v_add_f32_e32 v185, v236, v237
	v_add_f32_e32 v185, v185, v219
	v_cvt_pk_bf16_f32 v236, v50, v51
	v_cvt_pk_bf16_f32 v237, v52, v53
	v_cvt_pk_bf16_f32 v238, v54, v55
	v_cvt_pk_bf16_f32 v239, v56, v57
	s_nop 1
	s_waitcnt lgkmcnt(14)
	v_mfma_f32_16x16x32_bf16 v[210:213], v[186:189], v[236:239], 0
	s_waitcnt lgkmcnt(12)
	v_mfma_f32_16x16x32_bf16 v[214:217], v[190:193], v[236:239], 0
	s_waitcnt lgkmcnt(10)
	v_mfma_f32_16x16x32_bf16 v[220:223], v[194:197], v[236:239], 0
	s_waitcnt lgkmcnt(8)
	v_mfma_f32_16x16x32_bf16 v[224:227], v[198:201], v[236:239], 0
	v_cvt_pk_bf16_f32 v240, v58, v59
	v_cvt_pk_bf16_f32 v241, v60, v61
	v_cvt_pk_bf16_f32 v242, v62, v63
	v_cvt_pk_bf16_f32 v243, v64, v65
	s_waitcnt lgkmcnt(7)
	ds_read_b64_tr_b16 v[186:187], v124 offset:10240
	ds_read_b64_tr_b16 v[188:189], v124 offset:12288
	ds_read_b64_tr_b16 v[190:191], v125 offset:10240
	ds_read_b64_tr_b16 v[192:193], v125 offset:12288
	ds_read_b64_tr_b16 v[194:195], v126 offset:10240
	ds_read_b64_tr_b16 v[196:197], v126 offset:12288
	ds_read_b64_tr_b16 v[198:199], v127 offset:10240
	ds_read_b64_tr_b16 v[200:201], v127 offset:12288
	v_fmamk_f32 v50, v130, 0x43000000, v132
	v_fmamk_f32 v51, v130, 0x42fe0000, v132
	v_fmamk_f32 v52, v130, 0x42fc0000, v132
	v_fmamk_f32 v53, v130, 0x42fa0000, v132
	v_mov_b32_e32 v245, 0xff800000
	v_cndmask_b32_e64 v50, v245, v50, s[16:17]
	v_cndmask_b32_e64 v51, v245, v51, s[18:19]
	v_cndmask_b32_e64 v52, v245, v52, s[22:23]
	v_cndmask_b32_e64 v53, v245, v53, s[24:25]
	v_fmamk_f32 v54, v130, 0x42e00000, v132
	v_fmamk_f32 v55, v130, 0x42de0000, v132
	v_fmamk_f32 v56, v130, 0x42dc0000, v132
	v_fmamk_f32 v57, v130, 0x42da0000, v132
	s_waitcnt lgkmcnt(14)
; #define LAS __attribute__((address_space(3)))
; __device__ __forceinline__ unsigned pk2(float lo, float hi) { return pg8::cvt_pk_bf16(lo, hi); }
; __device__ __forceinline__ s16x4 vtr(const LAS unsigned char* p) { return __builtin_bit_cast(s16x4, __builtin_amdgcn_ds_read_tr16_b64_v4i16((LAS s16x4*)p)); }
; #define MFMA16(a, b, c) __builtin_amdgcn_mfma_f32_16x16x32_bf16((a), (b), (c), 0, 0, 0)
; __device__ __forceinline__ void pv_at(const LAS unsigned char* const (&vp)[4], int off, const f32x4& P0, const f32x4& P1, f32x4 (&O)[4]) {
;     v4u pw; pw.x = pk2(P0[0], P0[1]); pw.y = pk2(P0[2], P0[3]); pw.z = pk2(P1[0], P1[1]); pw.w = pk2(P1[2], P1[3]);
;     const bf16x8 pb = __builtin_bit_cast(bf16x8, pw);
; #pragma unroll
;     for (int db = 0; db < 4; ++db) {
;         const s16x4 lo = vtr(vp[db] + off), hi = vtr(vp[db] + off + 2048);
;         const bf16x8 vt = (bf16x8){lo[0], lo[1], lo[2], lo[3], hi[0], hi[1], hi[2], hi[3]};
;         O[db] = MFMA16(vt, pb, O[db]);
;     }
; }
; template <bool MASK> __device__ __forceinline__ void a_scores(f32x4& S0, f32x4& S1, float basef, float c1, float slope2, int krow0, int kstart) {
; #pragma unroll
;     for (int r = 0; r < 4; ++r) {
;         const float d0 = fabsf(basef - (float)r), d1 = fabsf(basef - (float)(16 + r));
;         const float v0 = S0[r] - slope2 * d0, v1 = S1[r] - slope2 * d1;
;         if (MASK) { const int p0 = kstart + krow0 + r, p1 = p0 + 16;
;             S0[r] = (d0 <= 128.f && p0 >= 0 && p0 < SEQ) ? v0 : -INFINITY; S1[r] = (d1 <= 128.f && p1 >= 0 && p1 < SEQ) ? v1 : -INFINITY; }
;         else { S0[r] = v0; S1[r] = v1; }
;     }
; }
	v_mfma_f32_16x16x32_bf16 v[210:213], v[202:205], v[240:243], v[210:213]
	s_waitcnt lgkmcnt(12)
	v_mfma_f32_16x16x32_bf16 v[214:217], v[206:209], v[240:243], v[214:217]
	s_waitcnt lgkmcnt(10)
	v_mfma_f32_16x16x32_bf16 v[220:223], v[228:231], v[240:243], v[220:223]
	s_waitcnt lgkmcnt(8)
	v_mfma_f32_16x16x32_bf16 v[224:227], v[232:235], v[240:243], v[224:227]
	v_cvt_pk_bf16_f32 v236, v66, v67
	v_cvt_pk_bf16_f32 v237, v68, v69
	v_cvt_pk_bf16_f32 v238, v70, v71
	v_cvt_pk_bf16_f32 v239, v72, v73
	s_waitcnt lgkmcnt(7)
	ds_read_b64_tr_b16 v[202:203], v124 offset:14336
	ds_read_b64_tr_b16 v[204:205], v124 offset:16384
	ds_read_b64_tr_b16 v[206:207], v125 offset:14336
	ds_read_b64_tr_b16 v[208:209], v125 offset:16384
	ds_read_b64_tr_b16 v[228:229], v126 offset:14336
	ds_read_b64_tr_b16 v[230:231], v126 offset:16384
	ds_read_b64_tr_b16 v[232:233], v127 offset:14336
	ds_read_b64_tr_b16 v[234:235], v127 offset:16384
	v_fmamk_f32 v58, v130, 0x42c00000, v132
	v_fmamk_f32 v59, v130, 0x42be0000, v132
	v_fmamk_f32 v60, v130, 0x42bc0000, v132
	v_fmamk_f32 v61, v130, 0x42ba0000, v132
	v_fmamk_f32 v62, v130, 0x42a00000, v132
	v_fmamk_f32 v63, v130, 0x429e0000, v132
	v_fmamk_f32 v64, v130, 0x429c0000, v132
	v_fmamk_f32 v65, v130, 0x429a0000, v132
	s_waitcnt lgkmcnt(14)
	v_mfma_f32_16x16x32_bf16 v[210:213], v[186:189], v[236:239], v[210:213]
	s_waitcnt lgkmcnt(12)
	v_mfma_f32_16x16x32_bf16 v[214:217], v[190:193], v[236:239], v[214:217]
	s_waitcnt lgkmcnt(10)
	v_mfma_f32_16x16x32_bf16 v[220:223], v[194:197], v[236:239], v[220:223]
	s_waitcnt lgkmcnt(8)
	v_mfma_f32_16x16x32_bf16 v[224:227], v[198:201], v[236:239], v[224:227]
	v_cvt_pk_bf16_f32 v240, v74, v75
	v_cvt_pk_bf16_f32 v241, v76, v77
	v_cvt_pk_bf16_f32 v242, v78, v79
	v_cvt_pk_bf16_f32 v243, v80, v81
	s_waitcnt lgkmcnt(7)
	ds_read_b64_tr_b16 v[186:187], v124 offset:18432
	ds_read_b64_tr_b16 v[188:189], v124 offset:20480
	ds_read_b64_tr_b16 v[190:191], v125 offset:18432
	ds_read_b64_tr_b16 v[192:193], v125 offset:20480
	ds_read_b64_tr_b16 v[194:195], v126 offset:18432
	ds_read_b64_tr_b16 v[196:197], v126 offset:20480
	ds_read_b64_tr_b16 v[198:199], v127 offset:18432
	ds_read_b64_tr_b16 v[200:201], v127 offset:20480
	v_fmamk_f32 v66, v130, 0x42800000, v132
	v_fmamk_f32 v67, v130, 0x427c0000, v132
	v_fmamk_f32 v68, v130, 0x42780000, v132
	v_fmamk_f32 v69, v130, 0x42740000, v132
	v_fmamk_f32 v70, v130, 0x42400000, v132
	v_fmamk_f32 v71, v130, 0x423c0000, v132
	v_fmamk_f32 v72, v130, 0x42380000, v132
	v_fmamk_f32 v73, v130, 0x42340000, v132
	s_waitcnt lgkmcnt(14)
	v_mfma_f32_16x16x32_bf16 v[210:213], v[202:205], v[240:243], v[210:213]
	s_waitcnt lgkmcnt(12)
	v_mfma_f32_16x16x32_bf16 v[214:217], v[206:209], v[240:243], v[214:217]
	s_waitcnt lgkmcnt(10)
	v_mfma_f32_16x16x32_bf16 v[220:223], v[228:231], v[240:243], v[220:223]
	s_waitcnt lgkmcnt(8)
	v_mfma_f32_16x16x32_bf16 v[224:227], v[232:235], v[240:243], v[224:227]
	v_cvt_pk_bf16_f32 v236, v82, v83
	v_cvt_pk_bf16_f32 v237, v84, v85
	v_cvt_pk_bf16_f32 v238, v86, v87
	v_cvt_pk_bf16_f32 v239, v88, v89
	s_waitcnt lgkmcnt(7)
	ds_read_b64_tr_b16 v[202:203], v124 offset:22528
	ds_read_b64_tr_b16 v[204:205], v124 offset:24576
	ds_read_b64_tr_b16 v[206:207], v125 offset:22528
	ds_read_b64_tr_b16 v[208:209], v125 offset:24576
	ds_read_b64_tr_b16 v[228:229], v126 offset:22528
	ds_read_b64_tr_b16 v[230:231], v126 offset:24576
	ds_read_b64_tr_b16 v[232:233], v127 offset:22528
	ds_read_b64_tr_b16 v[234:235], v127 offset:24576
	v_fmamk_f32 v74, v130, 0x42000000, v132
	v_fmamk_f32 v75, v130, 0x41f80000, v132
	v_fmamk_f32 v76, v130, 0x41f00000, v132
	v_fmamk_f32 v77, v130, 0x41e80000, v132
	v_fmamk_f32 v78, v130, 0x41800000, v132
	v_fmamk_f32 v79, v130, 0x41700000, v132
	v_fmamk_f32 v80, v130, 0x41600000, v132
	v_fmamk_f32 v81, v130, 0x41500000, v132
	s_waitcnt lgkmcnt(14)
	v_mfma_f32_16x16x32_bf16 v[210:213], v[186:189], v[236:239], v[210:213]
	s_waitcnt lgkmcnt(12)
	v_mfma_f32_16x16x32_bf16 v[214:217], v[190:193], v[236:239], v[214:217]
	s_waitcnt lgkmcnt(10)
	v_mfma_f32_16x16x32_bf16 v[220:223], v[194:197], v[236:239], v[220:223]
	s_waitcnt lgkmcnt(8)
	v_mfma_f32_16x16x32_bf16 v[224:227], v[198:201], v[236:239], v[224:227]
	v_cvt_pk_bf16_f32 v240, v90, v91
	v_cvt_pk_bf16_f32 v241, v92, v93
	v_cvt_pk_bf16_f32 v242, v94, v95
	v_cvt_pk_bf16_f32 v243, v96, v97
	s_waitcnt lgkmcnt(7)
	ds_read_b64_tr_b16 v[186:187], v124 offset:26624
	ds_read_b64_tr_b16 v[188:189], v124 offset:28672
	ds_read_b64_tr_b16 v[190:191], v125 offset:26624
	ds_read_b64_tr_b16 v[192:193], v125 offset:28672
	ds_read_b64_tr_b16 v[194:195], v126 offset:26624
	ds_read_b64_tr_b16 v[196:197], v126 offset:28672
	ds_read_b64_tr_b16 v[198:199], v127 offset:26624
	ds_read_b64_tr_b16 v[200:201], v127 offset:28672
	v_add_f32_e32 v219, 0, v129
	v_mul_f32_e64 v82, v130, |v219|
	v_add_f32_e32 v245, 0xbf800000, v129
	v_mul_f32_e64 v83, v130, |v245|
	v_add_f32_e32 v219, 0xc0000000, v129
	v_mul_f32_e64 v84, v130, |v219|
	v_add_f32_e32 v245, 0xc0400000, v129
	v_mul_f32_e64 v85, v130, |v245|
	v_fmamk_f32 v86, v131, 0xc1800000, v133
	v_fmamk_f32 v87, v131, 0xc1880000, v133
	v_fmamk_f32 v88, v131, 0xc1900000, v133
	v_fmamk_f32 v89, v131, 0xc1980000, v133
	s_waitcnt lgkmcnt(14)
	v_mfma_f32_16x16x32_bf16 v[210:213], v[202:205], v[240:243], v[210:213]
	s_waitcnt lgkmcnt(12)
	v_mfma_f32_16x16x32_bf16 v[214:217], v[206:209], v[240:243], v[214:217]
	s_waitcnt lgkmcnt(10)
	v_mfma_f32_16x16x32_bf16 v[220:223], v[228:231], v[240:243], v[220:223]
	s_waitcnt lgkmcnt(8)
	v_mfma_f32_16x16x32_bf16 v[224:227], v[232:235], v[240:243], v[224:227]
	v_cvt_pk_bf16_f32 v236, v98, v99
	v_cvt_pk_bf16_f32 v237, v100, v101
	v_cvt_pk_bf16_f32 v238, v102, v103
	v_cvt_pk_bf16_f32 v239, v104, v105
	s_waitcnt lgkmcnt(7)
; #define LAS __attribute__((address_space(3)))
; __device__ __forceinline__ unsigned pk2(float lo, float hi) { return pg8::cvt_pk_bf16(lo, hi); }
; __device__ __forceinline__ void qk_at(const LAS unsigned char* kp0, const LAS unsigned char* kp1, int off, bf16x8 qf0, bf16x8 qf1, f32x4& S0, f32x4& S1) {
;     const bf16x8 k00 = *(const LAS bf16x8*)(kp0 + off), k01 = *(const LAS bf16x8*)(kp1 + off);
;     const bf16x8 k10 = *(const LAS bf16x8*)(kp0 + off + 2048), k11 = *(const LAS bf16x8*)(kp1 + off + 2048);
;     const f32x4 z = {0.f, 0.f, 0.f, 0.f};
;     S0 = MFMA16(k00, qf0, z); S0 = MFMA16(k01, qf1, S0);
;     S1 = MFMA16(k10, qf0, z); S1 = MFMA16(k11, qf1, S1);
; }
; __device__ __forceinline__ void pv_at(const LAS unsigned char* const (&vp)[4], int off, const f32x4& P0, const f32x4& P1, f32x4 (&O)[4]) {
;     v4u pw; pw.x = pk2(P0[0], P0[1]); pw.y = pk2(P0[2], P0[3]); pw.z = pk2(P1[0], P1[1]); pw.w = pk2(P1[2], P1[3]);
;     const bf16x8 pb = __builtin_bit_cast(bf16x8, pw);
; #pragma unroll
;     for (int db = 0; db < 4; ++db) {
;         const s16x4 lo = vtr(vp[db] + off), hi = vtr(vp[db] + off + 2048);
;         const bf16x8 vt = (bf16x8){lo[0], lo[1], lo[2], lo[3], hi[0], hi[1], hi[2], hi[3]};
;         O[db] = MFMA16(vt, pb, O[db]);
;     }
; }
; __device__ __forceinline__ void store_o(bf16* yrow, int g, float l, const f32x4 (&O)[4]) {
;     const float inv = 1.0f / xrow16_sum(l);
;     unsigned wx[4], wy[4];
; #pragma unroll
;     for (int db = 0; db < 4; ++db) { wx[db] = pk2(O[db][0] * inv, O[db][1] * inv); wy[db] = pk2(O[db][2] * inv, O[db][3] * inv); }
; #pragma unroll
;     for (int p = 0; p < 2; ++p) {
;         auto rx = __builtin_amdgcn_permlane16_swap(wx[2 * p], wx[2 * p + 1], false, false); wx[2 * p] = rx[0]; wx[2 * p + 1] = rx[1];
;         auto ry = __builtin_amdgcn_permlane16_swap(wy[2 * p], wy[2 * p + 1], false, false); wy[2 * p] = ry[0]; wy[2 * p + 1] = ry[1]; }
; #pragma unroll
;     for (int p = 0; p < 2; ++p) {
;         auto rx = __builtin_amdgcn_permlane32_swap(wx[p], wx[p + 2], false, false); wx[p] = rx[0]; wx[p + 2] = rx[1];
;         auto ry = __builtin_amdgcn_permlane32_swap(wy[p], wy[p + 2], false, false); wy[p] = ry[0]; wy[p + 2] = ry[1]; }
;     v4u lo = {wx[0], wy[0], wx[1], wy[1]}, hi = {wx[2], wy[2], wx[3], wy[3]};
;     *(v4u*)(yrow + 16 * g) = lo; *(v4u*)(yrow + 16 * g + 8) = hi;
; }
	ds_read_b64_tr_b16 v[202:203], v124 offset:30720
	ds_read_b64_tr_b16 v[204:205], v124 offset:32768
	ds_read_b64_tr_b16 v[206:207], v125 offset:30720
	ds_read_b64_tr_b16 v[208:209], v125 offset:32768
	ds_read_b64_tr_b16 v[228:229], v126 offset:30720
	ds_read_b64_tr_b16 v[230:231], v126 offset:32768
	ds_read_b64_tr_b16 v[232:233], v127 offset:30720
	ds_read_b64_tr_b16 v[234:235], v127 offset:32768
	v_fmamk_f32 v90, v131, 0xc2000000, v133
	v_fmamk_f32 v91, v131, 0xc2040000, v133
	v_fmamk_f32 v92, v131, 0xc2080000, v133
	v_fmamk_f32 v93, v131, 0xc20c0000, v133
	v_fmamk_f32 v94, v131, 0xc2400000, v133
	v_fmamk_f32 v95, v131, 0xc2440000, v133
	v_fmamk_f32 v96, v131, 0xc2480000, v133
	v_fmamk_f32 v97, v131, 0xc24c0000, v133
	s_waitcnt lgkmcnt(14)
	v_mfma_f32_16x16x32_bf16 v[210:213], v[186:189], v[236:239], v[210:213]
	s_waitcnt lgkmcnt(12)
	v_mfma_f32_16x16x32_bf16 v[214:217], v[190:193], v[236:239], v[214:217]
	s_waitcnt lgkmcnt(10)
	v_mfma_f32_16x16x32_bf16 v[220:223], v[194:197], v[236:239], v[220:223]
	s_waitcnt lgkmcnt(8)
	v_mfma_f32_16x16x32_bf16 v[224:227], v[198:201], v[236:239], v[224:227]
	v_cvt_pk_bf16_f32 v240, v106, v107
	v_cvt_pk_bf16_f32 v241, v108, v109
	v_cvt_pk_bf16_f32 v242, v110, v111
	v_cvt_pk_bf16_f32 v243, v112, v113
	s_waitcnt lgkmcnt(7)
	ds_read_b64_tr_b16 v[186:187], v124 offset:34816
	ds_read_b64_tr_b16 v[188:189], v124 offset:36864
	ds_read_b64_tr_b16 v[190:191], v125 offset:34816
	ds_read_b64_tr_b16 v[192:193], v125 offset:36864
	ds_read_b64_tr_b16 v[194:195], v126 offset:34816
	ds_read_b64_tr_b16 v[196:197], v126 offset:36864
	ds_read_b64_tr_b16 v[198:199], v127 offset:34816
	ds_read_b64_tr_b16 v[200:201], v127 offset:36864
	v_fmamk_f32 v98, v131, 0xc2800000, v133
	v_fmamk_f32 v99, v131, 0xc2820000, v133
	v_fmamk_f32 v100, v131, 0xc2840000, v133
	v_fmamk_f32 v101, v131, 0xc2860000, v133
	v_fmamk_f32 v102, v131, 0xc2a00000, v133
	v_fmamk_f32 v103, v131, 0xc2a20000, v133
	v_fmamk_f32 v104, v131, 0xc2a40000, v133
	v_fmamk_f32 v105, v131, 0xc2a60000, v133
	s_waitcnt lgkmcnt(14)
	v_mfma_f32_16x16x32_bf16 v[210:213], v[202:205], v[240:243], v[210:213]
	s_waitcnt lgkmcnt(12)
	v_mfma_f32_16x16x32_bf16 v[214:217], v[206:209], v[240:243], v[214:217]
	s_waitcnt lgkmcnt(10)
	v_mfma_f32_16x16x32_bf16 v[220:223], v[228:231], v[240:243], v[220:223]
	s_waitcnt lgkmcnt(8)
	v_mfma_f32_16x16x32_bf16 v[224:227], v[232:235], v[240:243], v[224:227]
	v_cvt_pk_bf16_f32 v236, v114, v115
	v_cvt_pk_bf16_f32 v237, v116, v117
	v_mov_b32_e32 v238, 0
	v_mov_b32_e32 v239, 0
	s_nop 1
	v_fmamk_f32 v106, v131, 0xc2c00000, v133
	v_fmamk_f32 v107, v131, 0xc2c20000, v133
	v_fmamk_f32 v108, v131, 0xc2c40000, v133
	v_fmamk_f32 v109, v131, 0xc2c60000, v133
	v_fmamk_f32 v110, v131, 0xc2e00000, v133
	v_fmamk_f32 v111, v131, 0xc2e20000, v133
	v_fmamk_f32 v112, v131, 0xc2e40000, v133
	v_fmamk_f32 v113, v131, 0xc2e60000, v133
	s_waitcnt lgkmcnt(6)
	v_mfma_f32_16x16x32_bf16 v[210:213], v[186:189], v[236:239], v[210:213]
	s_waitcnt lgkmcnt(4)
	v_mfma_f32_16x16x32_bf16 v[214:217], v[190:193], v[236:239], v[214:217]
	s_waitcnt lgkmcnt(2)
	v_mfma_f32_16x16x32_bf16 v[220:223], v[194:197], v[236:239], v[220:223]
	s_waitcnt lgkmcnt(0)
	v_mfma_f32_16x16x32_bf16 v[224:227], v[198:201], v[236:239], v[224:227]
	v_fmamk_f32 v114, v131, 0xc3000000, v133
	v_fmamk_f32 v115, v131, 0xc3010000, v133
	v_fmamk_f32 v116, v131, 0xc3020000, v133
	v_fmamk_f32 v117, v131, 0xc3030000, v133
	v_mov_b32_e32 v245, 0xff800000
	v_cndmask_b32_e64 v114, v245, v114, s[28:29]
	v_cndmask_b32_e64 v115, v245, v115, s[52:53]
	v_cndmask_b32_e64 v116, v245, v116, s[54:55]
	v_cndmask_b32_e64 v117, v245, v117, s[88:89]
	v_mov_b32_e32 v219, v185
	s_nop 1
	v_permlane16_swap_b32_e32 v185, v219
	v_add_f32_e32 v185, v185, v219
	v_mov_b32_e32 v219, v185
	s_nop 1
	v_permlane32_swap_b32_e32 v185, v219
	v_add_f32_e32 v185, v185, v219
	v_div_scale_f32 v236, s[78:79], v185, v185, 1.0
	v_div_scale_f32 v237, vcc, 1.0, v185, 1.0
	v_rcp_f32_e32 v238, v236
	s_nop 0
	v_fma_f32 v239, -v236, v238, 1.0
	v_fmac_f32_e32 v238, v239, v238
	v_mul_f32_e32 v240, v237, v238
	v_fma_f32 v241, -v236, v240, v237
	v_fmac_f32_e32 v240, v241, v238
	v_fma_f32 v237, -v236, v240, v237
	v_div_fmas_f32 v237, v237, v238, v240
	v_div_fixup_f32 v244, v237, v185, 1.0
	v_mul_f32_e32 v240, v210, v244
	v_mul_f32_e32 v241, v211, v244
	v_mul_f32_e32 v242, v212, v244
	v_mul_f32_e32 v243, v213, v244
	v_cvt_pk_bf16_f32 v186, v240, v241
	v_cvt_pk_bf16_f32 v187, v242, v243
	v_mul_f32_e32 v240, v214, v244
	v_mul_f32_e32 v241, v215, v244
	v_mul_f32_e32 v242, v216, v244
	v_mul_f32_e32 v243, v217, v244
	v_cvt_pk_bf16_f32 v188, v240, v241
	v_cvt_pk_bf16_f32 v189, v242, v243
	v_mul_f32_e32 v240, v220, v244
	v_mul_f32_e32 v241, v221, v244
	v_mul_f32_e32 v242, v222, v244
	v_mul_f32_e32 v243, v223, v244
	v_cvt_pk_bf16_f32 v190, v240, v241
	v_cvt_pk_bf16_f32 v191, v242, v243
	v_mul_f32_e32 v240, v224, v244
	v_mul_f32_e32 v241, v225, v244
	v_mul_f32_e32 v242, v226, v244
	v_mul_f32_e32 v243, v227, v244
	v_cvt_pk_bf16_f32 v192, v240, v241
	v_cvt_pk_bf16_f32 v193, v242, v243
	s_nop 1
	v_permlane16_swap_b32_e32 v186, v188
	v_permlane16_swap_b32_e32 v187, v189
	v_permlane16_swap_b32_e32 v190, v192
	v_permlane16_swap_b32_e32 v191, v193
	s_nop 0
	v_permlane32_swap_b32_e32 v186, v190
	v_permlane32_swap_b32_e32 v187, v191
	v_permlane32_swap_b32_e32 v188, v192
	v_permlane32_swap_b32_e32 v189, v193
	global_store_dwordx4 v128, v[186:189], s[82:83] offset:2048
	global_store_dwordx4 v128, v[190:193], s[82:83] offset:2064
	s_nop 1
	ds_read_b128 v[186:189], v122 offset:4096
	ds_read_b128 v[190:193], v123 offset:4096
	ds_read_b128 v[194:197], v122 offset:6144
	ds_read_b128 v[198:201], v123 offset:6144
	ds_read_b128 v[202:205], v122 offset:8192
	ds_read_b128 v[206:209], v123 offset:8192
	ds_read_b128 v[210:213], v122 offset:10240
	ds_read_b128 v[214:217], v123 offset:10240
	ds_read_b128 v[220:223], v122 offset:12288
	ds_read_b128 v[224:227], v123 offset:12288
	ds_read_b128 v[228:231], v122 offset:14336
	ds_read_b128 v[232:235], v123 offset:14336
	ds_read_b128 v[236:239], v122 offset:16384
	ds_read_b128 v[240:243], v123 offset:16384
	s_waitcnt lgkmcnt(13)
; #define LAS __attribute__((address_space(3)))
; #define MFMA16(a, b, c) __builtin_amdgcn_mfma_f32_16x16x32_bf16((a), (b), (c), 0, 0, 0)
; __device__ __forceinline__ void qk_at(const LAS unsigned char* kp0, const LAS unsigned char* kp1, int off, bf16x8 qf0, bf16x8 qf1, f32x4& S0, f32x4& S1) {
;     const bf16x8 k00 = *(const LAS bf16x8*)(kp0 + off), k01 = *(const LAS bf16x8*)(kp1 + off);
;     const bf16x8 k10 = *(const LAS bf16x8*)(kp0 + off + 2048), k11 = *(const LAS bf16x8*)(kp1 + off + 2048);
;     const f32x4 z = {0.f, 0.f, 0.f, 0.f};
;     S0 = MFMA16(k00, qf0, z); S0 = MFMA16(k01, qf1, S0);
;     S1 = MFMA16(k10, qf0, z); S1 = MFMA16(k11, qf1, S1);
; }
; __device__ __forceinline__ void softmax_step(f32x4& s0, f32x4& s1, float& m, float& l, f32x4 (&O)[4]) {
;     float t = fmaxf(fmaxf(fmaxf(s0[0], s0[1]), fmaxf(s0[2], s0[3])), fmaxf(fmaxf(s1[0], s1[1]), fmaxf(s1[2], s1[3])));
;     t = xrow16_max(t);
;     const float mn = fmaxf(m, t), alpha = __builtin_amdgcn_exp2f(m - mn);
;     m = mn;
	v_mfma_f32_16x16x32_bf16 v[50:53], v[186:189], v[162:165], v[50:53]
	s_waitcnt lgkmcnt(12)
	v_mfma_f32_16x16x32_bf16 v[50:53], v[190:193], v[166:169], v[50:53]
	ds_read_b128 v[186:189], v122 offset:18432
	ds_read_b128 v[190:193], v123 offset:18432
	s_waitcnt lgkmcnt(13)
	v_mfma_f32_16x16x32_bf16 v[54:57], v[194:197], v[162:165], v[54:57]
	s_waitcnt lgkmcnt(12)
	v_mfma_f32_16x16x32_bf16 v[54:57], v[198:201], v[166:169], v[54:57]
	ds_read_b128 v[194:197], v122 offset:20480
	ds_read_b128 v[198:201], v123 offset:20480
	s_waitcnt lgkmcnt(13)
	v_mfma_f32_16x16x32_bf16 v[58:61], v[202:205], v[162:165], v[58:61]
	s_waitcnt lgkmcnt(12)
	v_mfma_f32_16x16x32_bf16 v[58:61], v[206:209], v[166:169], v[58:61]
	ds_read_b128 v[202:205], v122 offset:22528
	ds_read_b128 v[206:209], v123 offset:22528
	s_waitcnt lgkmcnt(13)
	v_mfma_f32_16x16x32_bf16 v[62:65], v[210:213], v[162:165], v[62:65]
	s_waitcnt lgkmcnt(12)
	v_mfma_f32_16x16x32_bf16 v[62:65], v[214:217], v[166:169], v[62:65]
	ds_read_b128 v[210:213], v122 offset:24576
	ds_read_b128 v[214:217], v123 offset:24576
	s_waitcnt lgkmcnt(13)
	v_mfma_f32_16x16x32_bf16 v[66:69], v[220:223], v[162:165], v[66:69]
	s_waitcnt lgkmcnt(12)
	v_mfma_f32_16x16x32_bf16 v[66:69], v[224:227], v[166:169], v[66:69]
	ds_read_b128 v[220:223], v122 offset:26624
	ds_read_b128 v[224:227], v123 offset:26624
	s_waitcnt lgkmcnt(13)
	v_mfma_f32_16x16x32_bf16 v[70:73], v[228:231], v[162:165], v[70:73]
	s_waitcnt lgkmcnt(12)
	v_mfma_f32_16x16x32_bf16 v[70:73], v[232:235], v[166:169], v[70:73]
	ds_read_b128 v[228:231], v122 offset:28672
	ds_read_b128 v[232:235], v123 offset:28672
	s_waitcnt lgkmcnt(13)
	v_mfma_f32_16x16x32_bf16 v[74:77], v[236:239], v[162:165], v[74:77]
	s_waitcnt lgkmcnt(12)
	v_mfma_f32_16x16x32_bf16 v[74:77], v[240:243], v[166:169], v[74:77]
	ds_read_b128 v[236:239], v122 offset:30720
	ds_read_b128 v[240:243], v123 offset:30720
	s_waitcnt lgkmcnt(13)
	v_mfma_f32_16x16x32_bf16 v[78:81], v[186:189], v[162:165], v[78:81]
	s_waitcnt lgkmcnt(12)
	v_mfma_f32_16x16x32_bf16 v[78:81], v[190:193], v[166:169], v[78:81]
	ds_read_b128 v[186:189], v122 offset:32768
	ds_read_b128 v[190:193], v123 offset:32768
	s_waitcnt lgkmcnt(13)
	v_mfma_f32_16x16x32_bf16 v[82:85], v[194:197], v[162:165], v[82:85]
	s_waitcnt lgkmcnt(12)
	v_mfma_f32_16x16x32_bf16 v[82:85], v[198:201], v[166:169], v[82:85]
	ds_read_b128 v[194:197], v122 offset:34816
	ds_read_b128 v[198:201], v123 offset:34816
	s_waitcnt lgkmcnt(13)
	v_mfma_f32_16x16x32_bf16 v[86:89], v[202:205], v[162:165], v[86:89]
	s_waitcnt lgkmcnt(12)
	v_mfma_f32_16x16x32_bf16 v[86:89], v[206:209], v[166:169], v[86:89]
	ds_read_b128 v[202:205], v122 offset:36864
	ds_read_b128 v[206:209], v123 offset:36864
	s_waitcnt lgkmcnt(13)
	v_mfma_f32_16x16x32_bf16 v[90:93], v[210:213], v[162:165], v[90:93]
	s_waitcnt lgkmcnt(12)
	v_mfma_f32_16x16x32_bf16 v[90:93], v[214:217], v[166:169], v[90:93]
	s_waitcnt lgkmcnt(11)
	v_mfma_f32_16x16x32_bf16 v[94:97], v[220:223], v[162:165], v[94:97]
	s_waitcnt lgkmcnt(10)
	v_mfma_f32_16x16x32_bf16 v[94:97], v[224:227], v[166:169], v[94:97]
	s_waitcnt lgkmcnt(9)
	v_mfma_f32_16x16x32_bf16 v[98:101], v[228:231], v[162:165], v[98:101]
	s_waitcnt lgkmcnt(8)
	v_mfma_f32_16x16x32_bf16 v[98:101], v[232:235], v[166:169], v[98:101]
	s_waitcnt lgkmcnt(7)
	v_mfma_f32_16x16x32_bf16 v[102:105], v[236:239], v[162:165], v[102:105]
	s_waitcnt lgkmcnt(6)
	v_mfma_f32_16x16x32_bf16 v[102:105], v[240:243], v[166:169], v[102:105]
	s_waitcnt lgkmcnt(5)
	v_mfma_f32_16x16x32_bf16 v[106:109], v[186:189], v[162:165], v[106:109]
	s_waitcnt lgkmcnt(4)
	v_mfma_f32_16x16x32_bf16 v[106:109], v[190:193], v[166:169], v[106:109]
	s_waitcnt lgkmcnt(3)
	v_mfma_f32_16x16x32_bf16 v[110:113], v[194:197], v[162:165], v[110:113]
	s_waitcnt lgkmcnt(2)
	v_mfma_f32_16x16x32_bf16 v[110:113], v[198:201], v[166:169], v[110:113]
	s_waitcnt lgkmcnt(1)
	v_mfma_f32_16x16x32_bf16 v[114:117], v[202:205], v[162:165], v[114:117]
	s_waitcnt lgkmcnt(0)
	v_mfma_f32_16x16x32_bf16 v[114:117], v[206:209], v[166:169], v[114:117]
	v_max3_f32 v219, v50, v51, v52
	v_max3_f32 v244, v54, v55, v56
	v_max3_f32 v245, v58, v59, v60
	v_max3_f32 v120, v62, v63, v64
	v_max3_f32 v219, v219, v53, v66
	v_max3_f32 v244, v244, v57, v70
	v_max3_f32 v245, v245, v61, v74
	v_max3_f32 v120, v120, v65, v78
	v_max3_f32 v219, v219, v67, v68
	v_max3_f32 v244, v244, v71, v72
	v_max3_f32 v245, v245, v75, v76
	v_max3_f32 v120, v120, v79, v80
	ds_read_b64_tr_b16 v[186:187], v124 offset:4096
	ds_read_b64_tr_b16 v[188:189], v124 offset:6144
	ds_read_b64_tr_b16 v[190:191], v125 offset:4096
	ds_read_b64_tr_b16 v[192:193], v125 offset:6144
	ds_read_b64_tr_b16 v[194:195], v126 offset:4096
	ds_read_b64_tr_b16 v[196:197], v126 offset:6144
	ds_read_b64_tr_b16 v[198:199], v127 offset:4096
	ds_read_b64_tr_b16 v[200:201], v127 offset:6144
	v_max3_f32 v219, v219, v69, v82
	v_max3_f32 v244, v244, v73, v86
	v_max3_f32 v245, v245, v77, v90
	v_max3_f32 v120, v120, v81, v94
	v_max3_f32 v219, v219, v83, v84
	v_max3_f32 v244, v244, v87, v88
	v_max3_f32 v245, v245, v91, v92
	v_max3_f32 v120, v120, v95, v96
	v_max3_f32 v219, v219, v85, v98
	v_max3_f32 v244, v244, v89, v102
	v_max3_f32 v245, v245, v93, v106
	v_max3_f32 v120, v120, v97, v110
	v_max3_f32 v219, v219, v99, v100
	v_max3_f32 v244, v244, v103, v104
	v_max3_f32 v245, v245, v107, v108
	v_max3_f32 v120, v120, v111, v112
	v_max3_f32 v219, v219, v101, v114
	v_max3_f32 v219, v219, v115, v116
	v_max_f32_e32 v219, v219, v117
	v_max_f32_e32 v244, v244, v105
	v_max_f32_e32 v245, v245, v109
	v_max_f32_e32 v120, v120, v113
	v_max3_f32 v178, v219, v244, v245
	v_max_f32_e32 v178, v178, v120
	v_mov_b32_e32 v219, v178
	s_nop 1
	v_permlane16_swap_b32_e32 v178, v219
	v_max_f32_e32 v178, v178, v219
	v_mov_b32_e32 v219, v178
	s_nop 1
	v_permlane32_swap_b32_e32 v178, v219
	v_max3_f32 v178, v178, v219, v145
	s_waitcnt lgkmcnt(7)
; __device__ __forceinline__ void softmax_step(f32x4& s0, f32x4& s1, float& m, float& l, f32x4 (&O)[4]) {
;     float t = fmaxf(fmaxf(fmaxf(s0[0], s0[1]), fmaxf(s0[2], s0[3])), fmaxf(fmaxf(s1[0], s1[1]), fmaxf(s1[2], s1[3])));
;     t = xrow16_max(t);
;     const float mn = fmaxf(m, t), alpha = __builtin_amdgcn_exp2f(m - mn);
;     m = mn;
; #pragma unroll
;     for (int k = 0; k < 4; ++k) { s0[k] = __builtin_amdgcn_exp2f(s0[k] - mn); s1[k] = __builtin_amdgcn_exp2f(s1[k] - mn); }
;     l = l * alpha + ((s0[0] + s0[1]) + (s0[2] + s0[3])) + ((s1[0] + s1[1]) + (s1[2] + s1[3]));
; #pragma unroll
;     for (int db = 0; db < 4; ++db) O[db] *= alpha;
; }
	ds_read_b64_tr_b16 v[202:203], v124 offset:8192
	ds_read_b64_tr_b16 v[204:205], v124 offset:10240
	ds_read_b64_tr_b16 v[206:207], v125 offset:8192
	ds_read_b64_tr_b16 v[208:209], v125 offset:10240
	ds_read_b64_tr_b16 v[228:229], v126 offset:8192
	ds_read_b64_tr_b16 v[230:231], v126 offset:10240
	ds_read_b64_tr_b16 v[232:233], v127 offset:8192
	ds_read_b64_tr_b16 v[234:235], v127 offset:10240
	v_mov_b32_e32 v244, v178
	v_pk_add_f32 v[50:51], v[50:51], v[244:245] op_sel_hi:[1,0] neg_lo:[0,1] neg_hi:[0,1]
	v_pk_add_f32 v[52:53], v[52:53], v[244:245] op_sel_hi:[1,0] neg_lo:[0,1] neg_hi:[0,1]
	v_pk_add_f32 v[54:55], v[54:55], v[244:245] op_sel_hi:[1,0] neg_lo:[0,1] neg_hi:[0,1]
	v_pk_add_f32 v[56:57], v[56:57], v[244:245] op_sel_hi:[1,0] neg_lo:[0,1] neg_hi:[0,1]
	v_pk_add_f32 v[58:59], v[58:59], v[244:245] op_sel_hi:[1,0] neg_lo:[0,1] neg_hi:[0,1]
	v_pk_add_f32 v[60:61], v[60:61], v[244:245] op_sel_hi:[1,0] neg_lo:[0,1] neg_hi:[0,1]
	v_pk_add_f32 v[62:63], v[62:63], v[244:245] op_sel_hi:[1,0] neg_lo:[0,1] neg_hi:[0,1]
	v_pk_add_f32 v[64:65], v[64:65], v[244:245] op_sel_hi:[1,0] neg_lo:[0,1] neg_hi:[0,1]
	v_pk_add_f32 v[66:67], v[66:67], v[244:245] op_sel_hi:[1,0] neg_lo:[0,1] neg_hi:[0,1]
	v_pk_add_f32 v[68:69], v[68:69], v[244:245] op_sel_hi:[1,0] neg_lo:[0,1] neg_hi:[0,1]
	v_pk_add_f32 v[70:71], v[70:71], v[244:245] op_sel_hi:[1,0] neg_lo:[0,1] neg_hi:[0,1]
	v_pk_add_f32 v[72:73], v[72:73], v[244:245] op_sel_hi:[1,0] neg_lo:[0,1] neg_hi:[0,1]
	v_pk_add_f32 v[74:75], v[74:75], v[244:245] op_sel_hi:[1,0] neg_lo:[0,1] neg_hi:[0,1]
	v_pk_add_f32 v[76:77], v[76:77], v[244:245] op_sel_hi:[1,0] neg_lo:[0,1] neg_hi:[0,1]
	v_pk_add_f32 v[78:79], v[78:79], v[244:245] op_sel_hi:[1,0] neg_lo:[0,1] neg_hi:[0,1]
	v_pk_add_f32 v[80:81], v[80:81], v[244:245] op_sel_hi:[1,0] neg_lo:[0,1] neg_hi:[0,1]
	v_pk_add_f32 v[82:83], v[82:83], v[244:245] op_sel_hi:[1,0] neg_lo:[0,1] neg_hi:[0,1]
	v_pk_add_f32 v[84:85], v[84:85], v[244:245] op_sel_hi:[1,0] neg_lo:[0,1] neg_hi:[0,1]
	v_pk_add_f32 v[86:87], v[86:87], v[244:245] op_sel_hi:[1,0] neg_lo:[0,1] neg_hi:[0,1]
	v_pk_add_f32 v[88:89], v[88:89], v[244:245] op_sel_hi:[1,0] neg_lo:[0,1] neg_hi:[0,1]
	v_pk_add_f32 v[90:91], v[90:91], v[244:245] op_sel_hi:[1,0] neg_lo:[0,1] neg_hi:[0,1]
	v_pk_add_f32 v[92:93], v[92:93], v[244:245] op_sel_hi:[1,0] neg_lo:[0,1] neg_hi:[0,1]
	v_pk_add_f32 v[94:95], v[94:95], v[244:245] op_sel_hi:[1,0] neg_lo:[0,1] neg_hi:[0,1]
	v_pk_add_f32 v[96:97], v[96:97], v[244:245] op_sel_hi:[1,0] neg_lo:[0,1] neg_hi:[0,1]
	v_pk_add_f32 v[98:99], v[98:99], v[244:245] op_sel_hi:[1,0] neg_lo:[0,1] neg_hi:[0,1]
	v_pk_add_f32 v[100:101], v[100:101], v[244:245] op_sel_hi:[1,0] neg_lo:[0,1] neg_hi:[0,1]
	v_pk_add_f32 v[102:103], v[102:103], v[244:245] op_sel_hi:[1,0] neg_lo:[0,1] neg_hi:[0,1]
	v_pk_add_f32 v[104:105], v[104:105], v[244:245] op_sel_hi:[1,0] neg_lo:[0,1] neg_hi:[0,1]
	v_pk_add_f32 v[106:107], v[106:107], v[244:245] op_sel_hi:[1,0] neg_lo:[0,1] neg_hi:[0,1]
	v_pk_add_f32 v[108:109], v[108:109], v[244:245] op_sel_hi:[1,0] neg_lo:[0,1] neg_hi:[0,1]
	v_pk_add_f32 v[110:111], v[110:111], v[244:245] op_sel_hi:[1,0] neg_lo:[0,1] neg_hi:[0,1]
	v_pk_add_f32 v[112:113], v[112:113], v[244:245] op_sel_hi:[1,0] neg_lo:[0,1] neg_hi:[0,1]
	v_pk_add_f32 v[114:115], v[114:115], v[244:245] op_sel_hi:[1,0] neg_lo:[0,1] neg_hi:[0,1]
	v_pk_add_f32 v[116:117], v[116:117], v[244:245] op_sel_hi:[1,0] neg_lo:[0,1] neg_hi:[0,1]
	v_sub_f32_e32 v219, v145, v178
	v_exp_f32_e32 v50, v50
	v_exp_f32_e32 v51, v51
	v_exp_f32_e32 v52, v52
	v_exp_f32_e32 v53, v53
	v_exp_f32_e32 v54, v54
	v_exp_f32_e32 v55, v55
	v_exp_f32_e32 v56, v56
	v_exp_f32_e32 v57, v57
	v_exp_f32_e32 v58, v58
	v_exp_f32_e32 v59, v59
	v_exp_f32_e32 v60, v60
	v_exp_f32_e32 v61, v61
	v_exp_f32_e32 v62, v62
	v_exp_f32_e32 v63, v63
	v_exp_f32_e32 v64, v64
	v_exp_f32_e32 v65, v65
	v_exp_f32_e32 v66, v66
	v_exp_f32_e32 v67, v67
	v_exp_f32_e32 v68, v68
	v_exp_f32_e32 v69, v69
	v_exp_f32_e32 v70, v70
	v_exp_f32_e32 v71, v71
	v_exp_f32_e32 v72, v72
	v_exp_f32_e32 v73, v73
	v_exp_f32_e32 v74, v74
	v_exp_f32_e32 v75, v75
	v_exp_f32_e32 v76, v76
	v_exp_f32_e32 v77, v77
	v_exp_f32_e32 v78, v78
	v_exp_f32_e32 v79, v79
	v_exp_f32_e32 v80, v80
	v_exp_f32_e32 v81, v81
	v_exp_f32_e32 v82, v82
	v_exp_f32_e32 v83, v83
	v_exp_f32_e32 v84, v84
	v_exp_f32_e32 v85, v85
	v_exp_f32_e32 v86, v86
	v_exp_f32_e32 v87, v87
	v_exp_f32_e32 v88, v88
	v_exp_f32_e32 v89, v89
	v_exp_f32_e32 v90, v90
	v_exp_f32_e32 v91, v91
	v_exp_f32_e32 v92, v92
	v_exp_f32_e32 v93, v93
	v_exp_f32_e32 v94, v94
	v_exp_f32_e32 v95, v95
	v_exp_f32_e32 v96, v96
	v_exp_f32_e32 v97, v97
	v_exp_f32_e32 v98, v98
	v_exp_f32_e32 v99, v99
	v_exp_f32_e32 v100, v100
	v_exp_f32_e32 v101, v101
	v_exp_f32_e32 v102, v102
	v_exp_f32_e32 v103, v103
	v_exp_f32_e32 v104, v104
	v_exp_f32_e32 v105, v105
	v_exp_f32_e32 v106, v106
	v_exp_f32_e32 v107, v107
	v_exp_f32_e32 v108, v108
	v_exp_f32_e32 v109, v109
	v_exp_f32_e32 v110, v110
	v_exp_f32_e32 v111, v111
	v_exp_f32_e32 v112, v112
	v_exp_f32_e32 v113, v113
	v_exp_f32_e32 v114, v114
	v_exp_f32_e32 v115, v115
	v_exp_f32_e32 v116, v116
	v_exp_f32_e32 v117, v117
	v_exp_f32_e32 v219, v219
	v_pk_add_f32 v[236:237], v[50:51], v[52:53]
	v_pk_add_f32 v[238:239], v[54:55], v[56:57]
	v_pk_add_f32 v[240:241], v[58:59], v[60:61]
	v_pk_add_f32 v[242:243], v[62:63], v[64:65]
	v_pk_add_f32 v[236:237], v[236:237], v[66:67]
	v_pk_add_f32 v[238:239], v[238:239], v[70:71]
	v_pk_add_f32 v[240:241], v[240:241], v[74:75]
	v_pk_add_f32 v[242:243], v[242:243], v[78:79]
	v_pk_add_f32 v[236:237], v[236:237], v[68:69]
	v_pk_add_f32 v[238:239], v[238:239], v[72:73]
	v_pk_add_f32 v[240:241], v[240:241], v[76:77]
	v_pk_add_f32 v[242:243], v[242:243], v[80:81]
	v_pk_add_f32 v[236:237], v[236:237], v[82:83]
	v_pk_add_f32 v[238:239], v[238:239], v[86:87]
	v_pk_add_f32 v[240:241], v[240:241], v[90:91]
	v_pk_add_f32 v[242:243], v[242:243], v[94:95]
	v_pk_add_f32 v[236:237], v[236:237], v[84:85]
	v_pk_add_f32 v[238:239], v[238:239], v[88:89]
	v_pk_add_f32 v[240:241], v[240:241], v[92:93]
	v_pk_add_f32 v[242:243], v[242:243], v[96:97]
	v_pk_add_f32 v[236:237], v[236:237], v[98:99]
	v_pk_add_f32 v[238:239], v[238:239], v[102:103]
	v_pk_add_f32 v[240:241], v[240:241], v[106:107]
	v_pk_add_f32 v[242:243], v[242:243], v[110:111]
	v_pk_add_f32 v[236:237], v[236:237], v[100:101]
	v_pk_add_f32 v[238:239], v[238:239], v[104:105]
	v_pk_add_f32 v[240:241], v[240:241], v[108:109]
	v_pk_add_f32 v[242:243], v[242:243], v[112:113]
	v_pk_add_f32 v[236:237], v[236:237], v[114:115]
	v_pk_add_f32 v[236:237], v[236:237], v[116:117]
	v_pk_add_f32 v[236:237], v[236:237], v[238:239]
	v_pk_add_f32 v[240:241], v[240:241], v[242:243]
	v_cndmask_b32_e64 v219, 0, v219, s[74:75]
	v_pk_add_f32 v[236:237], v[236:237], v[240:241]
	v_add_f32_e32 v185, v236, v237
	v_add_f32_e32 v185, v185, v219
	v_cvt_pk_bf16_f32 v236, v50, v51
	v_cvt_pk_bf16_f32 v237, v52, v53
	v_cvt_pk_bf16_f32 v238, v54, v55
	v_cvt_pk_bf16_f32 v239, v56, v57
	s_nop 1
	s_waitcnt lgkmcnt(14)
; #define LAS __attribute__((address_space(3)))
; __device__ __forceinline__ unsigned pk2(float lo, float hi) { return pg8::cvt_pk_bf16(lo, hi); }
; __device__ __forceinline__ s16x4 vtr(const LAS unsigned char* p) { return __builtin_bit_cast(s16x4, __builtin_amdgcn_ds_read_tr16_b64_v4i16((LAS s16x4*)p)); }
; #define MFMA16(a, b, c) __builtin_amdgcn_mfma_f32_16x16x32_bf16((a), (b), (c), 0, 0, 0)
; __device__ __forceinline__ void pv_at(const LAS unsigned char* const (&vp)[4], int off, const f32x4& P0, const f32x4& P1, f32x4 (&O)[4]) {
;     v4u pw; pw.x = pk2(P0[0], P0[1]); pw.y = pk2(P0[2], P0[3]); pw.z = pk2(P1[0], P1[1]); pw.w = pk2(P1[2], P1[3]);
;     const bf16x8 pb = __builtin_bit_cast(bf16x8, pw);
; #pragma unroll
;     for (int db = 0; db < 4; ++db) {
;         const s16x4 lo = vtr(vp[db] + off), hi = vtr(vp[db] + off + 2048);
;         const bf16x8 vt = (bf16x8){lo[0], lo[1], lo[2], lo[3], hi[0], hi[1], hi[2], hi[3]};
;         O[db] = MFMA16(vt, pb, O[db]);
;     }
; }
; template <bool MASK> __device__ __forceinline__ void a_scores(f32x4& S0, f32x4& S1, float basef, float c1, float slope2, int krow0, int kstart) {
; #pragma unroll
;     for (int r = 0; r < 4; ++r) {
;         const float d0 = fabsf(basef - (float)r), d1 = fabsf(basef - (float)(16 + r));
;         const float v0 = S0[r] - slope2 * d0, v1 = S1[r] - slope2 * d1;
;         if (MASK) { const int p0 = kstart + krow0 + r, p1 = p0 + 16;
;             S0[r] = (d0 <= 128.f && p0 >= 0 && p0 < SEQ) ? v0 : -INFINITY; S1[r] = (d1 <= 128.f && p1 >= 0 && p1 < SEQ) ? v1 : -INFINITY; }
;         else { S0[r] = v0; S1[r] = v1; }
;     }
; }
	v_mfma_f32_16x16x32_bf16 v[210:213], v[186:189], v[236:239], 0
	s_waitcnt lgkmcnt(12)
	v_mfma_f32_16x16x32_bf16 v[214:217], v[190:193], v[236:239], 0
	s_waitcnt lgkmcnt(10)
	v_mfma_f32_16x16x32_bf16 v[220:223], v[194:197], v[236:239], 0
	s_waitcnt lgkmcnt(8)
	v_mfma_f32_16x16x32_bf16 v[224:227], v[198:201], v[236:239], 0
	v_cvt_pk_bf16_f32 v240, v58, v59
	v_cvt_pk_bf16_f32 v241, v60, v61
	v_cvt_pk_bf16_f32 v242, v62, v63
	v_cvt_pk_bf16_f32 v243, v64, v65
	s_waitcnt lgkmcnt(7)
	ds_read_b64_tr_b16 v[186:187], v124 offset:12288
	ds_read_b64_tr_b16 v[188:189], v124 offset:14336
	ds_read_b64_tr_b16 v[190:191], v125 offset:12288
	ds_read_b64_tr_b16 v[192:193], v125 offset:14336
	ds_read_b64_tr_b16 v[194:195], v126 offset:12288
	ds_read_b64_tr_b16 v[196:197], v126 offset:14336
	ds_read_b64_tr_b16 v[198:199], v127 offset:12288
	ds_read_b64_tr_b16 v[200:201], v127 offset:14336
	v_fmamk_f32 v50, v130, 0x43000000, v132
	v_fmamk_f32 v51, v130, 0x42fe0000, v132
	v_fmamk_f32 v52, v130, 0x42fc0000, v132
	v_fmamk_f32 v53, v130, 0x42fa0000, v132
	v_mov_b32_e32 v245, 0xff800000
	v_cndmask_b32_e64 v50, v245, v50, s[16:17]
	v_cndmask_b32_e64 v51, v245, v51, s[18:19]
	v_cndmask_b32_e64 v52, v245, v52, s[22:23]
	v_cndmask_b32_e64 v53, v245, v53, s[24:25]
	v_fmamk_f32 v54, v130, 0x42e00000, v132
	v_fmamk_f32 v55, v130, 0x42de0000, v132
	v_fmamk_f32 v56, v130, 0x42dc0000, v132
	v_fmamk_f32 v57, v130, 0x42da0000, v132
	s_waitcnt lgkmcnt(14)
	v_mfma_f32_16x16x32_bf16 v[210:213], v[202:205], v[240:243], v[210:213]
	s_waitcnt lgkmcnt(12)
	v_mfma_f32_16x16x32_bf16 v[214:217], v[206:209], v[240:243], v[214:217]
	s_waitcnt lgkmcnt(10)
	v_mfma_f32_16x16x32_bf16 v[220:223], v[228:231], v[240:243], v[220:223]
	s_waitcnt lgkmcnt(8)
	v_mfma_f32_16x16x32_bf16 v[224:227], v[232:235], v[240:243], v[224:227]
	v_cvt_pk_bf16_f32 v236, v66, v67
	v_cvt_pk_bf16_f32 v237, v68, v69
	v_cvt_pk_bf16_f32 v238, v70, v71
	v_cvt_pk_bf16_f32 v239, v72, v73
	s_waitcnt lgkmcnt(7)
	ds_read_b64_tr_b16 v[202:203], v124 offset:16384
	ds_read_b64_tr_b16 v[204:205], v124 offset:18432
	ds_read_b64_tr_b16 v[206:207], v125 offset:16384
	ds_read_b64_tr_b16 v[208:209], v125 offset:18432
	ds_read_b64_tr_b16 v[228:229], v126 offset:16384
	ds_read_b64_tr_b16 v[230:231], v126 offset:18432
	ds_read_b64_tr_b16 v[232:233], v127 offset:16384
	ds_read_b64_tr_b16 v[234:235], v127 offset:18432
	v_fmamk_f32 v58, v130, 0x42c00000, v132
	v_fmamk_f32 v59, v130, 0x42be0000, v132
	v_fmamk_f32 v60, v130, 0x42bc0000, v132
	v_fmamk_f32 v61, v130, 0x42ba0000, v132
	v_fmamk_f32 v62, v130, 0x42a00000, v132
	v_fmamk_f32 v63, v130, 0x429e0000, v132
	v_fmamk_f32 v64, v130, 0x429c0000, v132
	v_fmamk_f32 v65, v130, 0x429a0000, v132
	s_waitcnt lgkmcnt(14)
	v_mfma_f32_16x16x32_bf16 v[210:213], v[186:189], v[236:239], v[210:213]
	s_waitcnt lgkmcnt(12)
	v_mfma_f32_16x16x32_bf16 v[214:217], v[190:193], v[236:239], v[214:217]
	s_waitcnt lgkmcnt(10)
	v_mfma_f32_16x16x32_bf16 v[220:223], v[194:197], v[236:239], v[220:223]
	s_waitcnt lgkmcnt(8)
	v_mfma_f32_16x16x32_bf16 v[224:227], v[198:201], v[236:239], v[224:227]
	v_cvt_pk_bf16_f32 v240, v74, v75
	v_cvt_pk_bf16_f32 v241, v76, v77
	v_cvt_pk_bf16_f32 v242, v78, v79
	v_cvt_pk_bf16_f32 v243, v80, v81
	s_waitcnt lgkmcnt(7)
	ds_read_b64_tr_b16 v[186:187], v124 offset:20480
	ds_read_b64_tr_b16 v[188:189], v124 offset:22528
	ds_read_b64_tr_b16 v[190:191], v125 offset:20480
	ds_read_b64_tr_b16 v[192:193], v125 offset:22528
	ds_read_b64_tr_b16 v[194:195], v126 offset:20480
	ds_read_b64_tr_b16 v[196:197], v126 offset:22528
	ds_read_b64_tr_b16 v[198:199], v127 offset:20480
	ds_read_b64_tr_b16 v[200:201], v127 offset:22528
	v_fmamk_f32 v66, v130, 0x42800000, v132
	v_fmamk_f32 v67, v130, 0x427c0000, v132
	v_fmamk_f32 v68, v130, 0x42780000, v132
	v_fmamk_f32 v69, v130, 0x42740000, v132
	v_fmamk_f32 v70, v130, 0x42400000, v132
	v_fmamk_f32 v71, v130, 0x423c0000, v132
	v_fmamk_f32 v72, v130, 0x42380000, v132
	v_fmamk_f32 v73, v130, 0x42340000, v132
	s_waitcnt lgkmcnt(14)
	v_mfma_f32_16x16x32_bf16 v[210:213], v[202:205], v[240:243], v[210:213]
	s_waitcnt lgkmcnt(12)
	v_mfma_f32_16x16x32_bf16 v[214:217], v[206:209], v[240:243], v[214:217]
	s_waitcnt lgkmcnt(10)
	v_mfma_f32_16x16x32_bf16 v[220:223], v[228:231], v[240:243], v[220:223]
	s_waitcnt lgkmcnt(8)
	v_mfma_f32_16x16x32_bf16 v[224:227], v[232:235], v[240:243], v[224:227]
	v_cvt_pk_bf16_f32 v236, v82, v83
	v_cvt_pk_bf16_f32 v237, v84, v85
	v_cvt_pk_bf16_f32 v238, v86, v87
	v_cvt_pk_bf16_f32 v239, v88, v89
	s_waitcnt lgkmcnt(7)
	ds_read_b64_tr_b16 v[202:203], v124 offset:24576
	ds_read_b64_tr_b16 v[204:205], v124 offset:26624
	ds_read_b64_tr_b16 v[206:207], v125 offset:24576
	ds_read_b64_tr_b16 v[208:209], v125 offset:26624
	ds_read_b64_tr_b16 v[228:229], v126 offset:24576
	ds_read_b64_tr_b16 v[230:231], v126 offset:26624
	ds_read_b64_tr_b16 v[232:233], v127 offset:24576
	ds_read_b64_tr_b16 v[234:235], v127 offset:26624
	v_fmamk_f32 v74, v130, 0x42000000, v132
	v_fmamk_f32 v75, v130, 0x41f80000, v132
	v_fmamk_f32 v76, v130, 0x41f00000, v132
	v_fmamk_f32 v77, v130, 0x41e80000, v132
	v_fmamk_f32 v78, v130, 0x41800000, v132
	v_fmamk_f32 v79, v130, 0x41700000, v132
	v_fmamk_f32 v80, v130, 0x41600000, v132
	v_fmamk_f32 v81, v130, 0x41500000, v132
	s_waitcnt lgkmcnt(14)
	v_mfma_f32_16x16x32_bf16 v[210:213], v[186:189], v[236:239], v[210:213]
	s_waitcnt lgkmcnt(12)
	v_mfma_f32_16x16x32_bf16 v[214:217], v[190:193], v[236:239], v[214:217]
	s_waitcnt lgkmcnt(10)
	v_mfma_f32_16x16x32_bf16 v[220:223], v[194:197], v[236:239], v[220:223]
	s_waitcnt lgkmcnt(8)
; #define LAS __attribute__((address_space(3)))
; __device__ __forceinline__ unsigned pk2(float lo, float hi) { return pg8::cvt_pk_bf16(lo, hi); }
; __device__ __forceinline__ s16x4 vtr(const LAS unsigned char* p) { return __builtin_bit_cast(s16x4, __builtin_amdgcn_ds_read_tr16_b64_v4i16((LAS s16x4*)p)); }
; #define MFMA16(a, b, c) __builtin_amdgcn_mfma_f32_16x16x32_bf16((a), (b), (c), 0, 0, 0)
; __device__ __forceinline__ void pv_at(const LAS unsigned char* const (&vp)[4], int off, const f32x4& P0, const f32x4& P1, f32x4 (&O)[4]) {
;     v4u pw; pw.x = pk2(P0[0], P0[1]); pw.y = pk2(P0[2], P0[3]); pw.z = pk2(P1[0], P1[1]); pw.w = pk2(P1[2], P1[3]);
;     const bf16x8 pb = __builtin_bit_cast(bf16x8, pw);
; #pragma unroll
;     for (int db = 0; db < 4; ++db) {
;         const s16x4 lo = vtr(vp[db] + off), hi = vtr(vp[db] + off + 2048);
;         const bf16x8 vt = (bf16x8){lo[0], lo[1], lo[2], lo[3], hi[0], hi[1], hi[2], hi[3]};
;         O[db] = MFMA16(vt, pb, O[db]);
;     }
; }
; template <bool MASK> __device__ __forceinline__ void a_scores(f32x4& S0, f32x4& S1, float basef, float c1, float slope2, int krow0, int kstart) {
; #pragma unroll
;     for (int r = 0; r < 4; ++r) {
;         const float d0 = fabsf(basef - (float)r), d1 = fabsf(basef - (float)(16 + r));
;         const float v0 = S0[r] - slope2 * d0, v1 = S1[r] - slope2 * d1;
;         if (MASK) { const int p0 = kstart + krow0 + r, p1 = p0 + 16;
;             S0[r] = (d0 <= 128.f && p0 >= 0 && p0 < SEQ) ? v0 : -INFINITY; S1[r] = (d1 <= 128.f && p1 >= 0 && p1 < SEQ) ? v1 : -INFINITY; }
;         else { S0[r] = v0; S1[r] = v1; }
;     }
; }
	v_mfma_f32_16x16x32_bf16 v[224:227], v[198:201], v[236:239], v[224:227]
	v_cvt_pk_bf16_f32 v240, v90, v91
	v_cvt_pk_bf16_f32 v241, v92, v93
	v_cvt_pk_bf16_f32 v242, v94, v95
	v_cvt_pk_bf16_f32 v243, v96, v97
	s_waitcnt lgkmcnt(7)
	ds_read_b64_tr_b16 v[186:187], v124 offset:28672
	ds_read_b64_tr_b16 v[188:189], v124 offset:30720
	ds_read_b64_tr_b16 v[190:191], v125 offset:28672
	ds_read_b64_tr_b16 v[192:193], v125 offset:30720
	ds_read_b64_tr_b16 v[194:195], v126 offset:28672
	ds_read_b64_tr_b16 v[196:197], v126 offset:30720
	ds_read_b64_tr_b16 v[198:199], v127 offset:28672
	ds_read_b64_tr_b16 v[200:201], v127 offset:30720
	v_add_f32_e32 v219, 0, v129
	v_mul_f32_e64 v82, v130, |v219|
	v_add_f32_e32 v245, 0xbf800000, v129
	v_mul_f32_e64 v83, v130, |v245|
	v_add_f32_e32 v219, 0xc0000000, v129
	v_mul_f32_e64 v84, v130, |v219|
	v_add_f32_e32 v245, 0xc0400000, v129
	v_mul_f32_e64 v85, v130, |v245|
	v_fmamk_f32 v86, v131, 0xc1800000, v133
	v_fmamk_f32 v87, v131, 0xc1880000, v133
	v_fmamk_f32 v88, v131, 0xc1900000, v133
	v_fmamk_f32 v89, v131, 0xc1980000, v133
	s_waitcnt lgkmcnt(14)
	v_mfma_f32_16x16x32_bf16 v[210:213], v[202:205], v[240:243], v[210:213]
	s_waitcnt lgkmcnt(12)
	v_mfma_f32_16x16x32_bf16 v[214:217], v[206:209], v[240:243], v[214:217]
	s_waitcnt lgkmcnt(10)
	v_mfma_f32_16x16x32_bf16 v[220:223], v[228:231], v[240:243], v[220:223]
	s_waitcnt lgkmcnt(8)
	v_mfma_f32_16x16x32_bf16 v[224:227], v[232:235], v[240:243], v[224:227]
	v_cvt_pk_bf16_f32 v236, v98, v99
	v_cvt_pk_bf16_f32 v237, v100, v101
	v_cvt_pk_bf16_f32 v238, v102, v103
	v_cvt_pk_bf16_f32 v239, v104, v105
	s_waitcnt lgkmcnt(7)
	ds_read_b64_tr_b16 v[202:203], v124 offset:32768
	ds_read_b64_tr_b16 v[204:205], v124 offset:34816
	ds_read_b64_tr_b16 v[206:207], v125 offset:32768
	ds_read_b64_tr_b16 v[208:209], v125 offset:34816
	ds_read_b64_tr_b16 v[228:229], v126 offset:32768
	ds_read_b64_tr_b16 v[230:231], v126 offset:34816
	ds_read_b64_tr_b16 v[232:233], v127 offset:32768
	ds_read_b64_tr_b16 v[234:235], v127 offset:34816
	v_fmamk_f32 v90, v131, 0xc2000000, v133
	v_fmamk_f32 v91, v131, 0xc2040000, v133
	v_fmamk_f32 v92, v131, 0xc2080000, v133
	v_fmamk_f32 v93, v131, 0xc20c0000, v133
	v_fmamk_f32 v94, v131, 0xc2400000, v133
	v_fmamk_f32 v95, v131, 0xc2440000, v133
	v_fmamk_f32 v96, v131, 0xc2480000, v133
	v_fmamk_f32 v97, v131, 0xc24c0000, v133
	s_waitcnt lgkmcnt(14)
	v_mfma_f32_16x16x32_bf16 v[210:213], v[186:189], v[236:239], v[210:213]
	s_waitcnt lgkmcnt(12)
	v_mfma_f32_16x16x32_bf16 v[214:217], v[190:193], v[236:239], v[214:217]
	s_waitcnt lgkmcnt(10)
	v_mfma_f32_16x16x32_bf16 v[220:223], v[194:197], v[236:239], v[220:223]
	s_waitcnt lgkmcnt(8)
	v_mfma_f32_16x16x32_bf16 v[224:227], v[198:201], v[236:239], v[224:227]
	v_cvt_pk_bf16_f32 v240, v106, v107
	v_cvt_pk_bf16_f32 v241, v108, v109
	v_cvt_pk_bf16_f32 v242, v110, v111
	v_cvt_pk_bf16_f32 v243, v112, v113
	s_waitcnt lgkmcnt(7)
	ds_read_b64_tr_b16 v[186:187], v124 offset:36864
	ds_read_b64_tr_b16 v[188:189], v124 offset:38912
	ds_read_b64_tr_b16 v[190:191], v125 offset:36864
	ds_read_b64_tr_b16 v[192:193], v125 offset:38912
	ds_read_b64_tr_b16 v[194:195], v126 offset:36864
	ds_read_b64_tr_b16 v[196:197], v126 offset:38912
	ds_read_b64_tr_b16 v[198:199], v127 offset:36864
	ds_read_b64_tr_b16 v[200:201], v127 offset:38912
	v_fmamk_f32 v98, v131, 0xc2800000, v133
	v_fmamk_f32 v99, v131, 0xc2820000, v133
	v_fmamk_f32 v100, v131, 0xc2840000, v133
	v_fmamk_f32 v101, v131, 0xc2860000, v133
	v_fmamk_f32 v102, v131, 0xc2a00000, v133
	v_fmamk_f32 v103, v131, 0xc2a20000, v133
	v_fmamk_f32 v104, v131, 0xc2a40000, v133
	v_fmamk_f32 v105, v131, 0xc2a60000, v133
	s_waitcnt lgkmcnt(14)
	v_mfma_f32_16x16x32_bf16 v[210:213], v[202:205], v[240:243], v[210:213]
	s_waitcnt lgkmcnt(12)
	v_mfma_f32_16x16x32_bf16 v[214:217], v[206:209], v[240:243], v[214:217]
	s_waitcnt lgkmcnt(10)
	v_mfma_f32_16x16x32_bf16 v[220:223], v[228:231], v[240:243], v[220:223]
	s_waitcnt lgkmcnt(8)
	v_mfma_f32_16x16x32_bf16 v[224:227], v[232:235], v[240:243], v[224:227]
	v_cvt_pk_bf16_f32 v236, v114, v115
	v_cvt_pk_bf16_f32 v237, v116, v117
	v_mov_b32_e32 v238, 0
	v_mov_b32_e32 v239, 0
	s_nop 1
	v_fmamk_f32 v106, v131, 0xc2c00000, v133
	v_fmamk_f32 v107, v131, 0xc2c20000, v133
	v_fmamk_f32 v108, v131, 0xc2c40000, v133
	v_fmamk_f32 v109, v131, 0xc2c60000, v133
	v_fmamk_f32 v110, v131, 0xc2e00000, v133
	v_fmamk_f32 v111, v131, 0xc2e20000, v133
	v_fmamk_f32 v112, v131, 0xc2e40000, v133
	v_fmamk_f32 v113, v131, 0xc2e60000, v133
	s_waitcnt lgkmcnt(6)
	v_mfma_f32_16x16x32_bf16 v[210:213], v[186:189], v[236:239], v[210:213]
	s_waitcnt lgkmcnt(4)
	v_mfma_f32_16x16x32_bf16 v[214:217], v[190:193], v[236:239], v[214:217]
	s_waitcnt lgkmcnt(2)
	v_mfma_f32_16x16x32_bf16 v[220:223], v[194:197], v[236:239], v[220:223]
	s_waitcnt lgkmcnt(0)
; #define LAS __attribute__((address_space(3)))
; __device__ __forceinline__ unsigned pk2(float lo, float hi) { return pg8::cvt_pk_bf16(lo, hi); }
; __device__ __forceinline__ void qk_at(const LAS unsigned char* kp0, const LAS unsigned char* kp1, int off, bf16x8 qf0, bf16x8 qf1, f32x4& S0, f32x4& S1) {
;     const bf16x8 k00 = *(const LAS bf16x8*)(kp0 + off), k01 = *(const LAS bf16x8*)(kp1 + off);
;     const bf16x8 k10 = *(const LAS bf16x8*)(kp0 + off + 2048), k11 = *(const LAS bf16x8*)(kp1 + off + 2048);
;     const f32x4 z = {0.f, 0.f, 0.f, 0.f};
;     S0 = MFMA16(k00, qf0, z); S0 = MFMA16(k01, qf1, S0);
;     S1 = MFMA16(k10, qf0, z); S1 = MFMA16(k11, qf1, S1);
; }
; __device__ __forceinline__ void pv_at(const LAS unsigned char* const (&vp)[4], int off, const f32x4& P0, const f32x4& P1, f32x4 (&O)[4]) {
;     v4u pw; pw.x = pk2(P0[0], P0[1]); pw.y = pk2(P0[2], P0[3]); pw.z = pk2(P1[0], P1[1]); pw.w = pk2(P1[2], P1[3]);
;     const bf16x8 pb = __builtin_bit_cast(bf16x8, pw);
; #pragma unroll
;     for (int db = 0; db < 4; ++db) {
;         const s16x4 lo = vtr(vp[db] + off), hi = vtr(vp[db] + off + 2048);
;         const bf16x8 vt = (bf16x8){lo[0], lo[1], lo[2], lo[3], hi[0], hi[1], hi[2], hi[3]};
;         O[db] = MFMA16(vt, pb, O[db]);
;     }
; }
; __device__ __forceinline__ void store_o(bf16* yrow, int g, float l, const f32x4 (&O)[4]) {
;     const float inv = 1.0f / xrow16_sum(l);
;     unsigned wx[4], wy[4];
; #pragma unroll
;     for (int db = 0; db < 4; ++db) { wx[db] = pk2(O[db][0] * inv, O[db][1] * inv); wy[db] = pk2(O[db][2] * inv, O[db][3] * inv); }
; #pragma unroll
;     for (int p = 0; p < 2; ++p) {
;         auto rx = __builtin_amdgcn_permlane16_swap(wx[2 * p], wx[2 * p + 1], false, false); wx[2 * p] = rx[0]; wx[2 * p + 1] = rx[1];
;         auto ry = __builtin_amdgcn_permlane16_swap(wy[2 * p], wy[2 * p + 1], false, false); wy[2 * p] = ry[0]; wy[2 * p + 1] = ry[1]; }
; #pragma unroll
;     for (int p = 0; p < 2; ++p) {
;         auto rx = __builtin_amdgcn_permlane32_swap(wx[p], wx[p + 2], false, false); wx[p] = rx[0]; wx[p + 2] = rx[1];
;         auto ry = __builtin_amdgcn_permlane32_swap(wy[p], wy[p + 2], false, false); wy[p] = ry[0]; wy[p + 2] = ry[1]; }
;     v4u lo = {wx[0], wy[0], wx[1], wy[1]}, hi = {wx[2], wy[2], wx[3], wy[3]};
;     *(v4u*)(yrow + 16 * g) = lo; *(v4u*)(yrow + 16 * g + 8) = hi;
; }
	v_mfma_f32_16x16x32_bf16 v[224:227], v[198:201], v[236:239], v[224:227]
	v_fmamk_f32 v114, v131, 0xc3000000, v133
	v_fmamk_f32 v115, v131, 0xc3010000, v133
	v_fmamk_f32 v116, v131, 0xc3020000, v133
	v_fmamk_f32 v117, v131, 0xc3030000, v133
	v_mov_b32_e32 v245, 0xff800000
	v_cndmask_b32_e64 v114, v245, v114, s[28:29]
	v_cndmask_b32_e64 v115, v245, v115, s[52:53]
	v_cndmask_b32_e64 v116, v245, v116, s[54:55]
	v_cndmask_b32_e64 v117, v245, v117, s[88:89]
	v_mov_b32_e32 v219, v185
	s_nop 1
	v_permlane16_swap_b32_e32 v185, v219
	v_add_f32_e32 v185, v185, v219
	v_mov_b32_e32 v219, v185
	s_nop 1
	v_permlane32_swap_b32_e32 v185, v219
	v_add_f32_e32 v185, v185, v219
	v_div_scale_f32 v236, s[78:79], v185, v185, 1.0
	v_div_scale_f32 v237, vcc, 1.0, v185, 1.0
	v_rcp_f32_e32 v238, v236
	s_nop 0
	v_fma_f32 v239, -v236, v238, 1.0
	v_fmac_f32_e32 v238, v239, v238
	v_mul_f32_e32 v240, v237, v238
	v_fma_f32 v241, -v236, v240, v237
	v_fmac_f32_e32 v240, v241, v238
	v_fma_f32 v237, -v236, v240, v237
	v_div_fmas_f32 v237, v237, v238, v240
	v_div_fixup_f32 v244, v237, v185, 1.0
	v_mul_f32_e32 v240, v210, v244
	v_mul_f32_e32 v241, v211, v244
	v_mul_f32_e32 v242, v212, v244
	v_mul_f32_e32 v243, v213, v244
	v_cvt_pk_bf16_f32 v186, v240, v241
	v_cvt_pk_bf16_f32 v187, v242, v243
	v_mul_f32_e32 v240, v214, v244
	v_mul_f32_e32 v241, v215, v244
	v_mul_f32_e32 v242, v216, v244
	v_mul_f32_e32 v243, v217, v244
	v_cvt_pk_bf16_f32 v188, v240, v241
	v_cvt_pk_bf16_f32 v189, v242, v243
	v_mul_f32_e32 v240, v220, v244
	v_mul_f32_e32 v241, v221, v244
	v_mul_f32_e32 v242, v222, v244
	v_mul_f32_e32 v243, v223, v244
	v_cvt_pk_bf16_f32 v190, v240, v241
	v_cvt_pk_bf16_f32 v191, v242, v243
	v_mul_f32_e32 v240, v224, v244
	v_mul_f32_e32 v241, v225, v244
	v_mul_f32_e32 v242, v226, v244
	v_mul_f32_e32 v243, v227, v244
	v_cvt_pk_bf16_f32 v192, v240, v241
	v_cvt_pk_bf16_f32 v193, v242, v243
	s_nop 1
	v_permlane16_swap_b32_e32 v186, v188
	v_permlane16_swap_b32_e32 v187, v189
	v_permlane16_swap_b32_e32 v190, v192
	v_permlane16_swap_b32_e32 v191, v193
	s_nop 0
	v_permlane32_swap_b32_e32 v186, v190
	v_permlane32_swap_b32_e32 v187, v191
	v_permlane32_swap_b32_e32 v188, v192
	v_permlane32_swap_b32_e32 v189, v193
	v_add_u32_e32 v219, 0x1000, v128
	global_store_dwordx4 v219, v[186:189], s[82:83] offset:0
	global_store_dwordx4 v219, v[190:193], s[82:83] offset:16
	s_nop 1
	ds_read_b128 v[186:189], v122 offset:6144
	ds_read_b128 v[190:193], v123 offset:6144
	ds_read_b128 v[194:197], v122 offset:8192
	ds_read_b128 v[198:201], v123 offset:8192
	ds_read_b128 v[202:205], v122 offset:10240
	ds_read_b128 v[206:209], v123 offset:10240
	ds_read_b128 v[210:213], v122 offset:12288
	ds_read_b128 v[214:217], v123 offset:12288
	ds_read_b128 v[220:223], v122 offset:14336
	ds_read_b128 v[224:227], v123 offset:14336
	ds_read_b128 v[228:231], v122 offset:16384
	ds_read_b128 v[232:235], v123 offset:16384
	ds_read_b128 v[236:239], v122 offset:18432
	ds_read_b128 v[240:243], v123 offset:18432
	s_waitcnt lgkmcnt(13)
	v_mfma_f32_16x16x32_bf16 v[50:53], v[186:189], v[170:173], v[50:53]
	s_waitcnt lgkmcnt(12)
	v_mfma_f32_16x16x32_bf16 v[50:53], v[190:193], v[174:177], v[50:53]
	ds_read_b128 v[186:189], v122 offset:20480
	ds_read_b128 v[190:193], v123 offset:20480
	s_waitcnt lgkmcnt(13)
	v_mfma_f32_16x16x32_bf16 v[54:57], v[194:197], v[170:173], v[54:57]
	s_waitcnt lgkmcnt(12)
	v_mfma_f32_16x16x32_bf16 v[54:57], v[198:201], v[174:177], v[54:57]
	ds_read_b128 v[194:197], v122 offset:22528
	ds_read_b128 v[198:201], v123 offset:22528
	s_waitcnt lgkmcnt(13)
	v_mfma_f32_16x16x32_bf16 v[58:61], v[202:205], v[170:173], v[58:61]
	s_waitcnt lgkmcnt(12)
	v_mfma_f32_16x16x32_bf16 v[58:61], v[206:209], v[174:177], v[58:61]
	ds_read_b128 v[202:205], v122 offset:24576
	ds_read_b128 v[206:209], v123 offset:24576
	s_waitcnt lgkmcnt(13)
	v_mfma_f32_16x16x32_bf16 v[62:65], v[210:213], v[170:173], v[62:65]
	s_waitcnt lgkmcnt(12)
	v_mfma_f32_16x16x32_bf16 v[62:65], v[214:217], v[174:177], v[62:65]
	ds_read_b128 v[210:213], v122 offset:26624
	ds_read_b128 v[214:217], v123 offset:26624
	s_waitcnt lgkmcnt(13)
	v_mfma_f32_16x16x32_bf16 v[66:69], v[220:223], v[170:173], v[66:69]
	s_waitcnt lgkmcnt(12)
	v_mfma_f32_16x16x32_bf16 v[66:69], v[224:227], v[174:177], v[66:69]
	ds_read_b128 v[220:223], v122 offset:28672
	ds_read_b128 v[224:227], v123 offset:28672
	s_waitcnt lgkmcnt(13)
	v_mfma_f32_16x16x32_bf16 v[70:73], v[228:231], v[170:173], v[70:73]
	s_waitcnt lgkmcnt(12)
	v_mfma_f32_16x16x32_bf16 v[70:73], v[232:235], v[174:177], v[70:73]
	ds_read_b128 v[228:231], v122 offset:30720
	ds_read_b128 v[232:235], v123 offset:30720
	s_waitcnt lgkmcnt(13)
	v_mfma_f32_16x16x32_bf16 v[74:77], v[236:239], v[170:173], v[74:77]
	s_waitcnt lgkmcnt(12)
	v_mfma_f32_16x16x32_bf16 v[74:77], v[240:243], v[174:177], v[74:77]
	ds_read_b128 v[236:239], v122 offset:32768
	ds_read_b128 v[240:243], v123 offset:32768
	s_waitcnt lgkmcnt(13)
	v_mfma_f32_16x16x32_bf16 v[78:81], v[186:189], v[170:173], v[78:81]
	s_waitcnt lgkmcnt(12)
	v_mfma_f32_16x16x32_bf16 v[78:81], v[190:193], v[174:177], v[78:81]
	ds_read_b128 v[186:189], v122 offset:34816
	ds_read_b128 v[190:193], v123 offset:34816
	s_waitcnt lgkmcnt(13)
	v_mfma_f32_16x16x32_bf16 v[82:85], v[194:197], v[170:173], v[82:85]
	s_waitcnt lgkmcnt(12)
	v_mfma_f32_16x16x32_bf16 v[82:85], v[198:201], v[174:177], v[82:85]
	ds_read_b128 v[194:197], v122 offset:36864
	ds_read_b128 v[198:201], v123 offset:36864
	s_waitcnt lgkmcnt(13)
	v_mfma_f32_16x16x32_bf16 v[86:89], v[202:205], v[170:173], v[86:89]
	s_waitcnt lgkmcnt(12)
	v_mfma_f32_16x16x32_bf16 v[86:89], v[206:209], v[174:177], v[86:89]
	ds_read_b128 v[202:205], v122 offset:38912
	ds_read_b128 v[206:209], v123 offset:38912
	s_waitcnt lgkmcnt(13)
; #define LAS __attribute__((address_space(3)))
; #define MFMA16(a, b, c) __builtin_amdgcn_mfma_f32_16x16x32_bf16((a), (b), (c), 0, 0, 0)
; __device__ __forceinline__ void qk_at(const LAS unsigned char* kp0, const LAS unsigned char* kp1, int off, bf16x8 qf0, bf16x8 qf1, f32x4& S0, f32x4& S1) {
;     const bf16x8 k00 = *(const LAS bf16x8*)(kp0 + off), k01 = *(const LAS bf16x8*)(kp1 + off);
;     const bf16x8 k10 = *(const LAS bf16x8*)(kp0 + off + 2048), k11 = *(const LAS bf16x8*)(kp1 + off + 2048);
;     const f32x4 z = {0.f, 0.f, 0.f, 0.f};
;     S0 = MFMA16(k00, qf0, z); S0 = MFMA16(k01, qf1, S0);
;     S1 = MFMA16(k10, qf0, z); S1 = MFMA16(k11, qf1, S1);
; }
; __device__ __forceinline__ void softmax_step(f32x4& s0, f32x4& s1, float& m, float& l, f32x4 (&O)[4]) {
;     float t = fmaxf(fmaxf(fmaxf(s0[0], s0[1]), fmaxf(s0[2], s0[3])), fmaxf(fmaxf(s1[0], s1[1]), fmaxf(s1[2], s1[3])));
;     t = xrow16_max(t);
;     const float mn = fmaxf(m, t), alpha = __builtin_amdgcn_exp2f(m - mn);
;     m = mn;
	v_mfma_f32_16x16x32_bf16 v[90:93], v[210:213], v[170:173], v[90:93]
	s_waitcnt lgkmcnt(12)
	v_mfma_f32_16x16x32_bf16 v[90:93], v[214:217], v[174:177], v[90:93]
	s_waitcnt lgkmcnt(11)
	v_mfma_f32_16x16x32_bf16 v[94:97], v[220:223], v[170:173], v[94:97]
	s_waitcnt lgkmcnt(10)
	v_mfma_f32_16x16x32_bf16 v[94:97], v[224:227], v[174:177], v[94:97]
	s_waitcnt lgkmcnt(9)
	v_mfma_f32_16x16x32_bf16 v[98:101], v[228:231], v[170:173], v[98:101]
	s_waitcnt lgkmcnt(8)
	v_mfma_f32_16x16x32_bf16 v[98:101], v[232:235], v[174:177], v[98:101]
	s_waitcnt lgkmcnt(7)
	v_mfma_f32_16x16x32_bf16 v[102:105], v[236:239], v[170:173], v[102:105]
	s_waitcnt lgkmcnt(6)
	v_mfma_f32_16x16x32_bf16 v[102:105], v[240:243], v[174:177], v[102:105]
	s_waitcnt lgkmcnt(5)
	v_mfma_f32_16x16x32_bf16 v[106:109], v[186:189], v[170:173], v[106:109]
	s_waitcnt lgkmcnt(4)
	v_mfma_f32_16x16x32_bf16 v[106:109], v[190:193], v[174:177], v[106:109]
	s_waitcnt lgkmcnt(3)
	v_mfma_f32_16x16x32_bf16 v[110:113], v[194:197], v[170:173], v[110:113]
	s_waitcnt lgkmcnt(2)
	v_mfma_f32_16x16x32_bf16 v[110:113], v[198:201], v[174:177], v[110:113]
	s_waitcnt lgkmcnt(1)
	v_mfma_f32_16x16x32_bf16 v[114:117], v[202:205], v[170:173], v[114:117]
	s_waitcnt lgkmcnt(0)
	v_mfma_f32_16x16x32_bf16 v[114:117], v[206:209], v[174:177], v[114:117]
	v_max3_f32 v219, v50, v51, v52
	v_max3_f32 v244, v54, v55, v56
	v_max3_f32 v245, v58, v59, v60
	v_max3_f32 v120, v62, v63, v64
	v_max3_f32 v219, v219, v53, v66
	v_max3_f32 v244, v244, v57, v70
	v_max3_f32 v245, v245, v61, v74
	v_max3_f32 v120, v120, v65, v78
	v_max3_f32 v219, v219, v67, v68
	v_max3_f32 v244, v244, v71, v72
	v_max3_f32 v245, v245, v75, v76
	v_max3_f32 v120, v120, v79, v80
	ds_read_b64_tr_b16 v[186:187], v124 offset:6144
	ds_read_b64_tr_b16 v[188:189], v124 offset:8192
	ds_read_b64_tr_b16 v[190:191], v125 offset:6144
	ds_read_b64_tr_b16 v[192:193], v125 offset:8192
	ds_read_b64_tr_b16 v[194:195], v126 offset:6144
	ds_read_b64_tr_b16 v[196:197], v126 offset:8192
	ds_read_b64_tr_b16 v[198:199], v127 offset:6144
	ds_read_b64_tr_b16 v[200:201], v127 offset:8192
	v_max3_f32 v219, v219, v69, v82
	v_max3_f32 v244, v244, v73, v86
	v_max3_f32 v245, v245, v77, v90
	v_max3_f32 v120, v120, v81, v94
	v_max3_f32 v219, v219, v83, v84
	v_max3_f32 v244, v244, v87, v88
	v_max3_f32 v245, v245, v91, v92
	v_max3_f32 v120, v120, v95, v96
	v_max3_f32 v219, v219, v85, v98
	v_max3_f32 v244, v244, v89, v102
	v_max3_f32 v245, v245, v93, v106
	v_max3_f32 v120, v120, v97, v110
	v_max3_f32 v219, v219, v99, v100
	v_max3_f32 v244, v244, v103, v104
	v_max3_f32 v245, v245, v107, v108
	v_max3_f32 v120, v120, v111, v112
	v_max3_f32 v219, v219, v101, v114
	v_max3_f32 v219, v219, v115, v116
	v_max_f32_e32 v219, v219, v117
	v_max_f32_e32 v244, v244, v105
	v_max_f32_e32 v245, v245, v109
	v_max_f32_e32 v120, v120, v113
	v_max3_f32 v178, v219, v244, v245
	v_max_f32_e32 v178, v178, v120
	v_mov_b32_e32 v219, v178
	s_nop 1
	v_permlane16_swap_b32_e32 v178, v219
	v_max_f32_e32 v178, v178, v219
	v_mov_b32_e32 v219, v178
	s_nop 1
	v_permlane32_swap_b32_e32 v178, v219
	v_max3_f32 v178, v178, v219, v145
	s_waitcnt lgkmcnt(7)
	ds_read_b64_tr_b16 v[202:203], v124 offset:10240
	ds_read_b64_tr_b16 v[204:205], v124 offset:12288
	ds_read_b64_tr_b16 v[206:207], v125 offset:10240
	ds_read_b64_tr_b16 v[208:209], v125 offset:12288
	ds_read_b64_tr_b16 v[228:229], v126 offset:10240
	ds_read_b64_tr_b16 v[230:231], v126 offset:12288
	ds_read_b64_tr_b16 v[232:233], v127 offset:10240
	ds_read_b64_tr_b16 v[234:235], v127 offset:12288
	v_mov_b32_e32 v244, v178
	v_pk_add_f32 v[50:51], v[50:51], v[244:245] op_sel_hi:[1,0] neg_lo:[0,1] neg_hi:[0,1]
	v_pk_add_f32 v[52:53], v[52:53], v[244:245] op_sel_hi:[1,0] neg_lo:[0,1] neg_hi:[0,1]
	v_pk_add_f32 v[54:55], v[54:55], v[244:245] op_sel_hi:[1,0] neg_lo:[0,1] neg_hi:[0,1]
	v_pk_add_f32 v[56:57], v[56:57], v[244:245] op_sel_hi:[1,0] neg_lo:[0,1] neg_hi:[0,1]
	v_pk_add_f32 v[58:59], v[58:59], v[244:245] op_sel_hi:[1,0] neg_lo:[0,1] neg_hi:[0,1]
	v_pk_add_f32 v[60:61], v[60:61], v[244:245] op_sel_hi:[1,0] neg_lo:[0,1] neg_hi:[0,1]
	v_pk_add_f32 v[62:63], v[62:63], v[244:245] op_sel_hi:[1,0] neg_lo:[0,1] neg_hi:[0,1]
	v_pk_add_f32 v[64:65], v[64:65], v[244:245] op_sel_hi:[1,0] neg_lo:[0,1] neg_hi:[0,1]
	v_pk_add_f32 v[66:67], v[66:67], v[244:245] op_sel_hi:[1,0] neg_lo:[0,1] neg_hi:[0,1]
	v_pk_add_f32 v[68:69], v[68:69], v[244:245] op_sel_hi:[1,0] neg_lo:[0,1] neg_hi:[0,1]
	v_pk_add_f32 v[70:71], v[70:71], v[244:245] op_sel_hi:[1,0] neg_lo:[0,1] neg_hi:[0,1]
	v_pk_add_f32 v[72:73], v[72:73], v[244:245] op_sel_hi:[1,0] neg_lo:[0,1] neg_hi:[0,1]
	v_pk_add_f32 v[74:75], v[74:75], v[244:245] op_sel_hi:[1,0] neg_lo:[0,1] neg_hi:[0,1]
	v_pk_add_f32 v[76:77], v[76:77], v[244:245] op_sel_hi:[1,0] neg_lo:[0,1] neg_hi:[0,1]
	v_pk_add_f32 v[78:79], v[78:79], v[244:245] op_sel_hi:[1,0] neg_lo:[0,1] neg_hi:[0,1]
	v_pk_add_f32 v[80:81], v[80:81], v[244:245] op_sel_hi:[1,0] neg_lo:[0,1] neg_hi:[0,1]
	v_pk_add_f32 v[82:83], v[82:83], v[244:245] op_sel_hi:[1,0] neg_lo:[0,1] neg_hi:[0,1]
	v_pk_add_f32 v[84:85], v[84:85], v[244:245] op_sel_hi:[1,0] neg_lo:[0,1] neg_hi:[0,1]
	v_pk_add_f32 v[86:87], v[86:87], v[244:245] op_sel_hi:[1,0] neg_lo:[0,1] neg_hi:[0,1]
	v_pk_add_f32 v[88:89], v[88:89], v[244:245] op_sel_hi:[1,0] neg_lo:[0,1] neg_hi:[0,1]
	v_pk_add_f32 v[90:91], v[90:91], v[244:245] op_sel_hi:[1,0] neg_lo:[0,1] neg_hi:[0,1]
	v_pk_add_f32 v[92:93], v[92:93], v[244:245] op_sel_hi:[1,0] neg_lo:[0,1] neg_hi:[0,1]
	v_pk_add_f32 v[94:95], v[94:95], v[244:245] op_sel_hi:[1,0] neg_lo:[0,1] neg_hi:[0,1]
	v_pk_add_f32 v[96:97], v[96:97], v[244:245] op_sel_hi:[1,0] neg_lo:[0,1] neg_hi:[0,1]
; #define LAS __attribute__((address_space(3)))
; __device__ __forceinline__ unsigned pk2(float lo, float hi) { return pg8::cvt_pk_bf16(lo, hi); }
; __device__ __forceinline__ s16x4 vtr(const LAS unsigned char* p) { return __builtin_bit_cast(s16x4, __builtin_amdgcn_ds_read_tr16_b64_v4i16((LAS s16x4*)p)); }
; #define MFMA16(a, b, c) __builtin_amdgcn_mfma_f32_16x16x32_bf16((a), (b), (c), 0, 0, 0)
; __device__ __forceinline__ void pv_at(const LAS unsigned char* const (&vp)[4], int off, const f32x4& P0, const f32x4& P1, f32x4 (&O)[4]) {
;     v4u pw; pw.x = pk2(P0[0], P0[1]); pw.y = pk2(P0[2], P0[3]); pw.z = pk2(P1[0], P1[1]); pw.w = pk2(P1[2], P1[3]);
;     const bf16x8 pb = __builtin_bit_cast(bf16x8, pw);
; #pragma unroll
;     for (int db = 0; db < 4; ++db) {
;         const s16x4 lo = vtr(vp[db] + off), hi = vtr(vp[db] + off + 2048);
;         const bf16x8 vt = (bf16x8){lo[0], lo[1], lo[2], lo[3], hi[0], hi[1], hi[2], hi[3]};
;         O[db] = MFMA16(vt, pb, O[db]);
;     }
; }
; __device__ __forceinline__ void softmax_step(f32x4& s0, f32x4& s1, float& m, float& l, f32x4 (&O)[4]) {
;     float t = fmaxf(fmaxf(fmaxf(s0[0], s0[1]), fmaxf(s0[2], s0[3])), fmaxf(fmaxf(s1[0], s1[1]), fmaxf(s1[2], s1[3])));
;     t = xrow16_max(t);
;     const float mn = fmaxf(m, t), alpha = __builtin_amdgcn_exp2f(m - mn);
;     m = mn;
; #pragma unroll
;     for (int k = 0; k < 4; ++k) { s0[k] = __builtin_amdgcn_exp2f(s0[k] - mn); s1[k] = __builtin_amdgcn_exp2f(s1[k] - mn); }
;     l = l * alpha + ((s0[0] + s0[1]) + (s0[2] + s0[3])) + ((s1[0] + s1[1]) + (s1[2] + s1[3]));
; #pragma unroll
;     for (int db = 0; db < 4; ++db) O[db] *= alpha;
; }
	v_pk_add_f32 v[98:99], v[98:99], v[244:245] op_sel_hi:[1,0] neg_lo:[0,1] neg_hi:[0,1]
	v_pk_add_f32 v[100:101], v[100:101], v[244:245] op_sel_hi:[1,0] neg_lo:[0,1] neg_hi:[0,1]
	v_pk_add_f32 v[102:103], v[102:103], v[244:245] op_sel_hi:[1,0] neg_lo:[0,1] neg_hi:[0,1]
	v_pk_add_f32 v[104:105], v[104:105], v[244:245] op_sel_hi:[1,0] neg_lo:[0,1] neg_hi:[0,1]
	v_pk_add_f32 v[106:107], v[106:107], v[244:245] op_sel_hi:[1,0] neg_lo:[0,1] neg_hi:[0,1]
	v_pk_add_f32 v[108:109], v[108:109], v[244:245] op_sel_hi:[1,0] neg_lo:[0,1] neg_hi:[0,1]
	v_pk_add_f32 v[110:111], v[110:111], v[244:245] op_sel_hi:[1,0] neg_lo:[0,1] neg_hi:[0,1]
	v_pk_add_f32 v[112:113], v[112:113], v[244:245] op_sel_hi:[1,0] neg_lo:[0,1] neg_hi:[0,1]
	v_pk_add_f32 v[114:115], v[114:115], v[244:245] op_sel_hi:[1,0] neg_lo:[0,1] neg_hi:[0,1]
	v_pk_add_f32 v[116:117], v[116:117], v[244:245] op_sel_hi:[1,0] neg_lo:[0,1] neg_hi:[0,1]
	v_sub_f32_e32 v219, v145, v178
	v_exp_f32_e32 v50, v50
	v_exp_f32_e32 v51, v51
	v_exp_f32_e32 v52, v52
	v_exp_f32_e32 v53, v53
	v_exp_f32_e32 v54, v54
	v_exp_f32_e32 v55, v55
	v_exp_f32_e32 v56, v56
	v_exp_f32_e32 v57, v57
	v_exp_f32_e32 v58, v58
	v_exp_f32_e32 v59, v59
	v_exp_f32_e32 v60, v60
	v_exp_f32_e32 v61, v61
	v_exp_f32_e32 v62, v62
	v_exp_f32_e32 v63, v63
	v_exp_f32_e32 v64, v64
	v_exp_f32_e32 v65, v65
	v_exp_f32_e32 v66, v66
	v_exp_f32_e32 v67, v67
	v_exp_f32_e32 v68, v68
	v_exp_f32_e32 v69, v69
	v_exp_f32_e32 v70, v70
	v_exp_f32_e32 v71, v71
	v_exp_f32_e32 v72, v72
	v_exp_f32_e32 v73, v73
	v_exp_f32_e32 v74, v74
	v_exp_f32_e32 v75, v75
	v_exp_f32_e32 v76, v76
	v_exp_f32_e32 v77, v77
	v_exp_f32_e32 v78, v78
	v_exp_f32_e32 v79, v79
	v_exp_f32_e32 v80, v80
	v_exp_f32_e32 v81, v81
	v_exp_f32_e32 v82, v82
	v_exp_f32_e32 v83, v83
	v_exp_f32_e32 v84, v84
	v_exp_f32_e32 v85, v85
	v_exp_f32_e32 v86, v86
	v_exp_f32_e32 v87, v87
	v_exp_f32_e32 v88, v88
	v_exp_f32_e32 v89, v89
	v_exp_f32_e32 v90, v90
	v_exp_f32_e32 v91, v91
	v_exp_f32_e32 v92, v92
	v_exp_f32_e32 v93, v93
	v_exp_f32_e32 v94, v94
	v_exp_f32_e32 v95, v95
	v_exp_f32_e32 v96, v96
	v_exp_f32_e32 v97, v97
	v_exp_f32_e32 v98, v98
	v_exp_f32_e32 v99, v99
	v_exp_f32_e32 v100, v100
	v_exp_f32_e32 v101, v101
	v_exp_f32_e32 v102, v102
	v_exp_f32_e32 v103, v103
	v_exp_f32_e32 v104, v104
	v_exp_f32_e32 v105, v105
	v_exp_f32_e32 v106, v106
	v_exp_f32_e32 v107, v107
	v_exp_f32_e32 v108, v108
	v_exp_f32_e32 v109, v109
	v_exp_f32_e32 v110, v110
	v_exp_f32_e32 v111, v111
	v_exp_f32_e32 v112, v112
	v_exp_f32_e32 v113, v113
	v_exp_f32_e32 v114, v114
	v_exp_f32_e32 v115, v115
	v_exp_f32_e32 v116, v116
	v_exp_f32_e32 v117, v117
	v_exp_f32_e32 v219, v219
	v_pk_add_f32 v[236:237], v[50:51], v[52:53]
	v_pk_add_f32 v[238:239], v[54:55], v[56:57]
	v_pk_add_f32 v[240:241], v[58:59], v[60:61]
	v_pk_add_f32 v[242:243], v[62:63], v[64:65]
	v_pk_add_f32 v[236:237], v[236:237], v[66:67]
	v_pk_add_f32 v[238:239], v[238:239], v[70:71]
	v_pk_add_f32 v[240:241], v[240:241], v[74:75]
	v_pk_add_f32 v[242:243], v[242:243], v[78:79]
	v_pk_add_f32 v[236:237], v[236:237], v[68:69]
	v_pk_add_f32 v[238:239], v[238:239], v[72:73]
	v_pk_add_f32 v[240:241], v[240:241], v[76:77]
	v_pk_add_f32 v[242:243], v[242:243], v[80:81]
	v_pk_add_f32 v[236:237], v[236:237], v[82:83]
	v_pk_add_f32 v[238:239], v[238:239], v[86:87]
	v_pk_add_f32 v[240:241], v[240:241], v[90:91]
	v_pk_add_f32 v[242:243], v[242:243], v[94:95]
	v_pk_add_f32 v[236:237], v[236:237], v[84:85]
	v_pk_add_f32 v[238:239], v[238:239], v[88:89]
	v_pk_add_f32 v[240:241], v[240:241], v[92:93]
	v_pk_add_f32 v[242:243], v[242:243], v[96:97]
	v_pk_add_f32 v[236:237], v[236:237], v[98:99]
	v_pk_add_f32 v[238:239], v[238:239], v[102:103]
	v_pk_add_f32 v[240:241], v[240:241], v[106:107]
	v_pk_add_f32 v[242:243], v[242:243], v[110:111]
	v_pk_add_f32 v[236:237], v[236:237], v[100:101]
	v_pk_add_f32 v[238:239], v[238:239], v[104:105]
	v_pk_add_f32 v[240:241], v[240:241], v[108:109]
	v_pk_add_f32 v[242:243], v[242:243], v[112:113]
	v_pk_add_f32 v[236:237], v[236:237], v[114:115]
	v_pk_add_f32 v[236:237], v[236:237], v[116:117]
	v_pk_add_f32 v[236:237], v[236:237], v[238:239]
	v_pk_add_f32 v[240:241], v[240:241], v[242:243]
	v_cndmask_b32_e64 v219, 0, v219, s[74:75]
	v_pk_add_f32 v[236:237], v[236:237], v[240:241]
	v_add_f32_e32 v185, v236, v237
	v_add_f32_e32 v185, v185, v219
	v_cvt_pk_bf16_f32 v236, v50, v51
	v_cvt_pk_bf16_f32 v237, v52, v53
	v_cvt_pk_bf16_f32 v238, v54, v55
	v_cvt_pk_bf16_f32 v239, v56, v57
	s_nop 1
	s_waitcnt lgkmcnt(14)
	v_mfma_f32_16x16x32_bf16 v[210:213], v[186:189], v[236:239], 0
	s_waitcnt lgkmcnt(12)
	v_mfma_f32_16x16x32_bf16 v[214:217], v[190:193], v[236:239], 0
	s_waitcnt lgkmcnt(10)
	v_mfma_f32_16x16x32_bf16 v[220:223], v[194:197], v[236:239], 0
	s_waitcnt lgkmcnt(8)
	v_mfma_f32_16x16x32_bf16 v[224:227], v[198:201], v[236:239], 0
	v_cvt_pk_bf16_f32 v240, v58, v59
	v_cvt_pk_bf16_f32 v241, v60, v61
	v_cvt_pk_bf16_f32 v242, v62, v63
	v_cvt_pk_bf16_f32 v243, v64, v65
	s_waitcnt lgkmcnt(7)
	ds_read_b64_tr_b16 v[186:187], v124 offset:14336
	ds_read_b64_tr_b16 v[188:189], v124 offset:16384
	ds_read_b64_tr_b16 v[190:191], v125 offset:14336
	ds_read_b64_tr_b16 v[192:193], v125 offset:16384
	ds_read_b64_tr_b16 v[194:195], v126 offset:14336
	ds_read_b64_tr_b16 v[196:197], v126 offset:16384
	ds_read_b64_tr_b16 v[198:199], v127 offset:14336
	ds_read_b64_tr_b16 v[200:201], v127 offset:16384
	s_waitcnt lgkmcnt(14)
	v_mfma_f32_16x16x32_bf16 v[210:213], v[202:205], v[240:243], v[210:213]
	s_waitcnt lgkmcnt(12)
	v_mfma_f32_16x16x32_bf16 v[214:217], v[206:209], v[240:243], v[214:217]
	s_waitcnt lgkmcnt(10)
	v_mfma_f32_16x16x32_bf16 v[220:223], v[228:231], v[240:243], v[220:223]
	s_waitcnt lgkmcnt(8)
; #define LAS __attribute__((address_space(3)))
; __device__ __forceinline__ unsigned pk2(float lo, float hi) { return pg8::cvt_pk_bf16(lo, hi); }
; __device__ __forceinline__ s16x4 vtr(const LAS unsigned char* p) { return __builtin_bit_cast(s16x4, __builtin_amdgcn_ds_read_tr16_b64_v4i16((LAS s16x4*)p)); }
; #define MFMA16(a, b, c) __builtin_amdgcn_mfma_f32_16x16x32_bf16((a), (b), (c), 0, 0, 0)
; __device__ __forceinline__ void pv_at(const LAS unsigned char* const (&vp)[4], int off, const f32x4& P0, const f32x4& P1, f32x4 (&O)[4]) {
;     v4u pw; pw.x = pk2(P0[0], P0[1]); pw.y = pk2(P0[2], P0[3]); pw.z = pk2(P1[0], P1[1]); pw.w = pk2(P1[2], P1[3]);
;     const bf16x8 pb = __builtin_bit_cast(bf16x8, pw);
; #pragma unroll
;     for (int db = 0; db < 4; ++db) {
;         const s16x4 lo = vtr(vp[db] + off), hi = vtr(vp[db] + off + 2048);
;         const bf16x8 vt = (bf16x8){lo[0], lo[1], lo[2], lo[3], hi[0], hi[1], hi[2], hi[3]};
;         O[db] = MFMA16(vt, pb, O[db]);
;     }
; }
	v_mfma_f32_16x16x32_bf16 v[224:227], v[232:235], v[240:243], v[224:227]
	v_cvt_pk_bf16_f32 v236, v66, v67
	v_cvt_pk_bf16_f32 v237, v68, v69
	v_cvt_pk_bf16_f32 v238, v70, v71
	v_cvt_pk_bf16_f32 v239, v72, v73
	s_waitcnt lgkmcnt(7)
	ds_read_b64_tr_b16 v[202:203], v124 offset:18432
	ds_read_b64_tr_b16 v[204:205], v124 offset:20480
	ds_read_b64_tr_b16 v[206:207], v125 offset:18432
	ds_read_b64_tr_b16 v[208:209], v125 offset:20480
	ds_read_b64_tr_b16 v[228:229], v126 offset:18432
	ds_read_b64_tr_b16 v[230:231], v126 offset:20480
	ds_read_b64_tr_b16 v[232:233], v127 offset:18432
	ds_read_b64_tr_b16 v[234:235], v127 offset:20480
	s_waitcnt lgkmcnt(14)
	v_mfma_f32_16x16x32_bf16 v[210:213], v[186:189], v[236:239], v[210:213]
	s_waitcnt lgkmcnt(12)
	v_mfma_f32_16x16x32_bf16 v[214:217], v[190:193], v[236:239], v[214:217]
	s_waitcnt lgkmcnt(10)
	v_mfma_f32_16x16x32_bf16 v[220:223], v[194:197], v[236:239], v[220:223]
	s_waitcnt lgkmcnt(8)
	v_mfma_f32_16x16x32_bf16 v[224:227], v[198:201], v[236:239], v[224:227]
	v_cvt_pk_bf16_f32 v240, v74, v75
	v_cvt_pk_bf16_f32 v241, v76, v77
	v_cvt_pk_bf16_f32 v242, v78, v79
	v_cvt_pk_bf16_f32 v243, v80, v81
	s_waitcnt lgkmcnt(7)
	ds_read_b64_tr_b16 v[186:187], v124 offset:22528
	ds_read_b64_tr_b16 v[188:189], v124 offset:24576
	ds_read_b64_tr_b16 v[190:191], v125 offset:22528
	ds_read_b64_tr_b16 v[192:193], v125 offset:24576
	ds_read_b64_tr_b16 v[194:195], v126 offset:22528
	ds_read_b64_tr_b16 v[196:197], v126 offset:24576
	ds_read_b64_tr_b16 v[198:199], v127 offset:22528
	ds_read_b64_tr_b16 v[200:201], v127 offset:24576
	s_waitcnt lgkmcnt(14)
	v_mfma_f32_16x16x32_bf16 v[210:213], v[202:205], v[240:243], v[210:213]
	s_waitcnt lgkmcnt(12)
	v_mfma_f32_16x16x32_bf16 v[214:217], v[206:209], v[240:243], v[214:217]
	s_waitcnt lgkmcnt(10)
	v_mfma_f32_16x16x32_bf16 v[220:223], v[228:231], v[240:243], v[220:223]
	s_waitcnt lgkmcnt(8)
	v_mfma_f32_16x16x32_bf16 v[224:227], v[232:235], v[240:243], v[224:227]
	v_cvt_pk_bf16_f32 v236, v82, v83
	v_cvt_pk_bf16_f32 v237, v84, v85
	v_cvt_pk_bf16_f32 v238, v86, v87
	v_cvt_pk_bf16_f32 v239, v88, v89
	s_waitcnt lgkmcnt(7)
	ds_read_b64_tr_b16 v[202:203], v124 offset:26624
	ds_read_b64_tr_b16 v[204:205], v124 offset:28672
	ds_read_b64_tr_b16 v[206:207], v125 offset:26624
	ds_read_b64_tr_b16 v[208:209], v125 offset:28672
	ds_read_b64_tr_b16 v[228:229], v126 offset:26624
	ds_read_b64_tr_b16 v[230:231], v126 offset:28672
	ds_read_b64_tr_b16 v[232:233], v127 offset:26624
	ds_read_b64_tr_b16 v[234:235], v127 offset:28672
	s_waitcnt lgkmcnt(14)
	v_mfma_f32_16x16x32_bf16 v[210:213], v[186:189], v[236:239], v[210:213]
	s_waitcnt lgkmcnt(12)
	v_mfma_f32_16x16x32_bf16 v[214:217], v[190:193], v[236:239], v[214:217]
	s_waitcnt lgkmcnt(10)
	v_mfma_f32_16x16x32_bf16 v[220:223], v[194:197], v[236:239], v[220:223]
	s_waitcnt lgkmcnt(8)
	v_mfma_f32_16x16x32_bf16 v[224:227], v[198:201], v[236:239], v[224:227]
	v_cvt_pk_bf16_f32 v240, v90, v91
	v_cvt_pk_bf16_f32 v241, v92, v93
	v_cvt_pk_bf16_f32 v242, v94, v95
	v_cvt_pk_bf16_f32 v243, v96, v97
	s_waitcnt lgkmcnt(7)
	ds_read_b64_tr_b16 v[186:187], v124 offset:30720
	ds_read_b64_tr_b16 v[188:189], v124 offset:32768
	ds_read_b64_tr_b16 v[190:191], v125 offset:30720
	ds_read_b64_tr_b16 v[192:193], v125 offset:32768
	ds_read_b64_tr_b16 v[194:195], v126 offset:30720
	ds_read_b64_tr_b16 v[196:197], v126 offset:32768
	ds_read_b64_tr_b16 v[198:199], v127 offset:30720
	ds_read_b64_tr_b16 v[200:201], v127 offset:32768
	s_waitcnt lgkmcnt(14)
	v_mfma_f32_16x16x32_bf16 v[210:213], v[202:205], v[240:243], v[210:213]
	s_waitcnt lgkmcnt(12)
	v_mfma_f32_16x16x32_bf16 v[214:217], v[206:209], v[240:243], v[214:217]
	s_waitcnt lgkmcnt(10)
	v_mfma_f32_16x16x32_bf16 v[220:223], v[228:231], v[240:243], v[220:223]
	s_waitcnt lgkmcnt(8)
	v_mfma_f32_16x16x32_bf16 v[224:227], v[232:235], v[240:243], v[224:227]
	v_cvt_pk_bf16_f32 v236, v98, v99
	v_cvt_pk_bf16_f32 v237, v100, v101
	v_cvt_pk_bf16_f32 v238, v102, v103
	v_cvt_pk_bf16_f32 v239, v104, v105
	s_waitcnt lgkmcnt(7)
; #define LAS __attribute__((address_space(3)))
; __device__ __forceinline__ unsigned pk2(float lo, float hi) { return pg8::cvt_pk_bf16(lo, hi); }
; __device__ __forceinline__ s16x4 vtr(const LAS unsigned char* p) { return __builtin_bit_cast(s16x4, __builtin_amdgcn_ds_read_tr16_b64_v4i16((LAS s16x4*)p)); }
; #define MFMA16(a, b, c) __builtin_amdgcn_mfma_f32_16x16x32_bf16((a), (b), (c), 0, 0, 0)
; __device__ __forceinline__ void pv_at(const LAS unsigned char* const (&vp)[4], int off, const f32x4& P0, const f32x4& P1, f32x4 (&O)[4]) {
;     v4u pw; pw.x = pk2(P0[0], P0[1]); pw.y = pk2(P0[2], P0[3]); pw.z = pk2(P1[0], P1[1]); pw.w = pk2(P1[2], P1[3]);
;     const bf16x8 pb = __builtin_bit_cast(bf16x8, pw);
; #pragma unroll
;     for (int db = 0; db < 4; ++db) {
;         const s16x4 lo = vtr(vp[db] + off), hi = vtr(vp[db] + off + 2048);
;         const bf16x8 vt = (bf16x8){lo[0], lo[1], lo[2], lo[3], hi[0], hi[1], hi[2], hi[3]};
;         O[db] = MFMA16(vt, pb, O[db]);
;     }
; }
; __device__ __forceinline__ void store_o(bf16* yrow, int g, float l, const f32x4 (&O)[4]) {
;     const float inv = 1.0f / xrow16_sum(l);
;     unsigned wx[4], wy[4];
; #pragma unroll
;     for (int db = 0; db < 4; ++db) { wx[db] = pk2(O[db][0] * inv, O[db][1] * inv); wy[db] = pk2(O[db][2] * inv, O[db][3] * inv); }
; #pragma unroll
;     for (int p = 0; p < 2; ++p) {
;         auto rx = __builtin_amdgcn_permlane16_swap(wx[2 * p], wx[2 * p + 1], false, false); wx[2 * p] = rx[0]; wx[2 * p + 1] = rx[1];
;         auto ry = __builtin_amdgcn_permlane16_swap(wy[2 * p], wy[2 * p + 1], false, false); wy[2 * p] = ry[0]; wy[2 * p + 1] = ry[1]; }
; #pragma unroll
;     for (int p = 0; p < 2; ++p) {
;         auto rx = __builtin_amdgcn_permlane32_swap(wx[p], wx[p + 2], false, false); wx[p] = rx[0]; wx[p + 2] = rx[1];
;         auto ry = __builtin_amdgcn_permlane32_swap(wy[p], wy[p + 2], false, false); wy[p] = ry[0]; wy[p + 2] = ry[1]; }
;     v4u lo = {wx[0], wy[0], wx[1], wy[1]}, hi = {wx[2], wy[2], wx[3], wy[3]};
;     *(v4u*)(yrow + 16 * g) = lo; *(v4u*)(yrow + 16 * g + 8) = hi;
; }
	ds_read_b64_tr_b16 v[202:203], v124 offset:34816
	ds_read_b64_tr_b16 v[204:205], v124 offset:36864
	ds_read_b64_tr_b16 v[206:207], v125 offset:34816
	ds_read_b64_tr_b16 v[208:209], v125 offset:36864
	ds_read_b64_tr_b16 v[228:229], v126 offset:34816
	ds_read_b64_tr_b16 v[230:231], v126 offset:36864
	ds_read_b64_tr_b16 v[232:233], v127 offset:34816
	ds_read_b64_tr_b16 v[234:235], v127 offset:36864
	s_waitcnt lgkmcnt(14)
	v_mfma_f32_16x16x32_bf16 v[210:213], v[186:189], v[236:239], v[210:213]
	s_waitcnt lgkmcnt(12)
	v_mfma_f32_16x16x32_bf16 v[214:217], v[190:193], v[236:239], v[214:217]
	s_waitcnt lgkmcnt(10)
	v_mfma_f32_16x16x32_bf16 v[220:223], v[194:197], v[236:239], v[220:223]
	s_waitcnt lgkmcnt(8)
	v_mfma_f32_16x16x32_bf16 v[224:227], v[198:201], v[236:239], v[224:227]
	v_cvt_pk_bf16_f32 v240, v106, v107
	v_cvt_pk_bf16_f32 v241, v108, v109
	v_cvt_pk_bf16_f32 v242, v110, v111
	v_cvt_pk_bf16_f32 v243, v112, v113
	s_waitcnt lgkmcnt(7)
	ds_read_b64_tr_b16 v[186:187], v124 offset:38912
	ds_read_b64_tr_b16 v[188:189], v124 offset:40960
	ds_read_b64_tr_b16 v[190:191], v125 offset:38912
	ds_read_b64_tr_b16 v[192:193], v125 offset:40960
	ds_read_b64_tr_b16 v[194:195], v126 offset:38912
	ds_read_b64_tr_b16 v[196:197], v126 offset:40960
	ds_read_b64_tr_b16 v[198:199], v127 offset:38912
	ds_read_b64_tr_b16 v[200:201], v127 offset:40960
	s_waitcnt lgkmcnt(14)
	v_mfma_f32_16x16x32_bf16 v[210:213], v[202:205], v[240:243], v[210:213]
	s_waitcnt lgkmcnt(12)
	v_mfma_f32_16x16x32_bf16 v[214:217], v[206:209], v[240:243], v[214:217]
	s_waitcnt lgkmcnt(10)
	v_mfma_f32_16x16x32_bf16 v[220:223], v[228:231], v[240:243], v[220:223]
	s_waitcnt lgkmcnt(8)
	v_mfma_f32_16x16x32_bf16 v[224:227], v[232:235], v[240:243], v[224:227]
	v_cvt_pk_bf16_f32 v236, v114, v115
	v_cvt_pk_bf16_f32 v237, v116, v117
	v_mov_b32_e32 v238, 0
	v_mov_b32_e32 v239, 0
	s_nop 1
	s_waitcnt lgkmcnt(6)
	v_mfma_f32_16x16x32_bf16 v[210:213], v[186:189], v[236:239], v[210:213]
	s_waitcnt lgkmcnt(4)
	v_mfma_f32_16x16x32_bf16 v[214:217], v[190:193], v[236:239], v[214:217]
	s_waitcnt lgkmcnt(2)
	v_mfma_f32_16x16x32_bf16 v[220:223], v[194:197], v[236:239], v[220:223]
	s_waitcnt lgkmcnt(0)
	v_mfma_f32_16x16x32_bf16 v[224:227], v[198:201], v[236:239], v[224:227]
	v_mov_b32_e32 v219, v185
	s_nop 1
	v_permlane16_swap_b32_e32 v185, v219
	v_add_f32_e32 v185, v185, v219
	v_mov_b32_e32 v219, v185
	s_nop 1
	v_permlane32_swap_b32_e32 v185, v219
	v_add_f32_e32 v185, v185, v219
	v_div_scale_f32 v236, s[78:79], v185, v185, 1.0
	v_div_scale_f32 v237, vcc, 1.0, v185, 1.0
	v_rcp_f32_e32 v238, v236
	s_nop 0
	v_fma_f32 v239, -v236, v238, 1.0
	v_fmac_f32_e32 v238, v239, v238
	v_mul_f32_e32 v240, v237, v238
	v_fma_f32 v241, -v236, v240, v237
	v_fmac_f32_e32 v240, v241, v238
	v_fma_f32 v237, -v236, v240, v237
	v_div_fmas_f32 v237, v237, v238, v240
	v_div_fixup_f32 v244, v237, v185, 1.0
	v_mul_f32_e32 v240, v210, v244
	v_mul_f32_e32 v241, v211, v244
	v_mul_f32_e32 v242, v212, v244
	v_mul_f32_e32 v243, v213, v244
	v_cvt_pk_bf16_f32 v186, v240, v241
	v_cvt_pk_bf16_f32 v187, v242, v243
	v_mul_f32_e32 v240, v214, v244
	v_mul_f32_e32 v241, v215, v244
	v_mul_f32_e32 v242, v216, v244
	v_mul_f32_e32 v243, v217, v244
	v_cvt_pk_bf16_f32 v188, v240, v241
	v_cvt_pk_bf16_f32 v189, v242, v243
	v_mul_f32_e32 v240, v220, v244
	v_mul_f32_e32 v241, v221, v244
	v_mul_f32_e32 v242, v222, v244
	v_mul_f32_e32 v243, v223, v244
	v_cvt_pk_bf16_f32 v190, v240, v241
	v_cvt_pk_bf16_f32 v191, v242, v243
	v_mul_f32_e32 v240, v224, v244
	v_mul_f32_e32 v241, v225, v244
	v_mul_f32_e32 v242, v226, v244
	v_mul_f32_e32 v243, v227, v244
	v_cvt_pk_bf16_f32 v192, v240, v241
	v_cvt_pk_bf16_f32 v193, v242, v243
	s_nop 1
	v_permlane16_swap_b32_e32 v186, v188
	v_permlane16_swap_b32_e32 v187, v189
	v_permlane16_swap_b32_e32 v190, v192
	v_permlane16_swap_b32_e32 v191, v193
	s_nop 0
	v_permlane32_swap_b32_e32 v186, v190
	v_permlane32_swap_b32_e32 v187, v191
	v_permlane32_swap_b32_e32 v188, v192
	v_permlane32_swap_b32_e32 v189, v193
	v_add_u32_e32 v219, 0x1000, v128
	global_store_dwordx4 v219, v[186:189], s[82:83] offset:2048
	global_store_dwordx4 v219, v[190:193], s[82:83] offset:2064
	s_nop 1
	s_branch .LBB0_240
